# epilogue stores in SwiGLU/EpiWin/EpiResid: flat_store -> global_store (132 sites; no lgkmcnt coupling)
# speedup vs baseline: 1.0036x; 1.0036x over previous
; __device__ __forceinline__ u32x4 pack8(f32x4 a, f32x4 b) { u32x4 w; w.x = pk2(a[0], a[1]); w.y = pk2(a[2], a[3]); w.z = pk2(b[0], b[1]); w.w = pk2(b[2], b[3]); return w; }
; __device__ __forceinline__ float fast_sigmoid(float x) { return __builtin_amdgcn_rcpf(1.0f + __builtin_amdgcn_exp2f(-x * LOG2E)); }
; __device__ __forceinline__ float row_rs16(const float* ssq_x, int row) {
;     const f32x4* p = (const f32x4*)(ssq_x + (size_t)row * 16); const f32x4 a = p[0], b = p[1], c = p[2], d = p[3];
;     return rsqrtf((((a[0] + a[1]) + (a[2] + a[3])) + ((b[0] + b[1]) + (b[2] + b[3])) + ((c[0] + c[1]) + (c[2] + c[3])) + ((d[0] + d[1]) + (d[2] + d[3]))) * (1.0f / DM) + EPS);
; }
;     __device__ __forceinline__ void operator()(const Acc& acc, const Unit& u, int wr, int wc, int fr, int fq, const RsCtx& rc) const {
;     ...
;             for (int m = 0; m < 4; ++m) { const int row = EPI_ROW(u, ai, wr, m, fr); const float rs = rc.get(u.pm, ai * 128 + wr * 64 + m * 16 + fr, row);
;                 f32x4 a0 = acc[ai][0][m][0] * rs, a1 = acc[ai][0][m][1] * rs; const f32x4 b0 = acc[ai][1][m][0] * rs, b1 = acc[ai][1][m][1] * rs;
; #pragma unroll
;                 for (int e = 0; e < 4; ++e) { a0[e] = a0[e] * fast_sigmoid(a0[e]) * b0[e]; a1[e] = a1[e] * fast_sigmoid(a1[e]) * b1[e]; }
;                 *(u32x4*)(O + (size_t)row * FF + col) = pack8(a0, a1);
.LBB0_155:
	s_waitcnt lgkmcnt(0)
	v_lshl_or_b32 v140, s36, 7, v148
	v_readlane_b32 s6, v255, 0
	v_ashrrev_i32_e32 v141, 31, v140
	v_readlane_b32 s7, v255, 1
	v_lshl_add_u64 v[140:141], v[140:141], 1, s[6:7]
	s_mov_b64 s[28:29], -1
	s_andn2_b64 vcc, exec, s[24:25]
	s_mov_b32 s100, 0xbfb8aa3b
	v_pk_mul_f32 v[126:127], v[126:127], v[144:145] op_sel_hi:[1,0]
	v_pk_mul_f32 v[128:129], v[128:129], v[144:145] op_sel_hi:[1,0]
	v_pk_mul_f32 v[122:123], v[122:123], v[144:145] op_sel_hi:[1,0]
	v_pk_mul_f32 v[124:125], v[124:125], v[144:145] op_sel_hi:[1,0]
	v_pk_mul_f32 v[150:151], v[126:127], s[100:101] op_sel_hi:[1,0]
	v_pk_mul_f32 v[152:153], v[128:129], s[100:101] op_sel_hi:[1,0]
	v_pk_mul_f32 v[154:155], v[122:123], s[100:101] op_sel_hi:[1,0]
	v_pk_mul_f32 v[156:157], v[124:125], s[100:101] op_sel_hi:[1,0]
	s_mov_b32 s100, 1.0
	v_exp_f32_e32 v150, v150
	v_exp_f32_e32 v151, v151
	v_exp_f32_e32 v152, v152
	v_exp_f32_e32 v153, v153
	v_exp_f32_e32 v154, v154
	v_exp_f32_e32 v155, v155
	v_exp_f32_e32 v156, v156
	v_exp_f32_e32 v157, v157
	v_pk_mul_f32 v[118:119], v[118:119], v[144:145] op_sel_hi:[1,0]
	v_pk_mul_f32 v[120:121], v[120:121], v[144:145] op_sel_hi:[1,0]
	v_pk_mul_f32 v[114:115], v[114:115], v[144:145] op_sel_hi:[1,0]
	v_pk_mul_f32 v[116:117], v[116:117], v[144:145] op_sel_hi:[1,0]
	v_pk_add_f32 v[150:151], v[150:151], s[100:101] op_sel_hi:[1,0]
	v_pk_add_f32 v[152:153], v[152:153], s[100:101] op_sel_hi:[1,0]
	v_pk_add_f32 v[154:155], v[154:155], s[100:101] op_sel_hi:[1,0]
	v_pk_add_f32 v[156:157], v[156:157], s[100:101] op_sel_hi:[1,0]
	v_rcp_f32_e32 v150, v150
	v_rcp_f32_e32 v151, v151
	v_rcp_f32_e32 v152, v152
	v_rcp_f32_e32 v153, v153
	v_rcp_f32_e32 v154, v154
	v_rcp_f32_e32 v155, v155
	v_rcp_f32_e32 v156, v156
	v_rcp_f32_e32 v157, v157
	v_pk_mul_f32 v[126:127], v[126:127], v[150:151]
	v_pk_mul_f32 v[128:129], v[128:129], v[152:153]
	v_pk_mul_f32 v[122:123], v[122:123], v[154:155]
	v_pk_mul_f32 v[124:125], v[124:125], v[156:157]
	v_pk_mul_f32 v[118:119], v[118:119], v[126:127]
	v_pk_mul_f32 v[120:121], v[120:121], v[128:129]
	v_pk_mul_f32 v[122:123], v[114:115], v[122:123]
	v_pk_mul_f32 v[124:125], v[116:117], v[124:125]
	v_cvt_pk_bf16_f32 v114, v118, v119
	v_cvt_pk_bf16_f32 v115, v120, v121
	v_cvt_pk_bf16_f32 v116, v122, v123
	v_cvt_pk_bf16_f32 v117, v124, v125
	v_mad_i64_i32 v[118:119], s[6:7], v142, s64, v[140:141]
	global_store_dwordx4 v[118:119], v[114:117], off
	s_nop 1
	v_cndmask_b32_e64 v115, 0, 1, s[24:25]
	v_or_b32_e32 v114, 16, v142
	v_cmp_ne_u32_e64 s[6:7], 1, v115
	s_cbranch_vccnz .LBB0_161
	s_cmp_eq_u32 s48, s12
	s_mov_b64 s[24:25], -1
	s_cbranch_scc1 .LBB0_158
	v_ashrrev_i32_e32 v115, 31, v114
	v_lshlrev_b64 v[116:117], 6, v[114:115]
	v_lshl_add_u64 v[128:129], s[38:39], 0, v[116:117]
	flat_load_dwordx4 v[116:119], v[128:129]
	flat_load_dwordx4 v[120:123], v[128:129] offset:16
	flat_load_dwordx4 v[124:127], v[128:129] offset:32
	flat_load_dwordx4 v[150:153], v[128:129] offset:48
	s_mov_b64 s[24:25], 0
	s_waitcnt vmcnt(0) lgkmcnt(0)
	v_mov_b32_e32 v128, v117
	v_mov_b32_e32 v129, v118
	v_mov_b32_e32 v117, v119
	v_mov_b32_e32 v118, v121
	v_mov_b32_e32 v119, v122
	v_mov_b32_e32 v121, v123
	v_pk_add_f32 v[116:117], v[128:129], v[116:117]
	v_pk_add_f32 v[118:119], v[118:119], v[120:121]
	v_pk_add_f32 v[116:117], v[116:117], v[116:117] op_sel:[0,1] op_sel_hi:[1,0]
	v_pk_add_f32 v[118:119], v[118:119], v[118:119] op_sel:[0,1] op_sel_hi:[1,0]
	v_add_f32_e32 v120, v124, v125
	v_add_f32_e32 v122, v126, v127
	v_mov_b32_e32 v117, v150
	v_mov_b32_e32 v119, v151
	v_mov_b32_e32 v121, v152
	v_mov_b32_e32 v123, v153
	v_pk_add_f32 v[116:117], v[116:117], v[118:119]
	v_pk_add_f32 v[118:119], v[120:121], v[122:123]
	s_nop 0
	v_pk_add_f32 v[116:117], v[116:117], v[118:119]
	s_nop 0
	v_add_f32_e32 v115, v116, v117
	v_fmamk_f32 v115, v115, 0x3a800000, v205
	v_cmp_gt_f32_e32 vcc, s77, v115
	v_mul_f32_e32 v116, 0x4b800000, v115
	s_nop 0
	v_cndmask_b32_e32 v115, v115, v116, vcc
	v_rsq_f32_e32 v115, v115
	s_nop 0
	v_mul_f32_e32 v116, 0x45800000, v115
	v_cndmask_b32_e32 v116, v115, v116, vcc

; __device__ __forceinline__ u32x4 pack8(f32x4 a, f32x4 b) { u32x4 w; w.x = pk2(a[0], a[1]); w.y = pk2(a[2], a[3]); w.z = pk2(b[0], b[1]); w.w = pk2(b[2], b[3]); return w; }
; __device__ __forceinline__ float fast_sigmoid(float x) { return __builtin_amdgcn_rcpf(1.0f + __builtin_amdgcn_exp2f(-x * LOG2E)); }
; __device__ __forceinline__ float row_rs16(const float* ssq_x, int row) {
;     const f32x4* p = (const f32x4*)(ssq_x + (size_t)row * 16); const f32x4 a = p[0], b = p[1], c = p[2], d = p[3];
;     return rsqrtf((((a[0] + a[1]) + (a[2] + a[3])) + ((b[0] + b[1]) + (b[2] + b[3])) + ((c[0] + c[1]) + (c[2] + c[3])) + ((d[0] + d[1]) + (d[2] + d[3]))) * (1.0f / DM) + EPS);
; }
;     __device__ __forceinline__ void operator()(const Acc& acc, const Unit& u, int wr, int wc, int fr, int fq, const RsCtx& rc) const {
;     ...
;             for (int m = 0; m < 4; ++m) { const int row = EPI_ROW(u, ai, wr, m, fr); const float rs = rc.get(u.pm, ai * 128 + wr * 64 + m * 16 + fr, row);
;                 f32x4 a0 = acc[ai][0][m][0] * rs, a1 = acc[ai][0][m][1] * rs; const f32x4 b0 = acc[ai][1][m][0] * rs, b1 = acc[ai][1][m][1] * rs;
; #pragma unroll
;                 for (int e = 0; e < 4; ++e) { a0[e] = a0[e] * fast_sigmoid(a0[e]) * b0[e]; a1[e] = a1[e] * fast_sigmoid(a1[e]) * b1[e]; }
;                 *(u32x4*)(O + (size_t)row * FF + col) = pack8(a0, a1);
.LBB0_163:
	s_waitcnt lgkmcnt(0)
	s_and_b64 vcc, exec, s[6:7]
	s_mov_b32 s100, 0xbfb8aa3b
	v_pk_mul_f32 v[110:111], v[110:111], v[116:117] op_sel_hi:[1,0]
	v_pk_mul_f32 v[112:113], v[112:113], v[116:117] op_sel_hi:[1,0]
	v_pk_mul_f32 v[106:107], v[106:107], v[116:117] op_sel_hi:[1,0]
	v_pk_mul_f32 v[108:109], v[108:109], v[116:117] op_sel_hi:[1,0]
	v_pk_mul_f32 v[118:119], v[110:111], s[100:101] op_sel_hi:[1,0]
	v_pk_mul_f32 v[120:121], v[112:113], s[100:101] op_sel_hi:[1,0]
	v_pk_mul_f32 v[122:123], v[106:107], s[100:101] op_sel_hi:[1,0]
	v_pk_mul_f32 v[124:125], v[108:109], s[100:101] op_sel_hi:[1,0]
	s_mov_b32 s100, 1.0
	v_exp_f32_e32 v118, v118
	v_exp_f32_e32 v119, v119
	v_exp_f32_e32 v120, v120
	v_exp_f32_e32 v121, v121
	v_exp_f32_e32 v122, v122
	v_exp_f32_e32 v123, v123
	v_exp_f32_e32 v124, v124
	v_exp_f32_e32 v125, v125
	v_pk_mul_f32 v[102:103], v[102:103], v[116:117] op_sel_hi:[1,0]
	v_pk_mul_f32 v[104:105], v[104:105], v[116:117] op_sel_hi:[1,0]
	v_pk_mul_f32 v[98:99], v[98:99], v[116:117] op_sel_hi:[1,0]
	v_pk_mul_f32 v[100:101], v[100:101], v[116:117] op_sel_hi:[1,0]
	v_pk_add_f32 v[118:119], v[118:119], s[100:101] op_sel_hi:[1,0]
	v_pk_add_f32 v[120:121], v[120:121], s[100:101] op_sel_hi:[1,0]
	v_pk_add_f32 v[122:123], v[122:123], s[100:101] op_sel_hi:[1,0]
	v_pk_add_f32 v[124:125], v[124:125], s[100:101] op_sel_hi:[1,0]
	v_rcp_f32_e32 v118, v118
	v_rcp_f32_e32 v119, v119
	v_rcp_f32_e32 v120, v120
	v_rcp_f32_e32 v121, v121
	v_rcp_f32_e32 v122, v122
	v_rcp_f32_e32 v123, v123
	v_rcp_f32_e32 v124, v124
	v_rcp_f32_e32 v125, v125
	v_pk_mul_f32 v[110:111], v[110:111], v[118:119]
	v_pk_mul_f32 v[112:113], v[112:113], v[120:121]
	v_pk_mul_f32 v[106:107], v[106:107], v[122:123]
	v_pk_mul_f32 v[108:109], v[108:109], v[124:125]
	v_pk_mul_f32 v[102:103], v[102:103], v[110:111]
	v_pk_mul_f32 v[104:105], v[104:105], v[112:113]
	v_pk_mul_f32 v[106:107], v[98:99], v[106:107]
	v_pk_mul_f32 v[108:109], v[100:101], v[108:109]
	v_cvt_pk_bf16_f32 v98, v102, v103
	v_cvt_pk_bf16_f32 v99, v104, v105
	v_cvt_pk_bf16_f32 v100, v106, v107
	v_cvt_pk_bf16_f32 v101, v108, v109
	v_mad_i64_i32 v[102:103], s[24:25], v114, s64, v[140:141]
	global_store_dwordx4 v[102:103], v[98:101], off
	s_mov_b64 s[24:25], -1
	s_nop 0
	v_or_b32_e32 v98, 32, v142
	s_cbranch_vccnz .LBB0_169
	s_cmp_eq_u32 s48, s12
	s_cbranch_scc1 .LBB0_166
	v_ashrrev_i32_e32 v99, 31, v98
	v_lshlrev_b64 v[100:101], 6, v[98:99]
	v_lshl_add_u64 v[112:113], s[38:39], 0, v[100:101]
	flat_load_dwordx4 v[100:103], v[112:113]
	flat_load_dwordx4 v[104:107], v[112:113] offset:16
	flat_load_dwordx4 v[108:111], v[112:113] offset:32
	s_nop 0
	flat_load_dwordx4 v[112:115], v[112:113] offset:48
	s_mov_b64 s[24:25], 0
	s_waitcnt vmcnt(0) lgkmcnt(0)
	v_mov_b32_e32 v116, v101
	v_mov_b32_e32 v117, v102
	v_mov_b32_e32 v101, v103
	v_mov_b32_e32 v102, v105
	v_mov_b32_e32 v103, v106
	v_mov_b32_e32 v105, v107
	v_pk_add_f32 v[100:101], v[116:117], v[100:101]
	v_pk_add_f32 v[102:103], v[102:103], v[104:105]
	v_pk_add_f32 v[100:101], v[100:101], v[100:101] op_sel:[0,1] op_sel_hi:[1,0]
	v_pk_add_f32 v[102:103], v[102:103], v[102:103] op_sel:[0,1] op_sel_hi:[1,0]
	v_add_f32_e32 v104, v108, v109
	v_add_f32_e32 v106, v110, v111
	v_mov_b32_e32 v101, v112
	v_mov_b32_e32 v103, v113
	v_mov_b32_e32 v105, v114
	v_mov_b32_e32 v107, v115
	v_pk_add_f32 v[100:101], v[100:101], v[102:103]
	v_pk_add_f32 v[102:103], v[104:105], v[106:107]
	s_nop 0
	v_pk_add_f32 v[100:101], v[100:101], v[102:103]
	s_nop 0
	v_add_f32_e32 v99, v100, v101
	v_fmamk_f32 v99, v99, 0x3a800000, v205
	v_cmp_gt_f32_e32 vcc, s77, v99
	v_mul_f32_e32 v100, 0x4b800000, v99
	s_nop 0
	v_cndmask_b32_e32 v99, v99, v100, vcc
	v_rsq_f32_e32 v99, v99
	s_nop 0
	v_mul_f32_e32 v100, 0x45800000, v99
	v_cndmask_b32_e32 v100, v99, v100, vcc

; __device__ __forceinline__ u32x4 pack8(f32x4 a, f32x4 b) { u32x4 w; w.x = pk2(a[0], a[1]); w.y = pk2(a[2], a[3]); w.z = pk2(b[0], b[1]); w.w = pk2(b[2], b[3]); return w; }
; __device__ __forceinline__ float fast_sigmoid(float x) { return __builtin_amdgcn_rcpf(1.0f + __builtin_amdgcn_exp2f(-x * LOG2E)); }
; __device__ __forceinline__ float row_rs16(const float* ssq_x, int row) {
;     const f32x4* p = (const f32x4*)(ssq_x + (size_t)row * 16); const f32x4 a = p[0], b = p[1], c = p[2], d = p[3];
;     return rsqrtf((((a[0] + a[1]) + (a[2] + a[3])) + ((b[0] + b[1]) + (b[2] + b[3])) + ((c[0] + c[1]) + (c[2] + c[3])) + ((d[0] + d[1]) + (d[2] + d[3]))) * (1.0f / DM) + EPS);
; }
;     __device__ __forceinline__ void operator()(const Acc& acc, const Unit& u, int wr, int wc, int fr, int fq, const RsCtx& rc) const {
;     ...
;             for (int m = 0; m < 4; ++m) { const int row = EPI_ROW(u, ai, wr, m, fr); const float rs = rc.get(u.pm, ai * 128 + wr * 64 + m * 16 + fr, row);
;                 f32x4 a0 = acc[ai][0][m][0] * rs, a1 = acc[ai][0][m][1] * rs; const f32x4 b0 = acc[ai][1][m][0] * rs, b1 = acc[ai][1][m][1] * rs;
; #pragma unroll
;                 for (int e = 0; e < 4; ++e) { a0[e] = a0[e] * fast_sigmoid(a0[e]) * b0[e]; a1[e] = a1[e] * fast_sigmoid(a1[e]) * b1[e]; }
;                 *(u32x4*)(O + (size_t)row * FF + col) = pack8(a0, a1);
.LBB0_171:
	s_waitcnt lgkmcnt(0)
	s_and_b64 vcc, exec, s[6:7]
	s_mov_b32 s100, 0xbfb8aa3b
	v_pk_mul_f32 v[94:95], v[94:95], v[100:101] op_sel_hi:[1,0]
	v_pk_mul_f32 v[96:97], v[96:97], v[100:101] op_sel_hi:[1,0]
	v_pk_mul_f32 v[90:91], v[90:91], v[100:101] op_sel_hi:[1,0]
	v_pk_mul_f32 v[92:93], v[92:93], v[100:101] op_sel_hi:[1,0]
	v_pk_mul_f32 v[102:103], v[94:95], s[100:101] op_sel_hi:[1,0]
	v_pk_mul_f32 v[104:105], v[96:97], s[100:101] op_sel_hi:[1,0]
	v_pk_mul_f32 v[106:107], v[90:91], s[100:101] op_sel_hi:[1,0]
	v_pk_mul_f32 v[108:109], v[92:93], s[100:101] op_sel_hi:[1,0]
	s_mov_b32 s100, 1.0
	v_exp_f32_e32 v102, v102
	v_exp_f32_e32 v103, v103
	v_exp_f32_e32 v104, v104
	v_exp_f32_e32 v105, v105
	v_exp_f32_e32 v106, v106
	v_exp_f32_e32 v107, v107
	v_exp_f32_e32 v108, v108
	v_exp_f32_e32 v109, v109
	v_pk_mul_f32 v[86:87], v[86:87], v[100:101] op_sel_hi:[1,0]
	v_pk_mul_f32 v[88:89], v[88:89], v[100:101] op_sel_hi:[1,0]
	v_pk_mul_f32 v[82:83], v[82:83], v[100:101] op_sel_hi:[1,0]
	v_pk_mul_f32 v[84:85], v[84:85], v[100:101] op_sel_hi:[1,0]
	v_pk_add_f32 v[102:103], v[102:103], s[100:101] op_sel_hi:[1,0]
	v_pk_add_f32 v[104:105], v[104:105], s[100:101] op_sel_hi:[1,0]
	v_pk_add_f32 v[106:107], v[106:107], s[100:101] op_sel_hi:[1,0]
	v_pk_add_f32 v[108:109], v[108:109], s[100:101] op_sel_hi:[1,0]
	v_rcp_f32_e32 v102, v102
	v_rcp_f32_e32 v103, v103
	v_rcp_f32_e32 v104, v104
	v_rcp_f32_e32 v105, v105
	v_rcp_f32_e32 v106, v106
	v_rcp_f32_e32 v107, v107
	v_rcp_f32_e32 v108, v108
	v_rcp_f32_e32 v109, v109
	v_pk_mul_f32 v[94:95], v[94:95], v[102:103]
	v_pk_mul_f32 v[96:97], v[96:97], v[104:105]
	v_pk_mul_f32 v[90:91], v[90:91], v[106:107]
	v_pk_mul_f32 v[92:93], v[92:93], v[108:109]
	v_pk_mul_f32 v[86:87], v[86:87], v[94:95]
	v_pk_mul_f32 v[88:89], v[88:89], v[96:97]
	v_pk_mul_f32 v[90:91], v[82:83], v[90:91]
	v_pk_mul_f32 v[92:93], v[84:85], v[92:93]
	v_cvt_pk_bf16_f32 v82, v86, v87
	v_cvt_pk_bf16_f32 v83, v88, v89
	v_cvt_pk_bf16_f32 v84, v90, v91
	v_cvt_pk_bf16_f32 v85, v92, v93
	v_mad_i64_i32 v[86:87], s[24:25], v98, s64, v[140:141]
	global_store_dwordx4 v[86:87], v[82:85], off
	s_mov_b64 s[24:25], -1
	s_nop 0
	v_or_b32_e32 v82, 48, v142
	s_cbranch_vccnz .LBB0_177
	s_cmp_eq_u32 s48, s12
	s_cbranch_scc1 .LBB0_174
	v_ashrrev_i32_e32 v83, 31, v82
	v_lshlrev_b64 v[84:85], 6, v[82:83]
	v_lshl_add_u64 v[96:97], s[38:39], 0, v[84:85]
	flat_load_dwordx4 v[84:87], v[96:97]
	flat_load_dwordx4 v[88:91], v[96:97] offset:16
	flat_load_dwordx4 v[92:95], v[96:97] offset:32
	s_nop 0
	flat_load_dwordx4 v[96:99], v[96:97] offset:48
	s_mov_b64 s[24:25], 0
	s_waitcnt vmcnt(0) lgkmcnt(0)
	v_mov_b32_e32 v100, v85
	v_mov_b32_e32 v101, v86
	v_mov_b32_e32 v85, v87
	v_mov_b32_e32 v86, v89
	v_mov_b32_e32 v87, v90
	v_mov_b32_e32 v89, v91
	v_pk_add_f32 v[84:85], v[100:101], v[84:85]
	v_pk_add_f32 v[86:87], v[86:87], v[88:89]
	v_pk_add_f32 v[84:85], v[84:85], v[84:85] op_sel:[0,1] op_sel_hi:[1,0]
	v_pk_add_f32 v[86:87], v[86:87], v[86:87] op_sel:[0,1] op_sel_hi:[1,0]
	v_add_f32_e32 v88, v92, v93
	v_add_f32_e32 v90, v94, v95
	v_mov_b32_e32 v85, v96
	v_mov_b32_e32 v87, v97
	v_mov_b32_e32 v89, v98
	v_mov_b32_e32 v91, v99
	v_pk_add_f32 v[84:85], v[84:85], v[86:87]
	v_pk_add_f32 v[86:87], v[88:89], v[90:91]
	s_nop 0
	v_pk_add_f32 v[84:85], v[84:85], v[86:87]
	s_nop 0
	v_add_f32_e32 v83, v84, v85
	v_fmamk_f32 v83, v83, 0x3a800000, v205
	v_cmp_gt_f32_e32 vcc, s77, v83
	v_mul_f32_e32 v84, 0x4b800000, v83
	s_nop 0
	v_cndmask_b32_e32 v83, v83, v84, vcc
	v_rsq_f32_e32 v83, v83
	s_nop 0
	v_mul_f32_e32 v84, 0x45800000, v83
	v_cndmask_b32_e32 v84, v83, v84, vcc

; __device__ __forceinline__ u32x4 pack8(f32x4 a, f32x4 b) { u32x4 w; w.x = pk2(a[0], a[1]); w.y = pk2(a[2], a[3]); w.z = pk2(b[0], b[1]); w.w = pk2(b[2], b[3]); return w; }
; __device__ __forceinline__ float fast_sigmoid(float x) { return __builtin_amdgcn_rcpf(1.0f + __builtin_amdgcn_exp2f(-x * LOG2E)); }
; __device__ __forceinline__ float row_rs16(const float* ssq_x, int row) {
;     const f32x4* p = (const f32x4*)(ssq_x + (size_t)row * 16); const f32x4 a = p[0], b = p[1], c = p[2], d = p[3];
;     return rsqrtf((((a[0] + a[1]) + (a[2] + a[3])) + ((b[0] + b[1]) + (b[2] + b[3])) + ((c[0] + c[1]) + (c[2] + c[3])) + ((d[0] + d[1]) + (d[2] + d[3]))) * (1.0f / DM) + EPS);
; }
;     __device__ __forceinline__ void operator()(const Acc& acc, const Unit& u, int wr, int wc, int fr, int fq, const RsCtx& rc) const {
;     ...
;             for (int m = 0; m < 4; ++m) { const int row = EPI_ROW(u, ai, wr, m, fr); const float rs = rc.get(u.pm, ai * 128 + wr * 64 + m * 16 + fr, row);
;                 f32x4 a0 = acc[ai][0][m][0] * rs, a1 = acc[ai][0][m][1] * rs; const f32x4 b0 = acc[ai][1][m][0] * rs, b1 = acc[ai][1][m][1] * rs;
; #pragma unroll
;                 for (int e = 0; e < 4; ++e) { a0[e] = a0[e] * fast_sigmoid(a0[e]) * b0[e]; a1[e] = a1[e] * fast_sigmoid(a1[e]) * b1[e]; }
;                 *(u32x4*)(O + (size_t)row * FF + col) = pack8(a0, a1);
.LBB0_179:
	s_waitcnt lgkmcnt(0)
	s_and_b64 vcc, exec, s[6:7]
	s_mov_b32 s100, 0xbfb8aa3b
	v_pk_mul_f32 v[78:79], v[78:79], v[84:85] op_sel_hi:[1,0]
	v_pk_mul_f32 v[80:81], v[80:81], v[84:85] op_sel_hi:[1,0]
	v_pk_mul_f32 v[74:75], v[74:75], v[84:85] op_sel_hi:[1,0]
	v_pk_mul_f32 v[76:77], v[76:77], v[84:85] op_sel_hi:[1,0]
	v_pk_mul_f32 v[86:87], v[78:79], s[100:101] op_sel_hi:[1,0]
	v_pk_mul_f32 v[88:89], v[80:81], s[100:101] op_sel_hi:[1,0]
	v_pk_mul_f32 v[90:91], v[74:75], s[100:101] op_sel_hi:[1,0]
	v_pk_mul_f32 v[92:93], v[76:77], s[100:101] op_sel_hi:[1,0]
	s_mov_b32 s100, 1.0
	v_exp_f32_e32 v86, v86
	v_exp_f32_e32 v87, v87
	v_exp_f32_e32 v88, v88
	v_exp_f32_e32 v89, v89
	v_exp_f32_e32 v90, v90
	v_exp_f32_e32 v91, v91
	v_exp_f32_e32 v92, v92
	v_exp_f32_e32 v93, v93
	v_pk_mul_f32 v[70:71], v[70:71], v[84:85] op_sel_hi:[1,0]
	v_pk_mul_f32 v[72:73], v[72:73], v[84:85] op_sel_hi:[1,0]
	v_pk_mul_f32 v[66:67], v[66:67], v[84:85] op_sel_hi:[1,0]
	v_pk_mul_f32 v[68:69], v[68:69], v[84:85] op_sel_hi:[1,0]
	v_pk_add_f32 v[86:87], v[86:87], s[100:101] op_sel_hi:[1,0]
	v_pk_add_f32 v[88:89], v[88:89], s[100:101] op_sel_hi:[1,0]
	v_pk_add_f32 v[90:91], v[90:91], s[100:101] op_sel_hi:[1,0]
	v_pk_add_f32 v[92:93], v[92:93], s[100:101] op_sel_hi:[1,0]
	v_rcp_f32_e32 v86, v86
	v_rcp_f32_e32 v87, v87
	v_rcp_f32_e32 v88, v88
	v_rcp_f32_e32 v89, v89
	v_rcp_f32_e32 v90, v90
	v_rcp_f32_e32 v91, v91
	v_rcp_f32_e32 v92, v92
	v_rcp_f32_e32 v93, v93
	v_pk_mul_f32 v[78:79], v[78:79], v[86:87]
	v_pk_mul_f32 v[80:81], v[80:81], v[88:89]
	v_pk_mul_f32 v[74:75], v[74:75], v[90:91]
	v_pk_mul_f32 v[76:77], v[76:77], v[92:93]
	v_pk_mul_f32 v[70:71], v[70:71], v[78:79]
	v_pk_mul_f32 v[72:73], v[72:73], v[80:81]
	v_pk_mul_f32 v[74:75], v[66:67], v[74:75]
	v_pk_mul_f32 v[76:77], v[68:69], v[76:77]
	v_cvt_pk_bf16_f32 v66, v70, v71
	v_cvt_pk_bf16_f32 v67, v72, v73
	v_cvt_pk_bf16_f32 v68, v74, v75
	v_cvt_pk_bf16_f32 v69, v76, v77
	v_mad_i64_i32 v[70:71], s[24:25], v82, s64, v[140:141]
	global_store_dwordx4 v[70:71], v[66:69], off
	s_mov_b64 s[24:25], -1
	s_nop 0
	v_add_u32_e32 v66, 0x80, v142
	s_cbranch_vccnz .LBB0_185
	s_cmp_eq_u32 s48, s12
	s_cbranch_scc1 .LBB0_182
	v_ashrrev_i32_e32 v67, 31, v66
	v_lshlrev_b64 v[68:69], 6, v[66:67]
	v_lshl_add_u64 v[80:81], s[38:39], 0, v[68:69]
	flat_load_dwordx4 v[68:71], v[80:81]
	flat_load_dwordx4 v[72:75], v[80:81] offset:16
	flat_load_dwordx4 v[76:79], v[80:81] offset:32
	s_nop 0
	flat_load_dwordx4 v[80:83], v[80:81] offset:48
	s_mov_b64 s[24:25], 0
	s_waitcnt vmcnt(0) lgkmcnt(0)
	v_mov_b32_e32 v84, v69
	v_mov_b32_e32 v85, v70
	v_mov_b32_e32 v69, v71
	v_mov_b32_e32 v70, v73
	v_mov_b32_e32 v71, v74
	v_mov_b32_e32 v73, v75
	v_pk_add_f32 v[68:69], v[84:85], v[68:69]
	v_pk_add_f32 v[70:71], v[70:71], v[72:73]
	v_pk_add_f32 v[68:69], v[68:69], v[68:69] op_sel:[0,1] op_sel_hi:[1,0]
	v_pk_add_f32 v[70:71], v[70:71], v[70:71] op_sel:[0,1] op_sel_hi:[1,0]
	v_add_f32_e32 v72, v76, v77
	v_add_f32_e32 v74, v78, v79
	v_mov_b32_e32 v69, v80
	v_mov_b32_e32 v71, v81
	v_mov_b32_e32 v73, v82
	v_mov_b32_e32 v75, v83
	v_pk_add_f32 v[68:69], v[68:69], v[70:71]
	v_pk_add_f32 v[70:71], v[72:73], v[74:75]
	s_nop 0
	v_pk_add_f32 v[68:69], v[68:69], v[70:71]
	s_nop 0
	v_add_f32_e32 v67, v68, v69
	v_fmamk_f32 v67, v67, 0x3a800000, v205
	v_cmp_gt_f32_e32 vcc, s77, v67
	v_mul_f32_e32 v68, 0x4b800000, v67
	s_nop 0
	v_cndmask_b32_e32 v67, v67, v68, vcc
	v_rsq_f32_e32 v67, v67
	s_nop 0
	v_mul_f32_e32 v68, 0x45800000, v67
	v_cndmask_b32_e32 v68, v67, v68, vcc

; __device__ __forceinline__ u32x4 pack8(f32x4 a, f32x4 b) { u32x4 w; w.x = pk2(a[0], a[1]); w.y = pk2(a[2], a[3]); w.z = pk2(b[0], b[1]); w.w = pk2(b[2], b[3]); return w; }
; __device__ __forceinline__ float fast_sigmoid(float x) { return __builtin_amdgcn_rcpf(1.0f + __builtin_amdgcn_exp2f(-x * LOG2E)); }
; __device__ __forceinline__ float row_rs16(const float* ssq_x, int row) {
;     const f32x4* p = (const f32x4*)(ssq_x + (size_t)row * 16); const f32x4 a = p[0], b = p[1], c = p[2], d = p[3];
;     return rsqrtf((((a[0] + a[1]) + (a[2] + a[3])) + ((b[0] + b[1]) + (b[2] + b[3])) + ((c[0] + c[1]) + (c[2] + c[3])) + ((d[0] + d[1]) + (d[2] + d[3]))) * (1.0f / DM) + EPS);
; }
;     __device__ __forceinline__ void operator()(const Acc& acc, const Unit& u, int wr, int wc, int fr, int fq, const RsCtx& rc) const {
;     ...
;             for (int m = 0; m < 4; ++m) { const int row = EPI_ROW(u, ai, wr, m, fr); const float rs = rc.get(u.pm, ai * 128 + wr * 64 + m * 16 + fr, row);
;                 f32x4 a0 = acc[ai][0][m][0] * rs, a1 = acc[ai][0][m][1] * rs; const f32x4 b0 = acc[ai][1][m][0] * rs, b1 = acc[ai][1][m][1] * rs;
; #pragma unroll
;                 for (int e = 0; e < 4; ++e) { a0[e] = a0[e] * fast_sigmoid(a0[e]) * b0[e]; a1[e] = a1[e] * fast_sigmoid(a1[e]) * b1[e]; }
;                 *(u32x4*)(O + (size_t)row * FF + col) = pack8(a0, a1);
.LBB0_187:
	s_waitcnt lgkmcnt(0)
	s_and_b64 vcc, exec, s[6:7]
	s_mov_b32 s100, 0xbfb8aa3b
	v_pk_mul_f32 v[62:63], v[62:63], v[68:69] op_sel_hi:[1,0]
	v_pk_mul_f32 v[64:65], v[64:65], v[68:69] op_sel_hi:[1,0]
	v_pk_mul_f32 v[58:59], v[58:59], v[68:69] op_sel_hi:[1,0]
	v_pk_mul_f32 v[60:61], v[60:61], v[68:69] op_sel_hi:[1,0]
	v_pk_mul_f32 v[70:71], v[62:63], s[100:101] op_sel_hi:[1,0]
	v_pk_mul_f32 v[72:73], v[64:65], s[100:101] op_sel_hi:[1,0]
	v_pk_mul_f32 v[74:75], v[58:59], s[100:101] op_sel_hi:[1,0]
	v_pk_mul_f32 v[76:77], v[60:61], s[100:101] op_sel_hi:[1,0]
	s_mov_b32 s100, 1.0
	v_exp_f32_e32 v70, v70
	v_exp_f32_e32 v71, v71
	v_exp_f32_e32 v72, v72
	v_exp_f32_e32 v73, v73
	v_exp_f32_e32 v74, v74
	v_exp_f32_e32 v75, v75
	v_exp_f32_e32 v76, v76
	v_exp_f32_e32 v77, v77
	v_pk_mul_f32 v[54:55], v[54:55], v[68:69] op_sel_hi:[1,0]
	v_pk_mul_f32 v[56:57], v[56:57], v[68:69] op_sel_hi:[1,0]
	v_pk_mul_f32 v[50:51], v[50:51], v[68:69] op_sel_hi:[1,0]
	v_pk_mul_f32 v[52:53], v[52:53], v[68:69] op_sel_hi:[1,0]
	v_pk_add_f32 v[70:71], v[70:71], s[100:101] op_sel_hi:[1,0]
	v_pk_add_f32 v[72:73], v[72:73], s[100:101] op_sel_hi:[1,0]
	v_pk_add_f32 v[74:75], v[74:75], s[100:101] op_sel_hi:[1,0]
	v_pk_add_f32 v[76:77], v[76:77], s[100:101] op_sel_hi:[1,0]
	v_rcp_f32_e32 v70, v70
	v_rcp_f32_e32 v71, v71
	v_rcp_f32_e32 v72, v72
	v_rcp_f32_e32 v73, v73
	v_rcp_f32_e32 v74, v74
	v_rcp_f32_e32 v75, v75
	v_rcp_f32_e32 v76, v76
	v_rcp_f32_e32 v77, v77
	v_pk_mul_f32 v[62:63], v[62:63], v[70:71]
	v_pk_mul_f32 v[64:65], v[64:65], v[72:73]
	v_pk_mul_f32 v[58:59], v[58:59], v[74:75]
	v_pk_mul_f32 v[60:61], v[60:61], v[76:77]
	v_pk_mul_f32 v[54:55], v[54:55], v[62:63]
	v_pk_mul_f32 v[56:57], v[56:57], v[64:65]
	v_pk_mul_f32 v[58:59], v[50:51], v[58:59]
	v_pk_mul_f32 v[60:61], v[52:53], v[60:61]
	v_cvt_pk_bf16_f32 v50, v54, v55
	v_cvt_pk_bf16_f32 v51, v56, v57
	v_cvt_pk_bf16_f32 v52, v58, v59
	v_cvt_pk_bf16_f32 v53, v60, v61
	v_mad_i64_i32 v[54:55], s[24:25], v66, s64, v[140:141]
	global_store_dwordx4 v[54:55], v[50:53], off
	s_mov_b64 s[24:25], -1
	s_nop 0
	v_add_u32_e32 v50, 0x90, v142
	s_cbranch_vccnz .LBB0_193
	s_cmp_eq_u32 s48, s12
	s_cbranch_scc1 .LBB0_190
	v_ashrrev_i32_e32 v51, 31, v50
	v_lshlrev_b64 v[52:53], 6, v[50:51]
	v_lshl_add_u64 v[64:65], s[38:39], 0, v[52:53]
	flat_load_dwordx4 v[52:55], v[64:65]
	flat_load_dwordx4 v[56:59], v[64:65] offset:16
	flat_load_dwordx4 v[60:63], v[64:65] offset:32
	s_nop 0
	flat_load_dwordx4 v[64:67], v[64:65] offset:48
	s_mov_b64 s[24:25], 0
	s_waitcnt vmcnt(0) lgkmcnt(0)
	v_mov_b32_e32 v68, v53
	v_mov_b32_e32 v69, v54
	v_mov_b32_e32 v53, v55
	v_mov_b32_e32 v54, v57
	v_mov_b32_e32 v55, v58
	v_mov_b32_e32 v57, v59
	v_pk_add_f32 v[52:53], v[68:69], v[52:53]
	v_pk_add_f32 v[54:55], v[54:55], v[56:57]
	v_pk_add_f32 v[52:53], v[52:53], v[52:53] op_sel:[0,1] op_sel_hi:[1,0]
	v_pk_add_f32 v[54:55], v[54:55], v[54:55] op_sel:[0,1] op_sel_hi:[1,0]
	v_add_f32_e32 v56, v60, v61
	v_add_f32_e32 v58, v62, v63
	v_mov_b32_e32 v53, v64
	v_mov_b32_e32 v55, v65
	v_mov_b32_e32 v57, v66
	v_mov_b32_e32 v59, v67
	v_pk_add_f32 v[52:53], v[52:53], v[54:55]
	v_pk_add_f32 v[54:55], v[56:57], v[58:59]
	s_nop 0
	v_pk_add_f32 v[52:53], v[52:53], v[54:55]
	s_nop 0
	v_add_f32_e32 v51, v52, v53
	v_fmamk_f32 v51, v51, 0x3a800000, v205
	v_cmp_gt_f32_e32 vcc, s77, v51
	v_mul_f32_e32 v52, 0x4b800000, v51
	s_nop 0
	v_cndmask_b32_e32 v51, v51, v52, vcc
	v_rsq_f32_e32 v51, v51
	s_nop 0
	v_mul_f32_e32 v52, 0x45800000, v51
	v_cndmask_b32_e32 v52, v51, v52, vcc

; __device__ __forceinline__ u32x4 pack8(f32x4 a, f32x4 b) { u32x4 w; w.x = pk2(a[0], a[1]); w.y = pk2(a[2], a[3]); w.z = pk2(b[0], b[1]); w.w = pk2(b[2], b[3]); return w; }
; __device__ __forceinline__ float fast_sigmoid(float x) { return __builtin_amdgcn_rcpf(1.0f + __builtin_amdgcn_exp2f(-x * LOG2E)); }
; __device__ __forceinline__ float row_rs16(const float* ssq_x, int row) {
;     const f32x4* p = (const f32x4*)(ssq_x + (size_t)row * 16); const f32x4 a = p[0], b = p[1], c = p[2], d = p[3];
;     return rsqrtf((((a[0] + a[1]) + (a[2] + a[3])) + ((b[0] + b[1]) + (b[2] + b[3])) + ((c[0] + c[1]) + (c[2] + c[3])) + ((d[0] + d[1]) + (d[2] + d[3]))) * (1.0f / DM) + EPS);
; }
;     __device__ __forceinline__ void operator()(const Acc& acc, const Unit& u, int wr, int wc, int fr, int fq, const RsCtx& rc) const {
;     ...
;             for (int m = 0; m < 4; ++m) { const int row = EPI_ROW(u, ai, wr, m, fr); const float rs = rc.get(u.pm, ai * 128 + wr * 64 + m * 16 + fr, row);
;                 f32x4 a0 = acc[ai][0][m][0] * rs, a1 = acc[ai][0][m][1] * rs; const f32x4 b0 = acc[ai][1][m][0] * rs, b1 = acc[ai][1][m][1] * rs;
; #pragma unroll
;                 for (int e = 0; e < 4; ++e) { a0[e] = a0[e] * fast_sigmoid(a0[e]) * b0[e]; a1[e] = a1[e] * fast_sigmoid(a1[e]) * b1[e]; }
;                 *(u32x4*)(O + (size_t)row * FF + col) = pack8(a0, a1);
.LBB0_195:
	s_waitcnt lgkmcnt(0)
	s_and_b64 vcc, exec, s[6:7]
	s_mov_b32 s100, 0xbfb8aa3b
	v_pk_mul_f32 v[46:47], v[46:47], v[52:53] op_sel_hi:[1,0]
	v_pk_mul_f32 v[48:49], v[48:49], v[52:53] op_sel_hi:[1,0]
	v_pk_mul_f32 v[42:43], v[42:43], v[52:53] op_sel_hi:[1,0]
	v_pk_mul_f32 v[44:45], v[44:45], v[52:53] op_sel_hi:[1,0]
	v_pk_mul_f32 v[54:55], v[46:47], s[100:101] op_sel_hi:[1,0]
	v_pk_mul_f32 v[56:57], v[48:49], s[100:101] op_sel_hi:[1,0]
	v_pk_mul_f32 v[58:59], v[42:43], s[100:101] op_sel_hi:[1,0]
	v_pk_mul_f32 v[60:61], v[44:45], s[100:101] op_sel_hi:[1,0]
	s_mov_b32 s100, 1.0
	v_exp_f32_e32 v54, v54
	v_exp_f32_e32 v55, v55
	v_exp_f32_e32 v56, v56
	v_exp_f32_e32 v57, v57
	v_exp_f32_e32 v58, v58
	v_exp_f32_e32 v59, v59
	v_exp_f32_e32 v60, v60
	v_exp_f32_e32 v61, v61
	v_pk_mul_f32 v[38:39], v[38:39], v[52:53] op_sel_hi:[1,0]
	v_pk_mul_f32 v[40:41], v[40:41], v[52:53] op_sel_hi:[1,0]
	v_pk_mul_f32 v[34:35], v[34:35], v[52:53] op_sel_hi:[1,0]
	v_pk_mul_f32 v[36:37], v[36:37], v[52:53] op_sel_hi:[1,0]
	v_pk_add_f32 v[54:55], v[54:55], s[100:101] op_sel_hi:[1,0]
	v_pk_add_f32 v[56:57], v[56:57], s[100:101] op_sel_hi:[1,0]
	v_pk_add_f32 v[58:59], v[58:59], s[100:101] op_sel_hi:[1,0]
	v_pk_add_f32 v[60:61], v[60:61], s[100:101] op_sel_hi:[1,0]
	v_rcp_f32_e32 v54, v54
	v_rcp_f32_e32 v55, v55
	v_rcp_f32_e32 v56, v56
	v_rcp_f32_e32 v57, v57
	v_rcp_f32_e32 v58, v58
	v_rcp_f32_e32 v59, v59
	v_rcp_f32_e32 v60, v60
	v_rcp_f32_e32 v61, v61
	v_pk_mul_f32 v[46:47], v[46:47], v[54:55]
	v_pk_mul_f32 v[48:49], v[48:49], v[56:57]
	v_pk_mul_f32 v[42:43], v[42:43], v[58:59]
	v_pk_mul_f32 v[44:45], v[44:45], v[60:61]
	v_pk_mul_f32 v[38:39], v[38:39], v[46:47]
	v_pk_mul_f32 v[40:41], v[40:41], v[48:49]
	v_pk_mul_f32 v[42:43], v[34:35], v[42:43]
	v_pk_mul_f32 v[44:45], v[36:37], v[44:45]
	v_cvt_pk_bf16_f32 v34, v38, v39
	v_cvt_pk_bf16_f32 v35, v40, v41
	v_cvt_pk_bf16_f32 v36, v42, v43
	v_cvt_pk_bf16_f32 v37, v44, v45
	v_mad_i64_i32 v[38:39], s[24:25], v50, s64, v[140:141]
	global_store_dwordx4 v[38:39], v[34:37], off
	s_mov_b64 s[24:25], -1
	s_nop 0
	v_add_u32_e32 v34, 0xa0, v142
	s_cbranch_vccnz .LBB0_201
	s_cmp_eq_u32 s48, s12
	s_cbranch_scc1 .LBB0_198
	v_ashrrev_i32_e32 v35, 31, v34
	v_lshlrev_b64 v[36:37], 6, v[34:35]
	v_lshl_add_u64 v[48:49], s[38:39], 0, v[36:37]
	flat_load_dwordx4 v[36:39], v[48:49]
	flat_load_dwordx4 v[40:43], v[48:49] offset:16
	flat_load_dwordx4 v[44:47], v[48:49] offset:32
	s_nop 0
	flat_load_dwordx4 v[48:51], v[48:49] offset:48
	s_mov_b64 s[24:25], 0
	s_waitcnt vmcnt(0) lgkmcnt(0)
	v_mov_b32_e32 v52, v37
	v_mov_b32_e32 v53, v38
	v_mov_b32_e32 v37, v39
	v_mov_b32_e32 v38, v41
	v_mov_b32_e32 v39, v42
	v_mov_b32_e32 v41, v43
	v_pk_add_f32 v[36:37], v[52:53], v[36:37]
	v_pk_add_f32 v[38:39], v[38:39], v[40:41]
	v_pk_add_f32 v[36:37], v[36:37], v[36:37] op_sel:[0,1] op_sel_hi:[1,0]
	v_pk_add_f32 v[38:39], v[38:39], v[38:39] op_sel:[0,1] op_sel_hi:[1,0]
	v_add_f32_e32 v40, v44, v45
	v_add_f32_e32 v42, v46, v47
	v_mov_b32_e32 v37, v48
	v_mov_b32_e32 v39, v49
	v_mov_b32_e32 v41, v50
	v_mov_b32_e32 v43, v51
	v_pk_add_f32 v[36:37], v[36:37], v[38:39]
	v_pk_add_f32 v[38:39], v[40:41], v[42:43]
	s_nop 0
	v_pk_add_f32 v[36:37], v[36:37], v[38:39]
	s_nop 0
	v_add_f32_e32 v35, v36, v37
	v_fmamk_f32 v35, v35, 0x3a800000, v205
	v_cmp_gt_f32_e32 vcc, s77, v35
	v_mul_f32_e32 v36, 0x4b800000, v35
	s_nop 0
	v_cndmask_b32_e32 v35, v35, v36, vcc
	v_rsq_f32_e32 v35, v35
	s_nop 0
	v_mul_f32_e32 v36, 0x45800000, v35
	v_cndmask_b32_e32 v36, v35, v36, vcc

; __device__ __forceinline__ u32x4 pack8(f32x4 a, f32x4 b) { u32x4 w; w.x = pk2(a[0], a[1]); w.y = pk2(a[2], a[3]); w.z = pk2(b[0], b[1]); w.w = pk2(b[2], b[3]); return w; }
; __device__ __forceinline__ float fast_sigmoid(float x) { return __builtin_amdgcn_rcpf(1.0f + __builtin_amdgcn_exp2f(-x * LOG2E)); }
; __device__ __forceinline__ float row_rs16(const float* ssq_x, int row) {
;     const f32x4* p = (const f32x4*)(ssq_x + (size_t)row * 16); const f32x4 a = p[0], b = p[1], c = p[2], d = p[3];
;     return rsqrtf((((a[0] + a[1]) + (a[2] + a[3])) + ((b[0] + b[1]) + (b[2] + b[3])) + ((c[0] + c[1]) + (c[2] + c[3])) + ((d[0] + d[1]) + (d[2] + d[3]))) * (1.0f / DM) + EPS);
; }
;     __device__ __forceinline__ void operator()(const Acc& acc, const Unit& u, int wr, int wc, int fr, int fq, const RsCtx& rc) const {
;     ...
;             for (int m = 0; m < 4; ++m) { const int row = EPI_ROW(u, ai, wr, m, fr); const float rs = rc.get(u.pm, ai * 128 + wr * 64 + m * 16 + fr, row);
;                 f32x4 a0 = acc[ai][0][m][0] * rs, a1 = acc[ai][0][m][1] * rs; const f32x4 b0 = acc[ai][1][m][0] * rs, b1 = acc[ai][1][m][1] * rs;
; #pragma unroll
;                 for (int e = 0; e < 4; ++e) { a0[e] = a0[e] * fast_sigmoid(a0[e]) * b0[e]; a1[e] = a1[e] * fast_sigmoid(a1[e]) * b1[e]; }
;                 *(u32x4*)(O + (size_t)row * FF + col) = pack8(a0, a1);
.LBB0_203:
	s_waitcnt lgkmcnt(0)
	s_and_b64 vcc, exec, s[6:7]
	s_mov_b32 s100, 0xbfb8aa3b
	v_pk_mul_f32 v[30:31], v[30:31], v[36:37] op_sel_hi:[1,0]
	v_pk_mul_f32 v[32:33], v[32:33], v[36:37] op_sel_hi:[1,0]
	v_pk_mul_f32 v[26:27], v[26:27], v[36:37] op_sel_hi:[1,0]
	v_pk_mul_f32 v[28:29], v[28:29], v[36:37] op_sel_hi:[1,0]
	v_pk_mul_f32 v[38:39], v[30:31], s[100:101] op_sel_hi:[1,0]
	v_pk_mul_f32 v[40:41], v[32:33], s[100:101] op_sel_hi:[1,0]
	v_pk_mul_f32 v[42:43], v[26:27], s[100:101] op_sel_hi:[1,0]
	v_pk_mul_f32 v[44:45], v[28:29], s[100:101] op_sel_hi:[1,0]
	s_mov_b32 s100, 1.0
	v_exp_f32_e32 v38, v38
	v_exp_f32_e32 v39, v39
	v_exp_f32_e32 v40, v40
	v_exp_f32_e32 v41, v41
	v_exp_f32_e32 v42, v42
	v_exp_f32_e32 v43, v43
	v_exp_f32_e32 v44, v44
	v_exp_f32_e32 v45, v45
	v_pk_mul_f32 v[22:23], v[22:23], v[36:37] op_sel_hi:[1,0]
	v_pk_mul_f32 v[24:25], v[24:25], v[36:37] op_sel_hi:[1,0]
	v_pk_mul_f32 v[18:19], v[18:19], v[36:37] op_sel_hi:[1,0]
	v_pk_mul_f32 v[20:21], v[20:21], v[36:37] op_sel_hi:[1,0]
	v_pk_add_f32 v[38:39], v[38:39], s[100:101] op_sel_hi:[1,0]
	v_pk_add_f32 v[40:41], v[40:41], s[100:101] op_sel_hi:[1,0]
	v_pk_add_f32 v[42:43], v[42:43], s[100:101] op_sel_hi:[1,0]
	v_pk_add_f32 v[44:45], v[44:45], s[100:101] op_sel_hi:[1,0]
	v_rcp_f32_e32 v38, v38
	v_rcp_f32_e32 v39, v39
	v_rcp_f32_e32 v40, v40
	v_rcp_f32_e32 v41, v41
	v_rcp_f32_e32 v42, v42
	v_rcp_f32_e32 v43, v43
	v_rcp_f32_e32 v44, v44
	v_rcp_f32_e32 v45, v45
	v_pk_mul_f32 v[30:31], v[30:31], v[38:39]
	v_pk_mul_f32 v[32:33], v[32:33], v[40:41]
	v_pk_mul_f32 v[26:27], v[26:27], v[42:43]
	v_pk_mul_f32 v[28:29], v[28:29], v[44:45]
	v_pk_mul_f32 v[22:23], v[22:23], v[30:31]
	v_pk_mul_f32 v[24:25], v[24:25], v[32:33]
	v_pk_mul_f32 v[26:27], v[18:19], v[26:27]
	v_pk_mul_f32 v[28:29], v[20:21], v[28:29]
	v_cvt_pk_bf16_f32 v18, v22, v23
	v_cvt_pk_bf16_f32 v19, v24, v25
	v_cvt_pk_bf16_f32 v20, v26, v27
	v_cvt_pk_bf16_f32 v21, v28, v29
	v_mad_i64_i32 v[22:23], s[24:25], v34, s64, v[140:141]
	global_store_dwordx4 v[22:23], v[18:21], off
	s_mov_b64 s[24:25], -1
	s_nop 0
	v_add_u32_e32 v18, 0xb0, v142
	s_cbranch_vccnz .LBB0_209
	s_cmp_eq_u32 s48, s12
	s_mov_b64 s[6:7], -1
	s_cbranch_scc1 .LBB0_206
	v_ashrrev_i32_e32 v19, 31, v18
	v_lshlrev_b64 v[20:21], 6, v[18:19]
	v_lshl_add_u64 v[32:33], s[38:39], 0, v[20:21]
	flat_load_dwordx4 v[20:23], v[32:33]
	flat_load_dwordx4 v[24:27], v[32:33] offset:16
	flat_load_dwordx4 v[28:31], v[32:33] offset:32
	s_nop 0
	flat_load_dwordx4 v[32:35], v[32:33] offset:48
	s_mov_b64 s[6:7], 0
	s_waitcnt vmcnt(0) lgkmcnt(0)
	v_mov_b32_e32 v36, v21
	v_mov_b32_e32 v37, v22
	v_mov_b32_e32 v21, v23
	v_mov_b32_e32 v22, v25
	v_mov_b32_e32 v23, v26
	v_mov_b32_e32 v25, v27
	v_pk_add_f32 v[20:21], v[36:37], v[20:21]
	v_pk_add_f32 v[22:23], v[22:23], v[24:25]
	v_pk_add_f32 v[20:21], v[20:21], v[20:21] op_sel:[0,1] op_sel_hi:[1,0]
	v_pk_add_f32 v[22:23], v[22:23], v[22:23] op_sel:[0,1] op_sel_hi:[1,0]
	v_add_f32_e32 v24, v28, v29
	v_add_f32_e32 v26, v30, v31
	v_mov_b32_e32 v21, v32
	v_mov_b32_e32 v23, v33
	v_mov_b32_e32 v25, v34
	v_mov_b32_e32 v27, v35
	v_pk_add_f32 v[20:21], v[20:21], v[22:23]
	v_pk_add_f32 v[22:23], v[24:25], v[26:27]
	s_nop 0
	v_pk_add_f32 v[20:21], v[20:21], v[22:23]
	s_nop 0
	v_add_f32_e32 v19, v20, v21
	v_fmamk_f32 v19, v19, 0x3a800000, v205
	v_cmp_gt_f32_e32 vcc, s77, v19
	v_mul_f32_e32 v20, 0x4b800000, v19
	s_nop 0
	v_cndmask_b32_e32 v19, v19, v20, vcc
	v_rsq_f32_e32 v19, v19
	s_nop 0
	v_mul_f32_e32 v20, 0x45800000, v19
	v_cndmask_b32_e32 v20, v19, v20, vcc

; __device__ __forceinline__ u32x4 pack8(f32x4 a, f32x4 b) { u32x4 w; w.x = pk2(a[0], a[1]); w.y = pk2(a[2], a[3]); w.z = pk2(b[0], b[1]); w.w = pk2(b[2], b[3]); return w; }
; __device__ __forceinline__ float fast_sigmoid(float x) { return __builtin_amdgcn_rcpf(1.0f + __builtin_amdgcn_exp2f(-x * LOG2E)); }
;     __device__ __forceinline__ void operator()(const Acc& acc, const Unit& u, int wr, int wc, int fr, int fq, const RsCtx& rc) const {
;     ...
;             for (int m = 0; m < 4; ++m) { const int row = EPI_ROW(u, ai, wr, m, fr); const float rs = rc.get(u.pm, ai * 128 + wr * 64 + m * 16 + fr, row);
;                 f32x4 a0 = acc[ai][0][m][0] * rs, a1 = acc[ai][0][m][1] * rs; const f32x4 b0 = acc[ai][1][m][0] * rs, b1 = acc[ai][1][m][1] * rs;
; #pragma unroll
;                 for (int e = 0; e < 4; ++e) { a0[e] = a0[e] * fast_sigmoid(a0[e]) * b0[e]; a1[e] = a1[e] * fast_sigmoid(a1[e]) * b1[e]; }
;                 *(u32x4*)(O + (size_t)row * FF + col) = pack8(a0, a1);
;                 if (m == 3) asm volatile("" ::: "memory"); }
.LBB0_211:
	s_waitcnt lgkmcnt(0)
	s_andn2_b64 vcc, exec, s[4:5]
	s_mov_b32 s100, 0xbfb8aa3b
	v_pk_mul_f32 v[14:15], v[14:15], v[20:21] op_sel_hi:[1,0]
	v_pk_mul_f32 v[16:17], v[16:17], v[20:21] op_sel_hi:[1,0]
	v_pk_mul_f32 v[10:11], v[10:11], v[20:21] op_sel_hi:[1,0]
	v_pk_mul_f32 v[12:13], v[12:13], v[20:21] op_sel_hi:[1,0]
	v_pk_mul_f32 v[22:23], v[14:15], s[100:101] op_sel_hi:[1,0]
	v_pk_mul_f32 v[24:25], v[16:17], s[100:101] op_sel_hi:[1,0]
	v_pk_mul_f32 v[26:27], v[10:11], s[100:101] op_sel_hi:[1,0]
	v_pk_mul_f32 v[28:29], v[12:13], s[100:101] op_sel_hi:[1,0]
	s_mov_b32 s100, 1.0
	v_exp_f32_e32 v22, v22
	v_exp_f32_e32 v23, v23
	v_exp_f32_e32 v24, v24
	v_exp_f32_e32 v25, v25
	v_exp_f32_e32 v26, v26
	v_exp_f32_e32 v27, v27
	v_exp_f32_e32 v28, v28
	v_exp_f32_e32 v29, v29
	v_pk_mul_f32 v[6:7], v[6:7], v[20:21] op_sel_hi:[1,0]
	v_pk_mul_f32 v[8:9], v[8:9], v[20:21] op_sel_hi:[1,0]
	v_pk_mul_f32 v[2:3], v[2:3], v[20:21] op_sel_hi:[1,0]
	v_pk_mul_f32 v[4:5], v[4:5], v[20:21] op_sel_hi:[1,0]
	v_pk_add_f32 v[22:23], v[22:23], s[100:101] op_sel_hi:[1,0]
	v_pk_add_f32 v[24:25], v[24:25], s[100:101] op_sel_hi:[1,0]
	v_pk_add_f32 v[26:27], v[26:27], s[100:101] op_sel_hi:[1,0]
	v_pk_add_f32 v[28:29], v[28:29], s[100:101] op_sel_hi:[1,0]
	v_rcp_f32_e32 v22, v22
	v_rcp_f32_e32 v23, v23
	v_rcp_f32_e32 v24, v24
	v_rcp_f32_e32 v25, v25
	v_rcp_f32_e32 v26, v26
	v_rcp_f32_e32 v27, v27
	v_rcp_f32_e32 v28, v28
	v_rcp_f32_e32 v29, v29
	v_pk_mul_f32 v[14:15], v[14:15], v[22:23]
	v_pk_mul_f32 v[16:17], v[16:17], v[24:25]
	v_pk_mul_f32 v[10:11], v[10:11], v[26:27]
	v_pk_mul_f32 v[12:13], v[12:13], v[28:29]
	v_pk_mul_f32 v[6:7], v[6:7], v[14:15]
	v_pk_mul_f32 v[8:9], v[8:9], v[16:17]
	v_pk_mul_f32 v[10:11], v[2:3], v[10:11]
	v_pk_mul_f32 v[12:13], v[4:5], v[12:13]
	v_cvt_pk_bf16_f32 v2, v6, v7
	v_cvt_pk_bf16_f32 v3, v8, v9
	v_cvt_pk_bf16_f32 v4, v10, v11
	v_cvt_pk_bf16_f32 v5, v12, v13
	v_mad_i64_i32 v[6:7], s[6:7], v18, s64, v[140:141]
	global_store_dwordx4 v[6:7], v[2:5], off
	s_mov_b64 s[6:7], -1
	s_cbranch_vccnz .LBB0_138
	s_andn2_b64 vcc, exec, s[8:9]
	s_cbranch_vccnz .LBB0_137
	s_barrier
	s_branch .LBB0_137

; __device__ __forceinline__ u32x4 pack8(f32x4 a, f32x4 b) { u32x4 w; w.x = pk2(a[0], a[1]); w.y = pk2(a[2], a[3]); w.z = pk2(b[0], b[1]); w.w = pk2(b[2], b[3]); return w; }
;     __device__ __forceinline__ void operator()(const Acc& acc, const Unit& u, int wr, int wc, int fr, int fq, const RsCtx& rc) const {
;     ...
;                 const float rs = rc.get(u.pm, ai * 128 + wr * 64 + m * 16 + fr, row);
;                 f32x4 a0 = acc[ai][0][m][0] * rs, a1 = acc[ai][0][m][1] * rs, b0 = acc[ai][1][m][0] * rs, b1 = acc[ai][1][m][1] * rs;
;                 if (pn == 0) {
;                     float s = 0.f;
; #pragma unroll
;                     for (int e = 0; e < 4; ++e) s += a0[e] * a0[e] + a1[e] * a1[e] + b0[e] * b0[e] + b1[e] * b1[e];
;                     s += __shfl_xor(s, 16); s += __shfl_xor(s, 32);
;                     if (fq == 0) ssq_q[row * 4 + wc] = s;
;                     *(u32x4*)(LAT + (size_t)row * 512 + cw) = pack8(a0, a1); *(u32x4*)(LAT + (size_t)row * 512 + 128 + cw) = pack8(b0, b1);
;                 } else if (pn == 1) {
;                     float s = 0.f;
; #pragma unroll
;                     for (int e = 0; e < 4; ++e) s += a0[e] * a0[e] + a1[e] * a1[e];
;                     s += __shfl_xor(s, 16); s += __shfl_xor(s, 32);
;                     if (fq == 0) ssq_kv[row * 4 + wc] = s;
;                     *(u32x4*)(LAT + (size_t)row * 512 + 256 + cw) = pack8(a0, a1);
;                     if (wc == 0) { rope8(b0, b1, TABM + ((size_t)tok_pos(row) * 16 + 4 * fq) * 2); *(u32x4*)(LAT + (size_t)row * 512 + 384 + cw) = pack8(b0, b1); }
.LBB0_559:
	s_cmp_gt_i32 s82, 3
	s_cselect_b64 s[4:5], -1, 0
	s_cmp_gt_u32 s82, 7
	s_mov_b32 s18, s26
	s_cselect_b64 s[26:27], -1, 0
	s_cmp_gt_u32 s82, 9
	s_waitcnt lgkmcnt(0)
	v_pk_mul_f32 v[128:129], v[128:129], v[0:1] op_sel_hi:[1,0]
	v_pk_mul_f32 v[126:127], v[126:127], v[0:1] op_sel_hi:[1,0]
	v_pk_mul_f32 v[124:125], v[124:125], v[0:1] op_sel_hi:[1,0]
	v_pk_mul_f32 v[156:157], v[122:123], v[0:1] op_sel_hi:[1,0]
	v_pk_mul_f32 v[122:123], v[120:121], v[0:1] op_sel_hi:[1,0]
	v_pk_mul_f32 v[152:153], v[118:119], v[0:1] op_sel_hi:[1,0]
	v_pk_mul_f32 v[154:155], v[116:117], v[0:1] op_sel_hi:[1,0]
	v_pk_mul_f32 v[158:159], v[114:115], v[0:1] op_sel_hi:[1,0]
	s_cselect_b64 s[16:17], -1, 0
	s_mov_b64 s[22:23], -1
	s_mov_b64 s[6:7], 0
	s_cmp_lt_i32 s82, 1
	s_mov_b64 s[24:25], 0
	s_cbranch_scc1 .LBB0_567
	s_cmp_eq_u32 s82, 1
	s_mov_b64 s[24:25], -1
	s_cbranch_scc0 .LBB0_566
	v_mul_f32_e32 v0, v156, v156
	v_mul_f32_e32 v114, v157, v157
	v_fmac_f32_e32 v0, v126, v126
	v_fmac_f32_e32 v114, v127, v127
	v_add_f32_e32 v0, v0, v114
	v_mul_f32_e32 v114, v124, v124
	v_fmac_f32_e32 v114, v128, v128
	v_add_f32_e32 v0, v114, v0
	v_mul_f32_e32 v114, v125, v125
	v_fmac_f32_e32 v114, v129, v129
	v_and_b32_e32 v115, 64, v217
	v_add_f32_e32 v0, v114, v0
	v_add_u32_e32 v115, 64, v115
	s_nop 1
	v_mov_b32_e32 v114, v0
	s_nop 1
	v_permlane16_swap_b32_e32 v114, v0
	s_waitcnt lgkmcnt(0)
	v_add_f32_e32 v0, v0, v114
	s_nop 1
	v_mov_b32_e32 v114, v0
	s_nop 1
	v_permlane32_swap_b32_e32 v114, v0
	s_and_saveexec_b64 s[22:23], s[42:43]
	s_cbranch_execz .LBB0_563
	s_waitcnt lgkmcnt(0)
	v_add_f32_e32 v0, v0, v114
	v_lshl_or_b32 v114, v150, 2, s76
	v_ashrrev_i32_e32 v115, 31, v114
	v_lshl_add_u64 v[114:115], v[114:115], 2, s[62:63]
	global_store_dword v[114:115], v0, off
.LBB0_563:
	s_or_b64 exec, exec, s[22:23]
	v_ashrrev_i32_e32 v151, 31, v150
	s_waitcnt lgkmcnt(0)
	v_lshlrev_b64 v[114:115], 10, v[150:151]
	v_cvt_pk_bf16_f32 v116, v126, v127
	v_cvt_pk_bf16_f32 v117, v128, v129
	v_cvt_pk_bf16_f32 v118, v156, v157
	v_cvt_pk_bf16_f32 v119, v124, v125
	v_lshl_add_u64 v[114:115], v[142:143], 0, v[114:115]
	s_andn2_b64 vcc, exec, s[48:49]
	global_store_dwordx4 v[114:115], v[116:119], off offset:512
	s_cbranch_vccnz .LBB0_565
	s_movk_i32 s12, 0x4000
	v_cmp_gt_i32_e32 vcc, s12, v150
	v_mov_b32_e32 v0, 0x1fcf
	v_mov_b32_e32 v116, 0xfcf
	v_cndmask_b32_e32 v0, v0, v116, vcc
	v_and_b32_e32 v0, v0, v150
	v_lshlrev_b32_e32 v116, 2, v176
	v_readlane_b32 s12, v254, 58
	v_lshl_or_b32 v0, v0, 7, v116
	v_readlane_b32 s13, v254, 59
	s_nop 1
	v_lshl_add_u64 v[120:121], s[12:13], 0, v[0:1]
	flat_load_dwordx4 v[116:119], v[120:121]
	flat_load_dwordx4 v[160:163], v[120:121] offset:16
	s_waitcnt vmcnt(0) lgkmcnt(0)
	v_pk_mul_f32 v[120:121], v[152:153], v[116:117] op_sel:[1,1] op_sel_hi:[0,1]
	v_mov_b32_e32 v0, v119
	v_pk_fma_f32 v[164:165], v[152:153], v[116:117], v[120:121] neg_lo:[0,0,1] neg_hi:[0,0,1]
	v_pk_fma_f32 v[116:117], v[152:153], v[116:117], v[120:121] op_sel_hi:[1,0,1]
	v_pk_mul_f32 v[120:121], v[122:123], v[0:1] op_sel:[1,0] op_sel_hi:[0,0]
	v_pk_fma_f32 v[166:167], v[122:123], v[118:119], v[120:121] neg_lo:[0,0,1] neg_hi:[0,0,1]
	v_pk_fma_f32 v[118:119], v[122:123], v[118:119], v[120:121] op_sel_hi:[1,0,1]
	v_pk_mul_f32 v[120:121], v[158:159], v[160:161] op_sel:[1,1] op_sel_hi:[0,1]
	v_mov_b32_e32 v0, v163
	v_pk_fma_f32 v[168:169], v[158:159], v[160:161], v[120:121] neg_lo:[0,0,1] neg_hi:[0,0,1]
	v_pk_fma_f32 v[120:121], v[158:159], v[160:161], v[120:121] op_sel_hi:[1,0,1]
	v_pk_mul_f32 v[160:161], v[154:155], v[0:1] op_sel:[1,0] op_sel_hi:[0,0]
	v_pk_fma_f32 v[170:171], v[154:155], v[162:163], v[160:161] neg_lo:[0,0,1] neg_hi:[0,0,1]
	v_pk_fma_f32 v[160:161], v[154:155], v[162:163], v[160:161] op_sel_hi:[1,0,1]
	v_cvt_pk_bf16_f32 v116, v164, v117
	v_cvt_pk_bf16_f32 v117, v166, v119
	v_cvt_pk_bf16_f32 v118, v168, v121
	v_cvt_pk_bf16_f32 v119, v170, v161
	global_store_dwordx4 v[114:115], v[116:119], off offset:768

; __device__ __forceinline__ u32x4 pack8(f32x4 a, f32x4 b) { u32x4 w; w.x = pk2(a[0], a[1]); w.y = pk2(a[2], a[3]); w.z = pk2(b[0], b[1]); w.w = pk2(b[2], b[3]); return w; }
;     __device__ __forceinline__ void operator()(const Acc& acc, const Unit& u, int wr, int wc, int fr, int fq, const RsCtx& rc) const {
;     ...
;                 } else if (pn < 10) {
;                     const int c = (pn - 8) * 256 + cw; const float* tb = TABS + (size_t)tok_pos(row) * 64;
;                     rope8(a0, a1, tb + (c & 63)); rope8(b0, b1, tb + ((c + 128) & 63));
;                     const float sc = 0.125f * LOG2E;
;                     *(u32x4*)(SWAQK + (size_t)row * 768 + c) = pack8(a0 * sc, a1 * sc); *(u32x4*)(SWAQK + (size_t)row * 768 + c + 128) = pack8(b0 * sc, b1 * sc);
;                 } else {
;                     rope8(a0, a1, TABS + (size_t)tok_pos(row) * 64 + (cw & 63));
;                     *(u32x4*)(SWAQK + (size_t)row * 768 + 512 + cw) = pack8(a0, a1);
;                 }
.LBB0_569:
	s_lshl_b32 s13, s82, 8
	v_or_b32_e32 v0, 0xfffff800, v138
	s_add_i32 s22, s13, 0xfffffe00
	v_add_u32_e32 v0, s13, v0
	s_lshl_b32 s12, s82, 7
	s_andn2_b64 vcc, exec, s[24:25]
	s_ashr_i32 s23, s22, 31
	s_cbranch_vccnz .LBB0_583
	s_mov_b64 s[6:7], -1
	s_and_b64 vcc, exec, s[4:5]
	s_cbranch_vccz .LBB0_580
	s_and_b64 vcc, exec, s[26:27]
	s_cbranch_vccz .LBB0_577
	s_movk_i32 s6, 0x4000
	v_cmp_gt_i32_e32 vcc, s6, v150
	v_mov_b32_e32 v114, 0x1fcf
	v_mov_b32_e32 v115, 0xfcf
	v_cndmask_b32_e32 v114, v114, v115, vcc
	v_and_b32_e32 v114, v114, v150
	v_lshlrev_b32_e32 v114, 8, v114
	v_mov_b32_e32 v115, v1
	v_lshl_add_u64 v[114:115], v[140:141], 0, v[114:115]
	flat_load_dwordx4 v[118:121], v[114:115]
	s_nop 0
	flat_load_dwordx4 v[114:117], v[114:115] offset:16
	s_mov_b64 s[6:7], -1
	s_and_b64 vcc, exec, s[16:17]
	s_waitcnt vmcnt(0) lgkmcnt(0)
	v_mov_b32_e32 v162, v121
	v_mov_b32_e32 v170, v117
	v_pk_mul_f32 v[160:161], v[126:127], v[118:119] op_sel:[0,1]
	v_pk_mul_f32 v[168:169], v[156:157], v[114:115] op_sel:[0,1]
	v_pk_mul_f32 v[174:175], v[128:129], v[162:163] op_sel_hi:[1,0]
	v_pk_mul_f32 v[170:171], v[124:125], v[170:171] op_sel_hi:[1,0]
	v_pk_fma_f32 v[164:165], v[126:127], v[118:119], v[160:161] op_sel:[0,0,1] op_sel_hi:[1,0,0] neg_lo:[0,0,1] neg_hi:[0,0,1]
	v_pk_fma_f32 v[166:167], v[126:127], v[118:119], v[160:161] op_sel:[0,0,1] op_sel_hi:[1,0,0]
	v_pk_fma_f32 v[160:161], v[156:157], v[114:115], v[168:169] op_sel:[0,0,1] op_sel_hi:[1,0,0] neg_lo:[0,0,1] neg_hi:[0,0,1]
	v_pk_fma_f32 v[162:163], v[156:157], v[114:115], v[168:169] op_sel:[0,0,1] op_sel_hi:[1,0,0]
	v_pk_fma_f32 v[172:173], v[128:129], v[120:121], v[174:175] op_sel:[0,0,1] op_sel_hi:[1,0,0] neg_lo:[0,0,1] neg_hi:[0,0,1]
	v_pk_fma_f32 v[174:175], v[128:129], v[120:121], v[174:175] op_sel:[0,0,1] op_sel_hi:[1,0,0]
	v_pk_fma_f32 v[168:169], v[124:125], v[116:117], v[170:171] op_sel:[0,0,1] op_sel_hi:[1,0,0] neg_lo:[0,0,1] neg_hi:[0,0,1]
	v_pk_fma_f32 v[170:171], v[124:125], v[116:117], v[170:171] op_sel:[0,0,1] op_sel_hi:[1,0,0]
	s_cbranch_vccz .LBB0_574
	s_movk_i32 s6, 0x600
	v_cvt_pk_bf16_f32 v180, v164, v167
	v_cvt_pk_bf16_f32 v181, v172, v175
	v_cvt_pk_bf16_f32 v182, v160, v163
	v_cvt_pk_bf16_f32 v183, v168, v171
	v_mad_i64_i32 v[184:185], s[6:7], v150, s6, v[144:145]
	global_store_dwordx4 v[184:185], v[180:183], off offset:1024
	s_mov_b64 s[6:7], 0
.LBB0_574:
	s_andn2_b64 vcc, exec, s[6:7]
	s_cbranch_vccnz .LBB0_576
	v_mov_b32_e32 v180, v118
	v_mov_b32_e32 v181, v118
	v_mov_b32_e32 v118, v119
	v_mov_b32_e32 v182, v120
	v_mov_b32_e32 v183, v120
	v_mov_b32_e32 v120, v121
	v_mov_b32_e32 v184, v114
	v_mov_b32_e32 v185, v114
	v_mov_b32_e32 v114, v115
	v_mov_b32_e32 v186, v116
	v_mov_b32_e32 v187, v116
	v_mov_b32_e32 v116, v117
	v_pk_mul_f32 v[118:119], v[152:153], v[118:119]
	v_pk_mul_f32 v[120:121], v[122:123], v[120:121]
	v_pk_mul_f32 v[114:115], v[158:159], v[114:115]
	v_pk_fma_f32 v[188:189], v[152:153], v[180:181], v[118:119] op_sel:[0,0,1] op_sel_hi:[1,1,0] neg_lo:[0,0,1] neg_hi:[0,0,1]
	v_pk_fma_f32 v[118:119], v[152:153], v[180:181], v[118:119] op_sel:[0,0,1] op_sel_hi:[1,1,0]
	v_pk_fma_f32 v[180:181], v[122:123], v[182:183], v[120:121] op_sel:[0,0,1] op_sel_hi:[1,1,0] neg_lo:[0,0,1] neg_hi:[0,0,1]
	v_pk_fma_f32 v[120:121], v[122:123], v[182:183], v[120:121] op_sel:[0,0,1] op_sel_hi:[1,1,0]
	v_pk_fma_f32 v[182:183], v[158:159], v[184:185], v[114:115] op_sel:[0,0,1] op_sel_hi:[1,1,0] neg_lo:[0,0,1] neg_hi:[0,0,1]
	v_pk_fma_f32 v[184:185], v[158:159], v[184:185], v[114:115] op_sel:[0,0,1] op_sel_hi:[1,1,0]
	v_pk_mul_f32 v[114:115], v[154:155], v[116:117]
	v_mov_b32_e32 v173, v175
	s_mov_b32 s14, 0x3e38aa3b
	v_mov_b32_e32 v165, v167
	v_mov_b32_e32 v161, v163
	v_readlane_b32 s6, v255, 4
	v_pk_fma_f32 v[190:191], v[154:155], v[186:187], v[114:115] op_sel:[0,0,1] op_sel_hi:[1,1,0] neg_lo:[0,0,1] neg_hi:[0,0,1]
	v_pk_fma_f32 v[186:187], v[154:155], v[186:187], v[114:115] op_sel:[0,0,1] op_sel_hi:[1,1,0]
	v_pk_mul_f32 v[116:117], v[172:173], s[14:15] op_sel_hi:[1,0]
	v_pk_mul_f32 v[114:115], v[164:165], s[14:15] op_sel_hi:[1,0]
	v_pk_mul_f32 v[160:161], v[160:161], s[14:15] op_sel_hi:[1,0]
	v_readlane_b32 s7, v255, 5
	v_mov_b32_e32 v169, v171
	v_cvt_pk_bf16_f32 v114, v114, v115
	v_cvt_pk_bf16_f32 v115, v116, v117
	v_cvt_pk_bf16_f32 v116, v160, v161
	v_mov_b64_e32 v[160:161], s[6:7]
	s_movk_i32 s6, 0x600
	v_pk_mul_f32 v[164:165], v[168:169], s[14:15] op_sel_hi:[1,0]
	v_mad_i64_i32 v[160:161], s[6:7], v150, s6, v[160:161]
	v_cvt_pk_bf16_f32 v117, v164, v165
	v_lshl_add_u64 v[160:161], v[0:1], 1, v[160:161]
	v_mov_b32_e32 v181, v121
	v_mov_b32_e32 v189, v119
	v_mov_b32_e32 v191, v187
	v_mov_b32_e32 v183, v185
	global_store_dwordx4 v[160:161], v[114:117], off
	v_pk_mul_f32 v[118:119], v[190:191], s[14:15] op_sel_hi:[1,0]
	v_pk_mul_f32 v[120:121], v[182:183], s[14:15] op_sel_hi:[1,0]
	v_pk_mul_f32 v[116:117], v[180:181], s[14:15] op_sel_hi:[1,0]
	v_pk_mul_f32 v[114:115], v[188:189], s[14:15] op_sel_hi:[1,0]
	s_nop 0
	v_cvt_pk_bf16_f32 v114, v114, v115
	v_cvt_pk_bf16_f32 v115, v116, v117
	v_cvt_pk_bf16_f32 v116, v120, v121
	v_cvt_pk_bf16_f32 v117, v118, v119
	global_store_dwordx4 v[160:161], v[114:117], off offset:256

; __device__ __forceinline__ u32x4 pack8(f32x4 a, f32x4 b) { u32x4 w; w.x = pk2(a[0], a[1]); w.y = pk2(a[2], a[3]); w.z = pk2(b[0], b[1]); w.w = pk2(b[2], b[3]); return w; }
;     __device__ __forceinline__ void operator()(const Acc& acc, const Unit& u, int wr, int wc, int fr, int fq, const RsCtx& rc) const {
;     ...
;                 } else if (pn < 8) {
;                     *(u32x4*)(CONVZ + (size_t)row * 512 + (pn - 4) * 128 + cw) = pack8(a0 * b0, a1 * b1);
.LBB0_577:
	s_andn2_b64 vcc, exec, s[6:7]
	s_cbranch_vccnz .LBB0_579
	v_pk_mul_f32 v[116:117], v[128:129], v[122:123]
	v_pk_mul_f32 v[114:115], v[126:127], v[152:153]
	v_pk_mul_f32 v[118:119], v[124:125], v[154:155]
	v_ashrrev_i32_e32 v151, 31, v150
	v_readlane_b32 s6, v255, 2
	v_cvt_pk_bf16_f32 v114, v114, v115
	v_cvt_pk_bf16_f32 v115, v116, v117
	v_cvt_pk_bf16_f32 v117, v118, v119
	v_lshlrev_b64 v[118:119], 10, v[150:151]
	v_readlane_b32 s7, v255, 3
	v_pk_mul_f32 v[120:121], v[156:157], v[158:159]
	s_lshl_b32 s92, s12, 1
	v_lshl_add_u64 v[118:119], s[6:7], 0, v[118:119]
	v_cvt_pk_bf16_f32 v116, v120, v121
	v_lshl_add_u64 v[118:119], v[118:119], 0, s[92:93]
	v_lshlrev_b32_e32 v120, 1, v138
	v_mov_b32_e32 v121, v1
	v_lshl_add_u64 v[118:119], v[118:119], 0, v[120:121]
	v_add_co_u32_e32 v118, vcc, 0xfffffc00, v118
	s_nop 1
	v_addc_co_u32_e32 v119, vcc, -1, v119, vcc
	global_store_dwordx4 v[118:119], v[114:117], off

; __device__ __forceinline__ u32x4 pack8(f32x4 a, f32x4 b) { u32x4 w; w.x = pk2(a[0], a[1]); w.y = pk2(a[2], a[3]); w.z = pk2(b[0], b[1]); w.w = pk2(b[2], b[3]); return w; }
;     __device__ __forceinline__ void operator()(const Acc& acc, const Unit& u, int wr, int wc, int fr, int fq, const RsCtx& rc) const {
;     ...
;                 } else if (pn < 4) {
;                     bf16_t* p = CONVB + (size_t)row * 512 + (pn - 2) * 256 + cw;
;                     *(u32x4*)p = pack8(a0, a1); *(u32x4*)(p + 128) = pack8(b0, b1);
.LBB0_580:
	s_andn2_b64 vcc, exec, s[6:7]
	s_cbranch_vccnz .LBB0_582
	v_ashrrev_i32_e32 v151, 31, v150
	v_lshlrev_b64 v[114:115], 10, v[150:151]
	v_lshl_add_u64 v[114:115], s[54:55], 0, v[114:115]
	v_lshl_add_u64 v[114:115], s[22:23], 1, v[114:115]
	v_lshlrev_b32_e32 v116, 1, v138
	v_mov_b32_e32 v117, v1
	v_lshl_add_u64 v[118:119], v[114:115], 0, v[116:117]
	v_cvt_pk_bf16_f32 v114, v126, v127
	v_cvt_pk_bf16_f32 v115, v128, v129
	v_cvt_pk_bf16_f32 v116, v156, v157
	v_cvt_pk_bf16_f32 v117, v124, v125
	global_store_dwordx4 v[118:119], v[114:117], off
	s_nop 1
	v_cvt_pk_bf16_f32 v114, v152, v153
	v_cvt_pk_bf16_f32 v115, v122, v123
	v_cvt_pk_bf16_f32 v116, v158, v159
	v_cvt_pk_bf16_f32 v117, v154, v155
	global_store_dwordx4 v[118:119], v[114:117], off offset:256

; __device__ __forceinline__ u32x4 pack8(f32x4 a, f32x4 b) { u32x4 w; w.x = pk2(a[0], a[1]); w.y = pk2(a[2], a[3]); w.z = pk2(b[0], b[1]); w.w = pk2(b[2], b[3]); return w; }
;     __device__ __forceinline__ void operator()(const Acc& acc, const Unit& u, int wr, int wc, int fr, int fq, const RsCtx& rc) const {
;     ...
;                 if (pn == 0) {
;                     float s = 0.f;
; #pragma unroll
;                     for (int e = 0; e < 4; ++e) s += a0[e] * a0[e] + a1[e] * a1[e] + b0[e] * b0[e] + b1[e] * b1[e];
;                     s += __shfl_xor(s, 16); s += __shfl_xor(s, 32);
;                     if (fq == 0) ssq_q[row * 4 + wc] = s;
;                     *(u32x4*)(LAT + (size_t)row * 512 + cw) = pack8(a0, a1); *(u32x4*)(LAT + (size_t)row * 512 + 128 + cw) = pack8(b0, b1);
.LBB0_583:
	s_andn2_b64 vcc, exec, s[6:7]
	s_cbranch_vccnz .LBB0_587
	v_mul_f32_e32 v114, v156, v156
	v_mul_f32_e32 v115, v157, v157
	v_fmac_f32_e32 v114, v126, v126
	v_fmac_f32_e32 v115, v127, v127
	v_fmac_f32_e32 v114, v152, v152
	v_fmac_f32_e32 v115, v153, v153
	v_fmac_f32_e32 v114, v158, v158
	v_fmac_f32_e32 v115, v159, v159
	v_add_f32_e32 v114, v114, v115
	v_mul_f32_e32 v115, v124, v124
	v_fmac_f32_e32 v115, v128, v128
	v_fmac_f32_e32 v115, v122, v122
	v_fmac_f32_e32 v115, v154, v154
	v_add_f32_e32 v114, v115, v114
	v_mul_f32_e32 v115, v125, v125
	v_fmac_f32_e32 v115, v129, v129
	v_fmac_f32_e32 v115, v123, v123
	v_fmac_f32_e32 v115, v155, v155
	v_and_b32_e32 v116, 64, v217
	v_add_f32_e32 v114, v115, v114
	v_add_u32_e32 v116, 64, v116
	s_nop 1
	v_mov_b32_e32 v115, v114
	s_nop 1
	v_permlane16_swap_b32_e32 v115, v114
	s_waitcnt lgkmcnt(0)
	v_add_f32_e32 v114, v114, v115
	s_nop 1
	v_mov_b32_e32 v115, v114
	s_nop 1
	v_permlane32_swap_b32_e32 v115, v114
	s_and_saveexec_b64 s[6:7], s[42:43]
	s_cbranch_execz .LBB0_586
	s_waitcnt lgkmcnt(0)
	v_add_f32_e32 v116, v114, v115
	v_lshl_or_b32 v114, v150, 2, s76
	v_readlane_b32 s36, v254, 54
	v_ashrrev_i32_e32 v115, 31, v114
	v_readlane_b32 s37, v254, 55
	v_readlane_b32 s38, v254, 56
	v_readlane_b32 s39, v254, 57
	v_readlane_b32 s36, v254, 44
	v_readlane_b32 s37, v254, 45
	v_lshl_add_u64 v[114:115], v[114:115], 2, s[38:39]
	v_readlane_b32 s38, v254, 48
	v_readlane_b32 s39, v254, 49
	global_store_dword v[114:115], v116, off
.LBB0_586:
	s_or_b64 exec, exec, s[6:7]
	v_ashrrev_i32_e32 v151, 31, v150
	v_lshlrev_b64 v[118:119], 10, v[150:151]
	v_cvt_pk_bf16_f32 v114, v126, v127
	s_waitcnt lgkmcnt(0)
	v_cvt_pk_bf16_f32 v115, v128, v129
	v_cvt_pk_bf16_f32 v116, v156, v157
	v_cvt_pk_bf16_f32 v117, v124, v125
	v_lshl_add_u64 v[118:119], v[142:143], 0, v[118:119]
	global_store_dwordx4 v[118:119], v[114:117], off
	s_nop 1
	v_cvt_pk_bf16_f32 v114, v152, v153
	v_cvt_pk_bf16_f32 v115, v122, v123
	v_cvt_pk_bf16_f32 v116, v158, v159
	v_cvt_pk_bf16_f32 v117, v154, v155
	global_store_dwordx4 v[118:119], v[114:117], off offset:256

; __device__ __forceinline__ u32x4 pack8(f32x4 a, f32x4 b) { u32x4 w; w.x = pk2(a[0], a[1]); w.y = pk2(a[2], a[3]); w.z = pk2(b[0], b[1]); w.w = pk2(b[2], b[3]); return w; }
;     __device__ __forceinline__ void operator()(const Acc& acc, const Unit& u, int wr, int wc, int fr, int fq, const RsCtx& rc) const {
;     ...
;             for (int m = 0; m < 4; ++m) { const int row = EPI_ROW(u, ai, wr, m, fr);
;                 const float rs = rc.get(u.pm, ai * 128 + wr * 64 + m * 16 + fr, row);
;                 f32x4 a0 = acc[ai][0][m][0] * rs, a1 = acc[ai][0][m][1] * rs, b0 = acc[ai][1][m][0] * rs, b1 = acc[ai][1][m][1] * rs;
;                 if (pn == 0) {
;                     float s = 0.f;
; #pragma unroll
;                     for (int e = 0; e < 4; ++e) s += a0[e] * a0[e] + a1[e] * a1[e] + b0[e] * b0[e] + b1[e] * b1[e];
;                     s += __shfl_xor(s, 16); s += __shfl_xor(s, 32);
;                     if (fq == 0) ssq_q[row * 4 + wc] = s;
;                     *(u32x4*)(LAT + (size_t)row * 512 + cw) = pack8(a0, a1); *(u32x4*)(LAT + (size_t)row * 512 + 128 + cw) = pack8(b0, b1);
;                 } else if (pn == 1) {
;                     float s = 0.f;
; #pragma unroll
;                     for (int e = 0; e < 4; ++e) s += a0[e] * a0[e] + a1[e] * a1[e];
;                     s += __shfl_xor(s, 16); s += __shfl_xor(s, 32);
;                     if (fq == 0) ssq_kv[row * 4 + wc] = s;
;                     *(u32x4*)(LAT + (size_t)row * 512 + 256 + cw) = pack8(a0, a1);
;                     if (wc == 0) { rope8(b0, b1, TABM + ((size_t)tok_pos(row) * 16 + 4 * fq) * 2); *(u32x4*)(LAT + (size_t)row * 512 + 384 + cw) = pack8(b0, b1); }
.LBB0_595:
	s_waitcnt lgkmcnt(0)
	v_pk_mul_f32 v[112:113], v[112:113], v[122:123] op_sel_hi:[1,0]
	v_pk_mul_f32 v[110:111], v[110:111], v[122:123] op_sel_hi:[1,0]
	v_pk_mul_f32 v[108:109], v[108:109], v[122:123] op_sel_hi:[1,0]
	v_pk_mul_f32 v[120:121], v[106:107], v[122:123] op_sel_hi:[1,0]
	v_pk_mul_f32 v[106:107], v[104:105], v[122:123] op_sel_hi:[1,0]
	v_pk_mul_f32 v[116:117], v[102:103], v[122:123] op_sel_hi:[1,0]
	v_pk_mul_f32 v[118:119], v[100:101], v[122:123] op_sel_hi:[1,0]
	v_pk_mul_f32 v[122:123], v[98:99], v[122:123] op_sel_hi:[1,0]
	s_mov_b64 s[28:29], -1
	s_mov_b64 s[20:21], 0
	s_cmp_lt_i32 s82, 1
	s_mov_b64 s[24:25], 0
	s_cbranch_scc1 .LBB0_623
	s_cmp_eq_u32 s82, 1
	s_mov_b64 s[24:25], -1
	s_cbranch_scc0 .LBB0_602
	v_mul_f32_e32 v98, v120, v120
	v_mul_f32_e32 v99, v121, v121
	v_fmac_f32_e32 v98, v110, v110
	v_fmac_f32_e32 v99, v111, v111
	v_add_f32_e32 v98, v98, v99
	v_mul_f32_e32 v99, v108, v108
	v_fmac_f32_e32 v99, v112, v112
	v_add_f32_e32 v98, v99, v98
	v_mul_f32_e32 v99, v109, v109
	v_fmac_f32_e32 v99, v113, v113
	v_and_b32_e32 v100, 64, v217
	v_add_f32_e32 v98, v99, v98
	v_add_u32_e32 v100, 64, v100
	s_nop 1
	v_mov_b32_e32 v99, v98
	s_nop 1
	v_permlane16_swap_b32_e32 v99, v98
	s_waitcnt lgkmcnt(0)
	v_add_f32_e32 v98, v98, v99
	s_nop 1
	v_mov_b32_e32 v99, v98
	s_nop 1
	v_permlane32_swap_b32_e32 v99, v98
	s_and_saveexec_b64 s[24:25], s[42:43]
	s_cbranch_execz .LBB0_599
	s_waitcnt lgkmcnt(0)
	v_add_f32_e32 v100, v98, v99
	v_lshl_or_b32 v98, v114, 2, s76
	v_ashrrev_i32_e32 v99, 31, v98
	v_lshl_add_u64 v[98:99], v[98:99], 2, s[62:63]
	global_store_dword v[98:99], v100, off
.LBB0_599:
	s_or_b64 exec, exec, s[24:25]
	v_ashrrev_i32_e32 v115, 31, v114
	s_waitcnt lgkmcnt(0)
	v_lshlrev_b64 v[98:99], 10, v[114:115]
	v_cvt_pk_bf16_f32 v100, v110, v111
	v_cvt_pk_bf16_f32 v101, v112, v113
	v_cvt_pk_bf16_f32 v102, v120, v121
	v_cvt_pk_bf16_f32 v103, v108, v109
	v_lshl_add_u64 v[98:99], v[142:143], 0, v[98:99]
	s_andn2_b64 vcc, exec, s[48:49]
	global_store_dwordx4 v[98:99], v[100:103], off offset:512
	s_cbranch_vccnz .LBB0_601
	s_movk_i32 s13, 0x4000
	v_cmp_gt_i32_e32 vcc, s13, v114
	v_mov_b32_e32 v100, 0x1fdf
	v_mov_b32_e32 v101, 0xfdf
	v_cndmask_b32_e32 v100, v100, v101, vcc
	v_and_b32_e32 v100, v100, v114
	v_lshlrev_b32_e32 v101, 2, v176
	v_readlane_b32 s14, v254, 58
	v_lshl_or_b32 v100, v100, 7, v101
	v_mov_b32_e32 v101, v1
	v_readlane_b32 s15, v254, 59
	s_nop 1
	v_lshl_add_u64 v[104:105], s[14:15], 0, v[100:101]
	flat_load_dwordx4 v[100:103], v[104:105]
	flat_load_dwordx4 v[124:127], v[104:105] offset:16
	s_waitcnt vmcnt(0) lgkmcnt(0)
	v_pk_mul_f32 v[104:105], v[116:117], v[100:101] op_sel:[1,1] op_sel_hi:[0,1]
	v_pk_fma_f32 v[128:129], v[116:117], v[100:101], v[104:105] neg_lo:[0,0,1] neg_hi:[0,0,1]
	v_pk_fma_f32 v[100:101], v[116:117], v[100:101], v[104:105] op_sel_hi:[1,0,1]
	s_nop 0
	v_mov_b32_e32 v100, v103
	v_pk_mul_f32 v[104:105], v[106:107], v[100:101] op_sel:[1,0] op_sel_hi:[0,0]
	v_pk_fma_f32 v[152:153], v[106:107], v[102:103], v[104:105] neg_lo:[0,0,1] neg_hi:[0,0,1]
	v_pk_fma_f32 v[102:103], v[106:107], v[102:103], v[104:105] op_sel_hi:[1,0,1]
	v_pk_mul_f32 v[104:105], v[122:123], v[124:125] op_sel:[1,1] op_sel_hi:[0,1]
	v_mov_b32_e32 v100, v127
	v_pk_fma_f32 v[154:155], v[122:123], v[124:125], v[104:105] neg_lo:[0,0,1] neg_hi:[0,0,1]
	v_pk_fma_f32 v[104:105], v[122:123], v[124:125], v[104:105] op_sel_hi:[1,0,1]
	v_pk_mul_f32 v[124:125], v[118:119], v[100:101] op_sel:[1,0] op_sel_hi:[0,0]
	v_pk_fma_f32 v[156:157], v[118:119], v[126:127], v[124:125] neg_lo:[0,0,1] neg_hi:[0,0,1]
	v_pk_fma_f32 v[124:125], v[118:119], v[126:127], v[124:125] op_sel_hi:[1,0,1]
	v_cvt_pk_bf16_f32 v100, v128, v101
	v_cvt_pk_bf16_f32 v101, v152, v103
	v_cvt_pk_bf16_f32 v102, v154, v105
	v_cvt_pk_bf16_f32 v103, v156, v125
	global_store_dwordx4 v[98:99], v[100:103], off offset:768

; __device__ __forceinline__ u32x4 pack8(f32x4 a, f32x4 b) { u32x4 w; w.x = pk2(a[0], a[1]); w.y = pk2(a[2], a[3]); w.z = pk2(b[0], b[1]); w.w = pk2(b[2], b[3]); return w; }
;     __device__ __forceinline__ void operator()(const Acc& acc, const Unit& u, int wr, int wc, int fr, int fq, const RsCtx& rc) const {
;     ...
;                 } else if (pn < 10) {
;                     const int c = (pn - 8) * 256 + cw; const float* tb = TABS + (size_t)tok_pos(row) * 64;
;                     rope8(a0, a1, tb + (c & 63)); rope8(b0, b1, tb + ((c + 128) & 63));
;                     const float sc = 0.125f * LOG2E;
;                     *(u32x4*)(SWAQK + (size_t)row * 768 + c) = pack8(a0 * sc, a1 * sc); *(u32x4*)(SWAQK + (size_t)row * 768 + c + 128) = pack8(b0 * sc, b1 * sc);
;                 } else {
;                     rope8(a0, a1, TABS + (size_t)tok_pos(row) * 64 + (cw & 63));
;                     *(u32x4*)(SWAQK + (size_t)row * 768 + 512 + cw) = pack8(a0, a1);
;                 }
.LBB0_604:
	s_and_b64 vcc, exec, s[4:5]
	s_mov_b64 s[20:21], -1
	s_cbranch_vccnz .LBB0_614
	s_andn2_b64 vcc, exec, s[26:27]
	s_cbranch_vccnz .LBB0_611
	s_movk_i32 s13, 0x4000
	v_cmp_gt_i32_e32 vcc, s13, v114
	v_mov_b32_e32 v98, 0x1fdf
	v_mov_b32_e32 v99, 0xfdf
	v_cndmask_b32_e32 v98, v98, v99, vcc
	v_and_b32_e32 v98, v98, v114
	v_lshlrev_b32_e32 v98, 8, v98
	v_mov_b32_e32 v99, v1
	v_lshl_add_u64 v[98:99], v[140:141], 0, v[98:99]
	flat_load_dwordx4 v[102:105], v[98:99]
	s_nop 0
	flat_load_dwordx4 v[98:101], v[98:99] offset:16
	s_andn2_b64 vcc, exec, s[16:17]
	s_waitcnt vmcnt(0) lgkmcnt(0)
	v_mov_b32_e32 v126, v105
	v_mov_b32_e32 v156, v101
	v_pk_mul_f32 v[124:125], v[110:111], v[102:103] op_sel:[0,1]
	v_pk_mul_f32 v[154:155], v[120:121], v[98:99] op_sel:[0,1]
	v_pk_mul_f32 v[160:161], v[112:113], v[126:127] op_sel_hi:[1,0]
	v_pk_mul_f32 v[156:157], v[108:109], v[156:157] op_sel_hi:[1,0]
	v_pk_fma_f32 v[128:129], v[110:111], v[102:103], v[124:125] op_sel:[0,0,1] op_sel_hi:[1,0,0] neg_lo:[0,0,1] neg_hi:[0,0,1]
	v_pk_fma_f32 v[152:153], v[110:111], v[102:103], v[124:125] op_sel:[0,0,1] op_sel_hi:[1,0,0]
	v_pk_fma_f32 v[124:125], v[120:121], v[98:99], v[154:155] op_sel:[0,0,1] op_sel_hi:[1,0,0] neg_lo:[0,0,1] neg_hi:[0,0,1]
	v_pk_fma_f32 v[126:127], v[120:121], v[98:99], v[154:155] op_sel:[0,0,1] op_sel_hi:[1,0,0]
	v_pk_fma_f32 v[158:159], v[112:113], v[104:105], v[160:161] op_sel:[0,0,1] op_sel_hi:[1,0,0] neg_lo:[0,0,1] neg_hi:[0,0,1]
	v_pk_fma_f32 v[160:161], v[112:113], v[104:105], v[160:161] op_sel:[0,0,1] op_sel_hi:[1,0,0]
	v_pk_fma_f32 v[154:155], v[108:109], v[100:101], v[156:157] op_sel:[0,0,1] op_sel_hi:[1,0,0] neg_lo:[0,0,1] neg_hi:[0,0,1]
	v_pk_fma_f32 v[156:157], v[108:109], v[100:101], v[156:157] op_sel:[0,0,1] op_sel_hi:[1,0,0]
	s_cbranch_vccnz .LBB0_608
	s_movk_i32 s13, 0x600
	v_cvt_pk_bf16_f32 v162, v128, v153
	v_cvt_pk_bf16_f32 v163, v158, v161
	v_cvt_pk_bf16_f32 v164, v124, v127
	v_cvt_pk_bf16_f32 v165, v154, v157
	v_mad_i64_i32 v[166:167], s[14:15], v114, s13, v[144:145]
	s_mov_b64 s[20:21], 0
	global_store_dwordx4 v[166:167], v[162:165], off offset:1024
.LBB0_608:
	s_andn2_b64 vcc, exec, s[20:21]
	s_cbranch_vccnz .LBB0_610
	v_mov_b32_e32 v162, v102
	v_mov_b32_e32 v163, v102
	v_mov_b32_e32 v102, v103
	v_mov_b32_e32 v164, v104
	v_mov_b32_e32 v165, v104
	v_mov_b32_e32 v104, v105
	v_mov_b32_e32 v166, v98
	v_mov_b32_e32 v167, v98
	v_mov_b32_e32 v98, v99
	v_mov_b32_e32 v168, v100
	v_mov_b32_e32 v169, v100
	v_mov_b32_e32 v100, v101
	v_pk_mul_f32 v[102:103], v[116:117], v[102:103]
	v_pk_mul_f32 v[104:105], v[106:107], v[104:105]
	v_pk_mul_f32 v[98:99], v[122:123], v[98:99]
	v_pk_fma_f32 v[170:171], v[116:117], v[162:163], v[102:103] op_sel:[0,0,1] op_sel_hi:[1,1,0] neg_lo:[0,0,1] neg_hi:[0,0,1]
	v_pk_fma_f32 v[102:103], v[116:117], v[162:163], v[102:103] op_sel:[0,0,1] op_sel_hi:[1,1,0]
	v_pk_fma_f32 v[162:163], v[106:107], v[164:165], v[104:105] op_sel:[0,0,1] op_sel_hi:[1,1,0] neg_lo:[0,0,1] neg_hi:[0,0,1]
	v_pk_fma_f32 v[104:105], v[106:107], v[164:165], v[104:105] op_sel:[0,0,1] op_sel_hi:[1,1,0]
	v_pk_fma_f32 v[164:165], v[122:123], v[166:167], v[98:99] op_sel:[0,0,1] op_sel_hi:[1,1,0] neg_lo:[0,0,1] neg_hi:[0,0,1]
	v_pk_fma_f32 v[166:167], v[122:123], v[166:167], v[98:99] op_sel:[0,0,1] op_sel_hi:[1,1,0]
	v_pk_mul_f32 v[98:99], v[118:119], v[100:101]
	v_mov_b32_e32 v159, v161
	s_mov_b32 s20, 0x3e38aa3b
	v_mov_b32_e32 v129, v153
	v_mov_b32_e32 v125, v127
	v_readlane_b32 s14, v255, 4
	v_pk_fma_f32 v[172:173], v[118:119], v[168:169], v[98:99] op_sel:[0,0,1] op_sel_hi:[1,1,0] neg_lo:[0,0,1] neg_hi:[0,0,1]
	v_pk_fma_f32 v[168:169], v[118:119], v[168:169], v[98:99] op_sel:[0,0,1] op_sel_hi:[1,1,0]
	v_pk_mul_f32 v[100:101], v[158:159], s[20:21] op_sel_hi:[1,0]
	v_pk_mul_f32 v[98:99], v[128:129], s[20:21] op_sel_hi:[1,0]
	v_pk_mul_f32 v[124:125], v[124:125], s[20:21] op_sel_hi:[1,0]
	v_readlane_b32 s15, v255, 5
	v_mov_b32_e32 v155, v157
	v_cvt_pk_bf16_f32 v98, v98, v99
	v_cvt_pk_bf16_f32 v99, v100, v101
	v_cvt_pk_bf16_f32 v100, v124, v125
	v_mov_b64_e32 v[124:125], s[14:15]
	s_movk_i32 s13, 0x600
	v_pk_mul_f32 v[128:129], v[154:155], s[20:21] op_sel_hi:[1,0]
	v_mad_i64_i32 v[124:125], s[14:15], v114, s13, v[124:125]
	v_cvt_pk_bf16_f32 v101, v128, v129
	v_lshl_add_u64 v[124:125], v[0:1], 1, v[124:125]
	v_mov_b32_e32 v163, v105
	v_mov_b32_e32 v171, v103
	v_mov_b32_e32 v173, v169
	v_mov_b32_e32 v165, v167
	global_store_dwordx4 v[124:125], v[98:101], off
	v_pk_mul_f32 v[102:103], v[172:173], s[20:21] op_sel_hi:[1,0]
	v_pk_mul_f32 v[104:105], v[164:165], s[20:21] op_sel_hi:[1,0]
	v_pk_mul_f32 v[100:101], v[162:163], s[20:21] op_sel_hi:[1,0]
	v_pk_mul_f32 v[98:99], v[170:171], s[20:21] op_sel_hi:[1,0]
	s_nop 0
	v_cvt_pk_bf16_f32 v98, v98, v99
	v_cvt_pk_bf16_f32 v99, v100, v101
	v_cvt_pk_bf16_f32 v100, v104, v105
	v_cvt_pk_bf16_f32 v101, v102, v103
	global_store_dwordx4 v[124:125], v[98:101], off offset:256

; __device__ __forceinline__ u32x4 pack8(f32x4 a, f32x4 b) { u32x4 w; w.x = pk2(a[0], a[1]); w.y = pk2(a[2], a[3]); w.z = pk2(b[0], b[1]); w.w = pk2(b[2], b[3]); return w; }
;     __device__ __forceinline__ void operator()(const Acc& acc, const Unit& u, int wr, int wc, int fr, int fq, const RsCtx& rc) const {
;     ...
;                 } else if (pn < 8) {
;                     *(u32x4*)(CONVZ + (size_t)row * 512 + (pn - 4) * 128 + cw) = pack8(a0 * b0, a1 * b1);
.LBB0_611:
	s_andn2_b64 vcc, exec, s[20:21]
	s_cbranch_vccnz .LBB0_613
	v_pk_mul_f32 v[100:101], v[112:113], v[106:107]
	v_pk_mul_f32 v[98:99], v[110:111], v[116:117]
	v_pk_mul_f32 v[102:103], v[108:109], v[118:119]
	v_ashrrev_i32_e32 v115, 31, v114
	v_readlane_b32 s14, v255, 2
	v_cvt_pk_bf16_f32 v98, v98, v99
	v_cvt_pk_bf16_f32 v99, v100, v101
	v_cvt_pk_bf16_f32 v101, v102, v103
	v_lshlrev_b64 v[102:103], 10, v[114:115]
	v_readlane_b32 s15, v255, 3
	v_pk_mul_f32 v[104:105], v[120:121], v[122:123]
	s_lshl_b32 s92, s12, 1
	v_lshl_add_u64 v[102:103], s[14:15], 0, v[102:103]
	v_cvt_pk_bf16_f32 v100, v104, v105
	v_lshl_add_u64 v[102:103], v[102:103], 0, s[92:93]
	v_lshlrev_b32_e32 v104, 1, v138
	v_mov_b32_e32 v105, v1
	v_lshl_add_u64 v[102:103], v[102:103], 0, v[104:105]
	v_add_co_u32_e32 v102, vcc, 0xfffffc00, v102
	s_nop 1
	v_addc_co_u32_e32 v103, vcc, -1, v103, vcc
	global_store_dwordx4 v[102:103], v[98:101], off

; __device__ __forceinline__ u32x4 pack8(f32x4 a, f32x4 b) { u32x4 w; w.x = pk2(a[0], a[1]); w.y = pk2(a[2], a[3]); w.z = pk2(b[0], b[1]); w.w = pk2(b[2], b[3]); return w; }
;     __device__ __forceinline__ void operator()(const Acc& acc, const Unit& u, int wr, int wc, int fr, int fq, const RsCtx& rc) const {
;     ...
;                 } else if (pn < 4) {
;                     bf16_t* p = CONVB + (size_t)row * 512 + (pn - 2) * 256 + cw;
;                     *(u32x4*)p = pack8(a0, a1); *(u32x4*)(p + 128) = pack8(b0, b1);
.LBB0_614:
	s_andn2_b64 vcc, exec, s[20:21]
	s_cbranch_vccnz .LBB0_616
	v_ashrrev_i32_e32 v115, 31, v114
	v_lshlrev_b64 v[98:99], 10, v[114:115]
	v_lshl_add_u64 v[98:99], s[54:55], 0, v[98:99]
	v_lshl_add_u64 v[98:99], s[22:23], 1, v[98:99]
	v_lshlrev_b32_e32 v100, 1, v138
	v_mov_b32_e32 v101, v1
	v_lshl_add_u64 v[102:103], v[98:99], 0, v[100:101]
	v_cvt_pk_bf16_f32 v98, v110, v111
	v_cvt_pk_bf16_f32 v99, v112, v113
	v_cvt_pk_bf16_f32 v100, v120, v121
	v_cvt_pk_bf16_f32 v101, v108, v109
	global_store_dwordx4 v[102:103], v[98:101], off
	s_nop 1
	v_cvt_pk_bf16_f32 v98, v116, v117
	v_cvt_pk_bf16_f32 v99, v106, v107
	v_cvt_pk_bf16_f32 v100, v122, v123
	v_cvt_pk_bf16_f32 v101, v118, v119
	global_store_dwordx4 v[102:103], v[98:101], off offset:256

; __device__ __forceinline__ u32x4 pack8(f32x4 a, f32x4 b) { u32x4 w; w.x = pk2(a[0], a[1]); w.y = pk2(a[2], a[3]); w.z = pk2(b[0], b[1]); w.w = pk2(b[2], b[3]); return w; }
;     __device__ __forceinline__ void operator()(const Acc& acc, const Unit& u, int wr, int wc, int fr, int fq, const RsCtx& rc) const {
;     ...
;                 if (pn == 0) {
;                     float s = 0.f;
; #pragma unroll
;                     for (int e = 0; e < 4; ++e) s += a0[e] * a0[e] + a1[e] * a1[e] + b0[e] * b0[e] + b1[e] * b1[e];
;                     s += __shfl_xor(s, 16); s += __shfl_xor(s, 32);
;                     if (fq == 0) ssq_q[row * 4 + wc] = s;
;                     *(u32x4*)(LAT + (size_t)row * 512 + cw) = pack8(a0, a1); *(u32x4*)(LAT + (size_t)row * 512 + 128 + cw) = pack8(b0, b1);
.LBB0_626:
	s_nop 0
	v_mul_f32_e32 v98, v120, v120
	v_mul_f32_e32 v99, v121, v121
	v_fmac_f32_e32 v98, v110, v110
	v_fmac_f32_e32 v99, v111, v111
	v_fmac_f32_e32 v98, v116, v116
	v_fmac_f32_e32 v99, v117, v117
	v_fmac_f32_e32 v98, v122, v122
	v_fmac_f32_e32 v99, v123, v123
	v_add_f32_e32 v98, v98, v99
	v_mul_f32_e32 v99, v108, v108
	v_fmac_f32_e32 v99, v112, v112
	v_fmac_f32_e32 v99, v106, v106
	v_fmac_f32_e32 v99, v118, v118
	v_add_f32_e32 v98, v99, v98
	v_mul_f32_e32 v99, v109, v109
	v_fmac_f32_e32 v99, v113, v113
	v_fmac_f32_e32 v99, v107, v107
	v_fmac_f32_e32 v99, v119, v119
	v_and_b32_e32 v100, 64, v217
	v_add_f32_e32 v98, v99, v98
	v_add_u32_e32 v100, 64, v100
	s_nop 1
	v_mov_b32_e32 v99, v98
	s_nop 1
	v_permlane16_swap_b32_e32 v99, v98
	s_waitcnt lgkmcnt(0)
	v_add_f32_e32 v98, v98, v99
	s_nop 1
	v_mov_b32_e32 v99, v98
	s_nop 1
	v_permlane32_swap_b32_e32 v99, v98
	s_and_saveexec_b64 s[20:21], s[42:43]
	s_cbranch_execz .LBB0_628
	s_waitcnt lgkmcnt(0)
	v_add_f32_e32 v100, v98, v99
	v_lshl_or_b32 v98, v114, 2, s76
	v_readlane_b32 s36, v254, 54
	v_ashrrev_i32_e32 v99, 31, v98
	v_readlane_b32 s37, v254, 55
	v_readlane_b32 s38, v254, 56
	v_readlane_b32 s39, v254, 57
	v_readlane_b32 s36, v254, 44
	v_readlane_b32 s37, v254, 45
	v_lshl_add_u64 v[98:99], v[98:99], 2, s[38:39]
	v_readlane_b32 s38, v254, 48
	v_readlane_b32 s39, v254, 49
	global_store_dword v[98:99], v100, off
.LBB0_628:
	s_or_b64 exec, exec, s[20:21]
	v_ashrrev_i32_e32 v115, 31, v114
	v_lshlrev_b64 v[102:103], 10, v[114:115]
	v_cvt_pk_bf16_f32 v98, v110, v111
	s_waitcnt lgkmcnt(0)
	v_cvt_pk_bf16_f32 v99, v112, v113
	v_cvt_pk_bf16_f32 v100, v120, v121
	v_cvt_pk_bf16_f32 v101, v108, v109
	v_lshl_add_u64 v[102:103], v[142:143], 0, v[102:103]
	global_store_dwordx4 v[102:103], v[98:101], off
	s_nop 1
	v_cvt_pk_bf16_f32 v98, v116, v117
	v_cvt_pk_bf16_f32 v99, v106, v107
	v_cvt_pk_bf16_f32 v100, v122, v123
	v_cvt_pk_bf16_f32 v101, v118, v119
	global_store_dwordx4 v[102:103], v[98:101], off offset:256
	s_nop 1
	v_or_b32_e32 v98, 32, v150
	s_and_b64 vcc, exec, s[6:7]
	s_mov_b64 s[20:21], -1
	s_cbranch_vccz .LBB0_618

; __device__ __forceinline__ u32x4 pack8(f32x4 a, f32x4 b) { u32x4 w; w.x = pk2(a[0], a[1]); w.y = pk2(a[2], a[3]); w.z = pk2(b[0], b[1]); w.w = pk2(b[2], b[3]); return w; }
;     __device__ __forceinline__ void operator()(const Acc& acc, const Unit& u, int wr, int wc, int fr, int fq, const RsCtx& rc) const {
;     ...
;             for (int m = 0; m < 4; ++m) { const int row = EPI_ROW(u, ai, wr, m, fr);
;                 const float rs = rc.get(u.pm, ai * 128 + wr * 64 + m * 16 + fr, row);
;                 f32x4 a0 = acc[ai][0][m][0] * rs, a1 = acc[ai][0][m][1] * rs, b0 = acc[ai][1][m][0] * rs, b1 = acc[ai][1][m][1] * rs;
;                 if (pn == 0) {
;                     float s = 0.f;
; #pragma unroll
;                     for (int e = 0; e < 4; ++e) s += a0[e] * a0[e] + a1[e] * a1[e] + b0[e] * b0[e] + b1[e] * b1[e];
;                     s += __shfl_xor(s, 16); s += __shfl_xor(s, 32);
;                     if (fq == 0) ssq_q[row * 4 + wc] = s;
;                     *(u32x4*)(LAT + (size_t)row * 512 + cw) = pack8(a0, a1); *(u32x4*)(LAT + (size_t)row * 512 + 128 + cw) = pack8(b0, b1);
;                 } else if (pn == 1) {
;                     float s = 0.f;
; #pragma unroll
;                     for (int e = 0; e < 4; ++e) s += a0[e] * a0[e] + a1[e] * a1[e];
;                     s += __shfl_xor(s, 16); s += __shfl_xor(s, 32);
;                     if (fq == 0) ssq_kv[row * 4 + wc] = s;
;                     *(u32x4*)(LAT + (size_t)row * 512 + 256 + cw) = pack8(a0, a1);
;                     if (wc == 0) { rope8(b0, b1, TABM + ((size_t)tok_pos(row) * 16 + 4 * fq) * 2); *(u32x4*)(LAT + (size_t)row * 512 + 384 + cw) = pack8(b0, b1); }
.LBB0_631:
	s_waitcnt lgkmcnt(0)
	v_pk_mul_f32 v[96:97], v[96:97], v[106:107] op_sel_hi:[1,0]
	v_pk_mul_f32 v[94:95], v[94:95], v[106:107] op_sel_hi:[1,0]
	v_pk_mul_f32 v[92:93], v[92:93], v[106:107] op_sel_hi:[1,0]
	v_pk_mul_f32 v[104:105], v[90:91], v[106:107] op_sel_hi:[1,0]
	v_pk_mul_f32 v[90:91], v[88:89], v[106:107] op_sel_hi:[1,0]
	v_pk_mul_f32 v[100:101], v[86:87], v[106:107] op_sel_hi:[1,0]
	v_pk_mul_f32 v[102:103], v[84:85], v[106:107] op_sel_hi:[1,0]
	v_pk_mul_f32 v[106:107], v[82:83], v[106:107] op_sel_hi:[1,0]
	s_mov_b64 s[28:29], -1
	s_mov_b64 s[20:21], 0
	s_cmp_lt_i32 s82, 1
	s_mov_b64 s[24:25], 0
	s_cbranch_scc1 .LBB0_659
	s_cmp_eq_u32 s82, 1
	s_mov_b64 s[24:25], -1
	s_cbranch_scc0 .LBB0_638
	v_mul_f32_e32 v82, v104, v104
	v_mul_f32_e32 v83, v105, v105
	v_fmac_f32_e32 v82, v94, v94
	v_fmac_f32_e32 v83, v95, v95
	v_add_f32_e32 v82, v82, v83
	v_mul_f32_e32 v83, v92, v92
	v_fmac_f32_e32 v83, v96, v96
	v_add_f32_e32 v82, v83, v82
	v_mul_f32_e32 v83, v93, v93
	v_fmac_f32_e32 v83, v97, v97
	v_and_b32_e32 v84, 64, v217
	v_add_f32_e32 v82, v83, v82
	v_add_u32_e32 v84, 64, v84
	s_nop 1
	v_mov_b32_e32 v83, v82
	s_nop 1
	v_permlane16_swap_b32_e32 v83, v82
	s_waitcnt lgkmcnt(0)
	v_add_f32_e32 v82, v82, v83
	s_nop 1
	v_mov_b32_e32 v83, v82
	s_nop 1
	v_permlane32_swap_b32_e32 v83, v82
	s_and_saveexec_b64 s[24:25], s[42:43]
	s_cbranch_execz .LBB0_635
	s_waitcnt lgkmcnt(0)
	v_add_f32_e32 v84, v82, v83
	v_lshl_or_b32 v82, v98, 2, s76
	v_ashrrev_i32_e32 v83, 31, v82
	v_lshl_add_u64 v[82:83], v[82:83], 2, s[62:63]
	global_store_dword v[82:83], v84, off
.LBB0_635:
	s_or_b64 exec, exec, s[24:25]
	v_ashrrev_i32_e32 v99, 31, v98
	s_waitcnt lgkmcnt(0)
	v_lshlrev_b64 v[82:83], 10, v[98:99]
	v_cvt_pk_bf16_f32 v84, v94, v95
	v_cvt_pk_bf16_f32 v85, v96, v97
	v_cvt_pk_bf16_f32 v86, v104, v105
	v_cvt_pk_bf16_f32 v87, v92, v93
	v_lshl_add_u64 v[82:83], v[142:143], 0, v[82:83]
	s_andn2_b64 vcc, exec, s[48:49]
	global_store_dwordx4 v[82:83], v[84:87], off offset:512
	s_cbranch_vccnz .LBB0_637
	s_movk_i32 s13, 0x4000
	v_cmp_gt_i32_e32 vcc, s13, v98
	v_mov_b32_e32 v84, 0x1fef
	v_mov_b32_e32 v85, 0xfef
	v_cndmask_b32_e32 v84, v84, v85, vcc
	v_and_b32_e32 v84, v84, v98
	v_lshlrev_b32_e32 v85, 2, v176
	v_readlane_b32 s14, v254, 58
	v_lshl_or_b32 v84, v84, 7, v85
	v_mov_b32_e32 v85, v1
	v_readlane_b32 s15, v254, 59
	s_nop 1
	v_lshl_add_u64 v[88:89], s[14:15], 0, v[84:85]
	flat_load_dwordx4 v[84:87], v[88:89]
	flat_load_dwordx4 v[108:111], v[88:89] offset:16
	s_waitcnt vmcnt(0) lgkmcnt(0)
	v_pk_mul_f32 v[88:89], v[100:101], v[84:85] op_sel:[1,1] op_sel_hi:[0,1]
	v_pk_fma_f32 v[112:113], v[100:101], v[84:85], v[88:89] neg_lo:[0,0,1] neg_hi:[0,0,1]
	v_pk_fma_f32 v[84:85], v[100:101], v[84:85], v[88:89] op_sel_hi:[1,0,1]
	s_nop 0
	v_mov_b32_e32 v84, v87
	v_pk_mul_f32 v[88:89], v[90:91], v[84:85] op_sel:[1,0] op_sel_hi:[0,0]
	v_pk_fma_f32 v[114:115], v[90:91], v[86:87], v[88:89] neg_lo:[0,0,1] neg_hi:[0,0,1]
	v_pk_fma_f32 v[86:87], v[90:91], v[86:87], v[88:89] op_sel_hi:[1,0,1]
	v_pk_mul_f32 v[88:89], v[106:107], v[108:109] op_sel:[1,1] op_sel_hi:[0,1]
	v_mov_b32_e32 v84, v111
	v_pk_fma_f32 v[116:117], v[106:107], v[108:109], v[88:89] neg_lo:[0,0,1] neg_hi:[0,0,1]
	v_pk_fma_f32 v[88:89], v[106:107], v[108:109], v[88:89] op_sel_hi:[1,0,1]
	v_pk_mul_f32 v[108:109], v[102:103], v[84:85] op_sel:[1,0] op_sel_hi:[0,0]
	v_pk_fma_f32 v[118:119], v[102:103], v[110:111], v[108:109] neg_lo:[0,0,1] neg_hi:[0,0,1]
	v_pk_fma_f32 v[108:109], v[102:103], v[110:111], v[108:109] op_sel_hi:[1,0,1]
	v_cvt_pk_bf16_f32 v84, v112, v85
	v_cvt_pk_bf16_f32 v85, v114, v87
	v_cvt_pk_bf16_f32 v86, v116, v89
	v_cvt_pk_bf16_f32 v87, v118, v109
	global_store_dwordx4 v[82:83], v[84:87], off offset:768

; __device__ __forceinline__ u32x4 pack8(f32x4 a, f32x4 b) { u32x4 w; w.x = pk2(a[0], a[1]); w.y = pk2(a[2], a[3]); w.z = pk2(b[0], b[1]); w.w = pk2(b[2], b[3]); return w; }
;     __device__ __forceinline__ void operator()(const Acc& acc, const Unit& u, int wr, int wc, int fr, int fq, const RsCtx& rc) const {
;     ...
;                 } else if (pn < 10) {
;                     const int c = (pn - 8) * 256 + cw; const float* tb = TABS + (size_t)tok_pos(row) * 64;
;                     rope8(a0, a1, tb + (c & 63)); rope8(b0, b1, tb + ((c + 128) & 63));
;                     const float sc = 0.125f * LOG2E;
;                     *(u32x4*)(SWAQK + (size_t)row * 768 + c) = pack8(a0 * sc, a1 * sc); *(u32x4*)(SWAQK + (size_t)row * 768 + c + 128) = pack8(b0 * sc, b1 * sc);
;                 } else {
;                     rope8(a0, a1, TABS + (size_t)tok_pos(row) * 64 + (cw & 63));
;                     *(u32x4*)(SWAQK + (size_t)row * 768 + 512 + cw) = pack8(a0, a1);
;                 }
.LBB0_640:
	s_and_b64 vcc, exec, s[4:5]
	s_mov_b64 s[20:21], -1
	s_cbranch_vccnz .LBB0_650
	s_andn2_b64 vcc, exec, s[26:27]
	s_cbranch_vccnz .LBB0_647
	s_movk_i32 s13, 0x4000
	v_cmp_gt_i32_e32 vcc, s13, v98
	v_mov_b32_e32 v82, 0x1fef
	v_mov_b32_e32 v83, 0xfef
	v_cndmask_b32_e32 v82, v82, v83, vcc
	v_and_b32_e32 v82, v82, v98
	v_lshlrev_b32_e32 v82, 8, v82
	v_mov_b32_e32 v83, v1
	v_lshl_add_u64 v[82:83], v[140:141], 0, v[82:83]
	flat_load_dwordx4 v[86:89], v[82:83]
	s_nop 0
	flat_load_dwordx4 v[82:85], v[82:83] offset:16
	s_andn2_b64 vcc, exec, s[16:17]
	s_waitcnt vmcnt(0) lgkmcnt(0)
	v_mov_b32_e32 v110, v89
	v_mov_b32_e32 v118, v85
	v_pk_mul_f32 v[108:109], v[94:95], v[86:87] op_sel:[0,1]
	v_pk_mul_f32 v[116:117], v[104:105], v[82:83] op_sel:[0,1]
	v_pk_mul_f32 v[122:123], v[96:97], v[110:111] op_sel_hi:[1,0]
	v_pk_mul_f32 v[118:119], v[92:93], v[118:119] op_sel_hi:[1,0]
	v_pk_fma_f32 v[112:113], v[94:95], v[86:87], v[108:109] op_sel:[0,0,1] op_sel_hi:[1,0,0] neg_lo:[0,0,1] neg_hi:[0,0,1]
	v_pk_fma_f32 v[114:115], v[94:95], v[86:87], v[108:109] op_sel:[0,0,1] op_sel_hi:[1,0,0]
	v_pk_fma_f32 v[108:109], v[104:105], v[82:83], v[116:117] op_sel:[0,0,1] op_sel_hi:[1,0,0] neg_lo:[0,0,1] neg_hi:[0,0,1]
	v_pk_fma_f32 v[110:111], v[104:105], v[82:83], v[116:117] op_sel:[0,0,1] op_sel_hi:[1,0,0]
	v_pk_fma_f32 v[120:121], v[96:97], v[88:89], v[122:123] op_sel:[0,0,1] op_sel_hi:[1,0,0] neg_lo:[0,0,1] neg_hi:[0,0,1]
	v_pk_fma_f32 v[122:123], v[96:97], v[88:89], v[122:123] op_sel:[0,0,1] op_sel_hi:[1,0,0]
	v_pk_fma_f32 v[116:117], v[92:93], v[84:85], v[118:119] op_sel:[0,0,1] op_sel_hi:[1,0,0] neg_lo:[0,0,1] neg_hi:[0,0,1]
	v_pk_fma_f32 v[118:119], v[92:93], v[84:85], v[118:119] op_sel:[0,0,1] op_sel_hi:[1,0,0]
	s_cbranch_vccnz .LBB0_644
	s_movk_i32 s13, 0x600
	v_cvt_pk_bf16_f32 v124, v112, v115
	v_cvt_pk_bf16_f32 v125, v120, v123
	v_cvt_pk_bf16_f32 v126, v108, v111
	v_cvt_pk_bf16_f32 v127, v116, v119
	v_mad_i64_i32 v[128:129], s[14:15], v98, s13, v[144:145]
	s_mov_b64 s[20:21], 0
	global_store_dwordx4 v[128:129], v[124:127], off offset:1024
.LBB0_644:
	s_andn2_b64 vcc, exec, s[20:21]
	s_cbranch_vccnz .LBB0_646
	v_mov_b32_e32 v124, v86
	v_mov_b32_e32 v125, v86
	v_mov_b32_e32 v86, v87
	v_mov_b32_e32 v126, v88
	v_mov_b32_e32 v127, v88
	v_mov_b32_e32 v88, v89
	v_mov_b32_e32 v128, v82
	v_mov_b32_e32 v129, v82
	v_mov_b32_e32 v82, v83
	v_mov_b32_e32 v152, v84
	v_mov_b32_e32 v153, v84
	v_mov_b32_e32 v84, v85
	v_pk_mul_f32 v[86:87], v[100:101], v[86:87]
	v_pk_mul_f32 v[88:89], v[90:91], v[88:89]
	v_pk_mul_f32 v[82:83], v[106:107], v[82:83]
	v_pk_fma_f32 v[154:155], v[100:101], v[124:125], v[86:87] op_sel:[0,0,1] op_sel_hi:[1,1,0] neg_lo:[0,0,1] neg_hi:[0,0,1]
	v_pk_fma_f32 v[86:87], v[100:101], v[124:125], v[86:87] op_sel:[0,0,1] op_sel_hi:[1,1,0]
	v_pk_fma_f32 v[124:125], v[90:91], v[126:127], v[88:89] op_sel:[0,0,1] op_sel_hi:[1,1,0] neg_lo:[0,0,1] neg_hi:[0,0,1]
	v_pk_fma_f32 v[88:89], v[90:91], v[126:127], v[88:89] op_sel:[0,0,1] op_sel_hi:[1,1,0]
	v_pk_fma_f32 v[126:127], v[106:107], v[128:129], v[82:83] op_sel:[0,0,1] op_sel_hi:[1,1,0] neg_lo:[0,0,1] neg_hi:[0,0,1]
	v_pk_fma_f32 v[128:129], v[106:107], v[128:129], v[82:83] op_sel:[0,0,1] op_sel_hi:[1,1,0]
	v_pk_mul_f32 v[82:83], v[102:103], v[84:85]
	v_mov_b32_e32 v121, v123
	s_mov_b32 s20, 0x3e38aa3b
	v_mov_b32_e32 v113, v115
	v_mov_b32_e32 v109, v111
	v_readlane_b32 s14, v255, 4
	v_pk_fma_f32 v[156:157], v[102:103], v[152:153], v[82:83] op_sel:[0,0,1] op_sel_hi:[1,1,0] neg_lo:[0,0,1] neg_hi:[0,0,1]
	v_pk_fma_f32 v[152:153], v[102:103], v[152:153], v[82:83] op_sel:[0,0,1] op_sel_hi:[1,1,0]
	v_pk_mul_f32 v[84:85], v[120:121], s[20:21] op_sel_hi:[1,0]
	v_pk_mul_f32 v[82:83], v[112:113], s[20:21] op_sel_hi:[1,0]
	v_pk_mul_f32 v[108:109], v[108:109], s[20:21] op_sel_hi:[1,0]
	v_readlane_b32 s15, v255, 5
	v_mov_b32_e32 v117, v119
	v_cvt_pk_bf16_f32 v82, v82, v83
	v_cvt_pk_bf16_f32 v83, v84, v85
	v_cvt_pk_bf16_f32 v84, v108, v109
	v_mov_b64_e32 v[108:109], s[14:15]
	s_movk_i32 s13, 0x600
	v_pk_mul_f32 v[112:113], v[116:117], s[20:21] op_sel_hi:[1,0]
	v_mad_i64_i32 v[108:109], s[14:15], v98, s13, v[108:109]
	v_cvt_pk_bf16_f32 v85, v112, v113
	v_lshl_add_u64 v[108:109], v[0:1], 1, v[108:109]
	v_mov_b32_e32 v125, v89
	v_mov_b32_e32 v155, v87
	v_mov_b32_e32 v157, v153
	v_mov_b32_e32 v127, v129
	global_store_dwordx4 v[108:109], v[82:85], off
	v_pk_mul_f32 v[86:87], v[156:157], s[20:21] op_sel_hi:[1,0]
	v_pk_mul_f32 v[88:89], v[126:127], s[20:21] op_sel_hi:[1,0]
	v_pk_mul_f32 v[84:85], v[124:125], s[20:21] op_sel_hi:[1,0]
	v_pk_mul_f32 v[82:83], v[154:155], s[20:21] op_sel_hi:[1,0]
	s_nop 0
	v_cvt_pk_bf16_f32 v82, v82, v83
	v_cvt_pk_bf16_f32 v83, v84, v85
	v_cvt_pk_bf16_f32 v84, v88, v89
	v_cvt_pk_bf16_f32 v85, v86, v87
	global_store_dwordx4 v[108:109], v[82:85], off offset:256

; __device__ __forceinline__ u32x4 pack8(f32x4 a, f32x4 b) { u32x4 w; w.x = pk2(a[0], a[1]); w.y = pk2(a[2], a[3]); w.z = pk2(b[0], b[1]); w.w = pk2(b[2], b[3]); return w; }
;     __device__ __forceinline__ void operator()(const Acc& acc, const Unit& u, int wr, int wc, int fr, int fq, const RsCtx& rc) const {
;     ...
;                 } else if (pn < 8) {
;                     *(u32x4*)(CONVZ + (size_t)row * 512 + (pn - 4) * 128 + cw) = pack8(a0 * b0, a1 * b1);
.LBB0_647:
	s_andn2_b64 vcc, exec, s[20:21]
	s_cbranch_vccnz .LBB0_649
	v_pk_mul_f32 v[84:85], v[96:97], v[90:91]
	v_pk_mul_f32 v[82:83], v[94:95], v[100:101]
	v_pk_mul_f32 v[86:87], v[92:93], v[102:103]
	v_ashrrev_i32_e32 v99, 31, v98
	v_readlane_b32 s14, v255, 2
	v_cvt_pk_bf16_f32 v82, v82, v83
	v_cvt_pk_bf16_f32 v83, v84, v85
	v_cvt_pk_bf16_f32 v85, v86, v87
	v_lshlrev_b64 v[86:87], 10, v[98:99]
	v_readlane_b32 s15, v255, 3
	v_pk_mul_f32 v[88:89], v[104:105], v[106:107]
	s_lshl_b32 s92, s12, 1
	v_lshl_add_u64 v[86:87], s[14:15], 0, v[86:87]
	v_cvt_pk_bf16_f32 v84, v88, v89
	v_lshl_add_u64 v[86:87], v[86:87], 0, s[92:93]
	v_lshlrev_b32_e32 v88, 1, v138
	v_mov_b32_e32 v89, v1
	v_lshl_add_u64 v[86:87], v[86:87], 0, v[88:89]
	v_add_co_u32_e32 v86, vcc, 0xfffffc00, v86
	s_nop 1
	v_addc_co_u32_e32 v87, vcc, -1, v87, vcc
	global_store_dwordx4 v[86:87], v[82:85], off

; __device__ __forceinline__ u32x4 pack8(f32x4 a, f32x4 b) { u32x4 w; w.x = pk2(a[0], a[1]); w.y = pk2(a[2], a[3]); w.z = pk2(b[0], b[1]); w.w = pk2(b[2], b[3]); return w; }
;     __device__ __forceinline__ void operator()(const Acc& acc, const Unit& u, int wr, int wc, int fr, int fq, const RsCtx& rc) const {
;     ...
;                 } else if (pn < 4) {
;                     bf16_t* p = CONVB + (size_t)row * 512 + (pn - 2) * 256 + cw;
;                     *(u32x4*)p = pack8(a0, a1); *(u32x4*)(p + 128) = pack8(b0, b1);
.LBB0_650:
	s_andn2_b64 vcc, exec, s[20:21]
	s_cbranch_vccnz .LBB0_652
	v_ashrrev_i32_e32 v99, 31, v98
	v_lshlrev_b64 v[82:83], 10, v[98:99]
	v_lshl_add_u64 v[82:83], s[54:55], 0, v[82:83]
	v_lshl_add_u64 v[82:83], s[22:23], 1, v[82:83]
	v_lshlrev_b32_e32 v84, 1, v138
	v_mov_b32_e32 v85, v1
	v_lshl_add_u64 v[86:87], v[82:83], 0, v[84:85]
	v_cvt_pk_bf16_f32 v82, v94, v95
	v_cvt_pk_bf16_f32 v83, v96, v97
	v_cvt_pk_bf16_f32 v84, v104, v105
	v_cvt_pk_bf16_f32 v85, v92, v93
	global_store_dwordx4 v[86:87], v[82:85], off
	s_nop 1
	v_cvt_pk_bf16_f32 v82, v100, v101
	v_cvt_pk_bf16_f32 v83, v90, v91
	v_cvt_pk_bf16_f32 v84, v106, v107
	v_cvt_pk_bf16_f32 v85, v102, v103
	global_store_dwordx4 v[86:87], v[82:85], off offset:256

; __device__ __forceinline__ u32x4 pack8(f32x4 a, f32x4 b) { u32x4 w; w.x = pk2(a[0], a[1]); w.y = pk2(a[2], a[3]); w.z = pk2(b[0], b[1]); w.w = pk2(b[2], b[3]); return w; }
;     __device__ __forceinline__ void operator()(const Acc& acc, const Unit& u, int wr, int wc, int fr, int fq, const RsCtx& rc) const {
;     ...
;                 if (pn == 0) {
;                     float s = 0.f;
; #pragma unroll
;                     for (int e = 0; e < 4; ++e) s += a0[e] * a0[e] + a1[e] * a1[e] + b0[e] * b0[e] + b1[e] * b1[e];
;                     s += __shfl_xor(s, 16); s += __shfl_xor(s, 32);
;                     if (fq == 0) ssq_q[row * 4 + wc] = s;
;                     *(u32x4*)(LAT + (size_t)row * 512 + cw) = pack8(a0, a1); *(u32x4*)(LAT + (size_t)row * 512 + 128 + cw) = pack8(b0, b1);
.LBB0_662:
	s_nop 0
	v_mul_f32_e32 v82, v104, v104
	v_mul_f32_e32 v83, v105, v105
	v_fmac_f32_e32 v82, v94, v94
	v_fmac_f32_e32 v83, v95, v95
	v_fmac_f32_e32 v82, v100, v100
	v_fmac_f32_e32 v83, v101, v101
	v_fmac_f32_e32 v82, v106, v106
	v_fmac_f32_e32 v83, v107, v107
	v_add_f32_e32 v82, v82, v83
	v_mul_f32_e32 v83, v92, v92
	v_fmac_f32_e32 v83, v96, v96
	v_fmac_f32_e32 v83, v90, v90
	v_fmac_f32_e32 v83, v102, v102
	v_add_f32_e32 v82, v83, v82
	v_mul_f32_e32 v83, v93, v93
	v_fmac_f32_e32 v83, v97, v97
	v_fmac_f32_e32 v83, v91, v91
	v_fmac_f32_e32 v83, v103, v103
	v_and_b32_e32 v84, 64, v217
	v_add_f32_e32 v82, v83, v82
	v_add_u32_e32 v84, 64, v84
	s_nop 1
	v_mov_b32_e32 v83, v82
	s_nop 1
	v_permlane16_swap_b32_e32 v83, v82
	s_waitcnt lgkmcnt(0)
	v_add_f32_e32 v82, v82, v83
	s_nop 1
	v_mov_b32_e32 v83, v82
	s_nop 1
	v_permlane32_swap_b32_e32 v83, v82
	s_and_saveexec_b64 s[20:21], s[42:43]
	s_cbranch_execz .LBB0_664
	s_waitcnt lgkmcnt(0)
	v_add_f32_e32 v84, v82, v83
	v_lshl_or_b32 v82, v98, 2, s76
	v_readlane_b32 s36, v254, 54
	v_ashrrev_i32_e32 v83, 31, v82
	v_readlane_b32 s37, v254, 55
	v_readlane_b32 s38, v254, 56
	v_readlane_b32 s39, v254, 57
	v_readlane_b32 s36, v254, 44
	v_readlane_b32 s37, v254, 45
	v_lshl_add_u64 v[82:83], v[82:83], 2, s[38:39]
	v_readlane_b32 s38, v254, 48
	v_readlane_b32 s39, v254, 49
	global_store_dword v[82:83], v84, off
.LBB0_664:
	s_or_b64 exec, exec, s[20:21]
	v_ashrrev_i32_e32 v99, 31, v98
	v_lshlrev_b64 v[86:87], 10, v[98:99]
	v_cvt_pk_bf16_f32 v82, v94, v95
	s_waitcnt lgkmcnt(0)
	v_cvt_pk_bf16_f32 v83, v96, v97
	v_cvt_pk_bf16_f32 v84, v104, v105
	v_cvt_pk_bf16_f32 v85, v92, v93
	v_lshl_add_u64 v[86:87], v[142:143], 0, v[86:87]
	global_store_dwordx4 v[86:87], v[82:85], off
	s_nop 1
	v_cvt_pk_bf16_f32 v82, v100, v101
	v_cvt_pk_bf16_f32 v83, v90, v91
	v_cvt_pk_bf16_f32 v84, v106, v107
	v_cvt_pk_bf16_f32 v85, v102, v103
	global_store_dwordx4 v[86:87], v[82:85], off offset:256
	s_nop 1
	v_or_b32_e32 v82, 48, v150
	s_and_b64 vcc, exec, s[6:7]
	s_mov_b64 s[20:21], -1
	s_cbranch_vccz .LBB0_654

; __device__ __forceinline__ u32x4 pack8(f32x4 a, f32x4 b) { u32x4 w; w.x = pk2(a[0], a[1]); w.y = pk2(a[2], a[3]); w.z = pk2(b[0], b[1]); w.w = pk2(b[2], b[3]); return w; }
;     __device__ __forceinline__ void operator()(const Acc& acc, const Unit& u, int wr, int wc, int fr, int fq, const RsCtx& rc) const {
;     ...
;             for (int m = 0; m < 4; ++m) { const int row = EPI_ROW(u, ai, wr, m, fr);
;                 const float rs = rc.get(u.pm, ai * 128 + wr * 64 + m * 16 + fr, row);
;                 f32x4 a0 = acc[ai][0][m][0] * rs, a1 = acc[ai][0][m][1] * rs, b0 = acc[ai][1][m][0] * rs, b1 = acc[ai][1][m][1] * rs;
;                 if (pn == 0) {
;                     float s = 0.f;
; #pragma unroll
;                     for (int e = 0; e < 4; ++e) s += a0[e] * a0[e] + a1[e] * a1[e] + b0[e] * b0[e] + b1[e] * b1[e];
;                     s += __shfl_xor(s, 16); s += __shfl_xor(s, 32);
;                     if (fq == 0) ssq_q[row * 4 + wc] = s;
;                     *(u32x4*)(LAT + (size_t)row * 512 + cw) = pack8(a0, a1); *(u32x4*)(LAT + (size_t)row * 512 + 128 + cw) = pack8(b0, b1);
;                 } else if (pn == 1) {
;                     float s = 0.f;
; #pragma unroll
;                     for (int e = 0; e < 4; ++e) s += a0[e] * a0[e] + a1[e] * a1[e];
;                     s += __shfl_xor(s, 16); s += __shfl_xor(s, 32);
;                     if (fq == 0) ssq_kv[row * 4 + wc] = s;
;                     *(u32x4*)(LAT + (size_t)row * 512 + 256 + cw) = pack8(a0, a1);
;                     if (wc == 0) { rope8(b0, b1, TABM + ((size_t)tok_pos(row) * 16 + 4 * fq) * 2); *(u32x4*)(LAT + (size_t)row * 512 + 384 + cw) = pack8(b0, b1); }
.LBB0_667:
	s_waitcnt lgkmcnt(0)
	v_pk_mul_f32 v[80:81], v[80:81], v[90:91] op_sel_hi:[1,0]
	v_pk_mul_f32 v[78:79], v[78:79], v[90:91] op_sel_hi:[1,0]
	v_pk_mul_f32 v[76:77], v[76:77], v[90:91] op_sel_hi:[1,0]
	v_pk_mul_f32 v[88:89], v[74:75], v[90:91] op_sel_hi:[1,0]
	v_pk_mul_f32 v[74:75], v[72:73], v[90:91] op_sel_hi:[1,0]
	v_pk_mul_f32 v[84:85], v[70:71], v[90:91] op_sel_hi:[1,0]
	v_pk_mul_f32 v[86:87], v[68:69], v[90:91] op_sel_hi:[1,0]
	v_pk_mul_f32 v[90:91], v[66:67], v[90:91] op_sel_hi:[1,0]
	s_mov_b64 s[28:29], -1
	s_mov_b64 s[20:21], 0
	s_cmp_lt_i32 s82, 1
	s_mov_b64 s[24:25], 0
	s_cbranch_scc1 .LBB0_689
	s_cmp_eq_u32 s82, 1
	s_mov_b64 s[24:25], -1
	s_cbranch_scc0 .LBB0_674
	v_mul_f32_e32 v66, v88, v88
	v_mul_f32_e32 v67, v89, v89
	v_fmac_f32_e32 v66, v78, v78
	v_fmac_f32_e32 v67, v79, v79
	v_add_f32_e32 v66, v66, v67
	v_mul_f32_e32 v67, v76, v76
	v_fmac_f32_e32 v67, v80, v80
	v_add_f32_e32 v66, v67, v66
	v_mul_f32_e32 v67, v77, v77
	v_fmac_f32_e32 v67, v81, v81
	v_and_b32_e32 v68, 64, v217
	v_add_f32_e32 v66, v67, v66
	v_add_u32_e32 v68, 64, v68
	s_nop 1
	v_mov_b32_e32 v67, v66
	s_nop 1
	v_permlane16_swap_b32_e32 v67, v66
	s_waitcnt lgkmcnt(0)
	v_add_f32_e32 v66, v66, v67
	s_nop 1
	v_mov_b32_e32 v67, v66
	s_nop 1
	v_permlane32_swap_b32_e32 v67, v66
	s_and_saveexec_b64 s[24:25], s[42:43]
	s_cbranch_execz .LBB0_671
	s_waitcnt lgkmcnt(0)
	v_add_f32_e32 v68, v66, v67
	v_lshl_or_b32 v66, v82, 2, s76
	v_ashrrev_i32_e32 v67, 31, v66
	v_lshl_add_u64 v[66:67], v[66:67], 2, s[62:63]
	global_store_dword v[66:67], v68, off
.LBB0_671:
	s_or_b64 exec, exec, s[24:25]
	v_ashrrev_i32_e32 v83, 31, v82
	s_waitcnt lgkmcnt(0)
	v_lshlrev_b64 v[66:67], 10, v[82:83]
	v_cvt_pk_bf16_f32 v68, v78, v79
	v_cvt_pk_bf16_f32 v69, v80, v81
	v_cvt_pk_bf16_f32 v70, v88, v89
	v_cvt_pk_bf16_f32 v71, v76, v77
	v_lshl_add_u64 v[66:67], v[142:143], 0, v[66:67]
	s_andn2_b64 vcc, exec, s[48:49]
	global_store_dwordx4 v[66:67], v[68:71], off offset:512
	s_cbranch_vccnz .LBB0_673
	s_movk_i32 s13, 0x4000
	v_cmp_gt_i32_e32 vcc, s13, v82
	v_lshlrev_b32_e32 v69, 2, v176
	v_readlane_b32 s14, v254, 58
	v_cndmask_b32_e32 v68, v215, v216, vcc
	v_and_b32_e32 v68, v68, v82
	v_lshl_or_b32 v68, v68, 7, v69
	v_mov_b32_e32 v69, v1
	v_readlane_b32 s15, v254, 59
	s_nop 1
	v_lshl_add_u64 v[72:73], s[14:15], 0, v[68:69]
	flat_load_dwordx4 v[68:71], v[72:73]
	flat_load_dwordx4 v[92:95], v[72:73] offset:16
	s_waitcnt vmcnt(0) lgkmcnt(0)
	v_pk_mul_f32 v[72:73], v[84:85], v[68:69] op_sel:[1,1] op_sel_hi:[0,1]
	v_pk_fma_f32 v[96:97], v[84:85], v[68:69], v[72:73] neg_lo:[0,0,1] neg_hi:[0,0,1]
	v_pk_fma_f32 v[68:69], v[84:85], v[68:69], v[72:73] op_sel_hi:[1,0,1]
	s_nop 0
	v_mov_b32_e32 v68, v71
	v_pk_mul_f32 v[72:73], v[74:75], v[68:69] op_sel:[1,0] op_sel_hi:[0,0]
	v_pk_fma_f32 v[98:99], v[74:75], v[70:71], v[72:73] neg_lo:[0,0,1] neg_hi:[0,0,1]
	v_pk_fma_f32 v[70:71], v[74:75], v[70:71], v[72:73] op_sel_hi:[1,0,1]
	v_pk_mul_f32 v[72:73], v[90:91], v[92:93] op_sel:[1,1] op_sel_hi:[0,1]
	v_mov_b32_e32 v68, v95
	v_pk_fma_f32 v[100:101], v[90:91], v[92:93], v[72:73] neg_lo:[0,0,1] neg_hi:[0,0,1]
	v_pk_fma_f32 v[72:73], v[90:91], v[92:93], v[72:73] op_sel_hi:[1,0,1]
	v_pk_mul_f32 v[92:93], v[86:87], v[68:69] op_sel:[1,0] op_sel_hi:[0,0]
	v_pk_fma_f32 v[102:103], v[86:87], v[94:95], v[92:93] neg_lo:[0,0,1] neg_hi:[0,0,1]
	v_pk_fma_f32 v[92:93], v[86:87], v[94:95], v[92:93] op_sel_hi:[1,0,1]
	v_cvt_pk_bf16_f32 v68, v96, v69
	v_cvt_pk_bf16_f32 v69, v98, v71
	v_cvt_pk_bf16_f32 v70, v100, v73
	v_cvt_pk_bf16_f32 v71, v102, v93
	global_store_dwordx4 v[66:67], v[68:71], off offset:768

; __device__ __forceinline__ u32x4 pack8(f32x4 a, f32x4 b) { u32x4 w; w.x = pk2(a[0], a[1]); w.y = pk2(a[2], a[3]); w.z = pk2(b[0], b[1]); w.w = pk2(b[2], b[3]); return w; }
;     __device__ __forceinline__ void operator()(const Acc& acc, const Unit& u, int wr, int wc, int fr, int fq, const RsCtx& rc) const {
;     ...
;                 } else if (pn < 10) {
;                     const int c = (pn - 8) * 256 + cw; const float* tb = TABS + (size_t)tok_pos(row) * 64;
;                     rope8(a0, a1, tb + (c & 63)); rope8(b0, b1, tb + ((c + 128) & 63));
;                     const float sc = 0.125f * LOG2E;
;                     *(u32x4*)(SWAQK + (size_t)row * 768 + c) = pack8(a0 * sc, a1 * sc); *(u32x4*)(SWAQK + (size_t)row * 768 + c + 128) = pack8(b0 * sc, b1 * sc);
;                 } else {
;                     rope8(a0, a1, TABS + (size_t)tok_pos(row) * 64 + (cw & 63));
;                     *(u32x4*)(SWAQK + (size_t)row * 768 + 512 + cw) = pack8(a0, a1);
;                 }
.LBB0_676:
	s_and_b64 vcc, exec, s[4:5]
	s_mov_b64 s[20:21], -1
	s_cbranch_vccnz .LBB0_686
	s_andn2_b64 vcc, exec, s[26:27]
	s_cbranch_vccnz .LBB0_683
	s_movk_i32 s13, 0x4000
	v_cmp_gt_i32_e32 vcc, s13, v82
	v_mov_b32_e32 v67, v1
	s_nop 0
	v_cndmask_b32_e32 v66, v215, v216, vcc
	v_and_b32_e32 v66, v66, v82
	v_lshlrev_b32_e32 v66, 8, v66
	v_lshl_add_u64 v[66:67], v[140:141], 0, v[66:67]
	flat_load_dwordx4 v[70:73], v[66:67]
	s_nop 0
	flat_load_dwordx4 v[66:69], v[66:67] offset:16
	s_andn2_b64 vcc, exec, s[16:17]
	s_waitcnt vmcnt(0) lgkmcnt(0)
	v_mov_b32_e32 v94, v73
	v_mov_b32_e32 v102, v69
	v_pk_mul_f32 v[92:93], v[78:79], v[70:71] op_sel:[0,1]
	v_pk_mul_f32 v[100:101], v[88:89], v[66:67] op_sel:[0,1]
	v_pk_mul_f32 v[106:107], v[80:81], v[94:95] op_sel_hi:[1,0]
	v_pk_mul_f32 v[102:103], v[76:77], v[102:103] op_sel_hi:[1,0]
	v_pk_fma_f32 v[96:97], v[78:79], v[70:71], v[92:93] op_sel:[0,0,1] op_sel_hi:[1,0,0] neg_lo:[0,0,1] neg_hi:[0,0,1]
	v_pk_fma_f32 v[98:99], v[78:79], v[70:71], v[92:93] op_sel:[0,0,1] op_sel_hi:[1,0,0]
	v_pk_fma_f32 v[92:93], v[88:89], v[66:67], v[100:101] op_sel:[0,0,1] op_sel_hi:[1,0,0] neg_lo:[0,0,1] neg_hi:[0,0,1]
	v_pk_fma_f32 v[94:95], v[88:89], v[66:67], v[100:101] op_sel:[0,0,1] op_sel_hi:[1,0,0]
	v_pk_fma_f32 v[104:105], v[80:81], v[72:73], v[106:107] op_sel:[0,0,1] op_sel_hi:[1,0,0] neg_lo:[0,0,1] neg_hi:[0,0,1]
	v_pk_fma_f32 v[106:107], v[80:81], v[72:73], v[106:107] op_sel:[0,0,1] op_sel_hi:[1,0,0]
	v_pk_fma_f32 v[100:101], v[76:77], v[68:69], v[102:103] op_sel:[0,0,1] op_sel_hi:[1,0,0] neg_lo:[0,0,1] neg_hi:[0,0,1]
	v_pk_fma_f32 v[102:103], v[76:77], v[68:69], v[102:103] op_sel:[0,0,1] op_sel_hi:[1,0,0]
	s_cbranch_vccnz .LBB0_680
	s_movk_i32 s13, 0x600
	v_cvt_pk_bf16_f32 v108, v96, v99
	v_cvt_pk_bf16_f32 v109, v104, v107
	v_cvt_pk_bf16_f32 v110, v92, v95
	v_cvt_pk_bf16_f32 v111, v100, v103
	v_mad_i64_i32 v[112:113], s[14:15], v82, s13, v[144:145]
	s_mov_b64 s[20:21], 0
	global_store_dwordx4 v[112:113], v[108:111], off offset:1024
.LBB0_680:
	s_andn2_b64 vcc, exec, s[20:21]
	s_cbranch_vccnz .LBB0_682
	v_mov_b32_e32 v108, v70
	v_mov_b32_e32 v109, v70
	v_mov_b32_e32 v70, v71
	v_mov_b32_e32 v110, v72
	v_mov_b32_e32 v111, v72
	v_mov_b32_e32 v72, v73
	v_mov_b32_e32 v112, v66
	v_mov_b32_e32 v113, v66
	v_mov_b32_e32 v66, v67
	v_mov_b32_e32 v114, v68
	v_mov_b32_e32 v115, v68
	v_mov_b32_e32 v68, v69
	v_pk_mul_f32 v[70:71], v[84:85], v[70:71]
	v_pk_mul_f32 v[72:73], v[74:75], v[72:73]
	v_pk_mul_f32 v[66:67], v[90:91], v[66:67]
	v_pk_fma_f32 v[116:117], v[84:85], v[108:109], v[70:71] op_sel:[0,0,1] op_sel_hi:[1,1,0] neg_lo:[0,0,1] neg_hi:[0,0,1]
	v_pk_fma_f32 v[70:71], v[84:85], v[108:109], v[70:71] op_sel:[0,0,1] op_sel_hi:[1,1,0]
	v_pk_fma_f32 v[108:109], v[74:75], v[110:111], v[72:73] op_sel:[0,0,1] op_sel_hi:[1,1,0] neg_lo:[0,0,1] neg_hi:[0,0,1]
	v_pk_fma_f32 v[72:73], v[74:75], v[110:111], v[72:73] op_sel:[0,0,1] op_sel_hi:[1,1,0]
	v_pk_fma_f32 v[110:111], v[90:91], v[112:113], v[66:67] op_sel:[0,0,1] op_sel_hi:[1,1,0] neg_lo:[0,0,1] neg_hi:[0,0,1]
	v_pk_fma_f32 v[112:113], v[90:91], v[112:113], v[66:67] op_sel:[0,0,1] op_sel_hi:[1,1,0]
	v_pk_mul_f32 v[66:67], v[86:87], v[68:69]
	v_mov_b32_e32 v105, v107
	s_mov_b32 s20, 0x3e38aa3b
	v_mov_b32_e32 v97, v99
	v_mov_b32_e32 v93, v95
	v_readlane_b32 s14, v255, 4
	v_pk_fma_f32 v[118:119], v[86:87], v[114:115], v[66:67] op_sel:[0,0,1] op_sel_hi:[1,1,0] neg_lo:[0,0,1] neg_hi:[0,0,1]
	v_pk_fma_f32 v[114:115], v[86:87], v[114:115], v[66:67] op_sel:[0,0,1] op_sel_hi:[1,1,0]
	v_pk_mul_f32 v[68:69], v[104:105], s[20:21] op_sel_hi:[1,0]
	v_pk_mul_f32 v[66:67], v[96:97], s[20:21] op_sel_hi:[1,0]
	v_pk_mul_f32 v[92:93], v[92:93], s[20:21] op_sel_hi:[1,0]
	v_readlane_b32 s15, v255, 5
	v_mov_b32_e32 v101, v103
	v_cvt_pk_bf16_f32 v66, v66, v67
	v_cvt_pk_bf16_f32 v67, v68, v69
	v_cvt_pk_bf16_f32 v68, v92, v93
	v_mov_b64_e32 v[92:93], s[14:15]
	s_movk_i32 s13, 0x600
	v_pk_mul_f32 v[96:97], v[100:101], s[20:21] op_sel_hi:[1,0]
	v_mad_i64_i32 v[92:93], s[14:15], v82, s13, v[92:93]
	v_cvt_pk_bf16_f32 v69, v96, v97
	v_lshl_add_u64 v[92:93], v[0:1], 1, v[92:93]
	v_mov_b32_e32 v109, v73
	v_mov_b32_e32 v117, v71
	v_mov_b32_e32 v119, v115
	v_mov_b32_e32 v111, v113
	global_store_dwordx4 v[92:93], v[66:69], off
	v_pk_mul_f32 v[70:71], v[118:119], s[20:21] op_sel_hi:[1,0]
	v_pk_mul_f32 v[72:73], v[110:111], s[20:21] op_sel_hi:[1,0]
	v_pk_mul_f32 v[68:69], v[108:109], s[20:21] op_sel_hi:[1,0]
	v_pk_mul_f32 v[66:67], v[116:117], s[20:21] op_sel_hi:[1,0]
	s_nop 0
	v_cvt_pk_bf16_f32 v66, v66, v67
	v_cvt_pk_bf16_f32 v67, v68, v69
	v_cvt_pk_bf16_f32 v68, v72, v73
	v_cvt_pk_bf16_f32 v69, v70, v71
	global_store_dwordx4 v[92:93], v[66:69], off offset:256

; __device__ __forceinline__ u32x4 pack8(f32x4 a, f32x4 b) { u32x4 w; w.x = pk2(a[0], a[1]); w.y = pk2(a[2], a[3]); w.z = pk2(b[0], b[1]); w.w = pk2(b[2], b[3]); return w; }
;     __device__ __forceinline__ void operator()(const Acc& acc, const Unit& u, int wr, int wc, int fr, int fq, const RsCtx& rc) const {
;     ...
;                 } else if (pn < 8) {
;                     *(u32x4*)(CONVZ + (size_t)row * 512 + (pn - 4) * 128 + cw) = pack8(a0 * b0, a1 * b1);
.LBB0_683:
	s_andn2_b64 vcc, exec, s[20:21]
	s_cbranch_vccnz .LBB0_685
	v_pk_mul_f32 v[68:69], v[80:81], v[74:75]
	v_pk_mul_f32 v[66:67], v[78:79], v[84:85]
	v_pk_mul_f32 v[70:71], v[76:77], v[86:87]
	v_ashrrev_i32_e32 v83, 31, v82
	v_readlane_b32 s14, v255, 2
	v_cvt_pk_bf16_f32 v66, v66, v67
	v_cvt_pk_bf16_f32 v67, v68, v69
	v_cvt_pk_bf16_f32 v69, v70, v71
	v_lshlrev_b64 v[70:71], 10, v[82:83]
	v_readlane_b32 s15, v255, 3
	v_pk_mul_f32 v[72:73], v[88:89], v[90:91]
	s_lshl_b32 s92, s12, 1
	v_lshl_add_u64 v[70:71], s[14:15], 0, v[70:71]
	v_cvt_pk_bf16_f32 v68, v72, v73
	v_lshl_add_u64 v[70:71], v[70:71], 0, s[92:93]
	v_lshlrev_b32_e32 v72, 1, v138
	v_mov_b32_e32 v73, v1
	v_lshl_add_u64 v[70:71], v[70:71], 0, v[72:73]
	v_add_co_u32_e32 v70, vcc, 0xfffffc00, v70
	s_nop 1
	v_addc_co_u32_e32 v71, vcc, -1, v71, vcc
	global_store_dwordx4 v[70:71], v[66:69], off

; __device__ __forceinline__ u32x4 pack8(f32x4 a, f32x4 b) { u32x4 w; w.x = pk2(a[0], a[1]); w.y = pk2(a[2], a[3]); w.z = pk2(b[0], b[1]); w.w = pk2(b[2], b[3]); return w; }
;     __device__ __forceinline__ void operator()(const Acc& acc, const Unit& u, int wr, int wc, int fr, int fq, const RsCtx& rc) const {
;     ...
;                 } else if (pn < 4) {
;                     bf16_t* p = CONVB + (size_t)row * 512 + (pn - 2) * 256 + cw;
;                     *(u32x4*)p = pack8(a0, a1); *(u32x4*)(p + 128) = pack8(b0, b1);
.LBB0_686:
	s_andn2_b64 vcc, exec, s[20:21]
	s_cbranch_vccnz .LBB0_688
	v_ashrrev_i32_e32 v83, 31, v82
	v_lshlrev_b64 v[66:67], 10, v[82:83]
	v_lshl_add_u64 v[66:67], s[54:55], 0, v[66:67]
	v_lshl_add_u64 v[66:67], s[22:23], 1, v[66:67]
	v_lshlrev_b32_e32 v68, 1, v138
	v_mov_b32_e32 v69, v1
	v_lshl_add_u64 v[70:71], v[66:67], 0, v[68:69]
	v_cvt_pk_bf16_f32 v66, v78, v79
	v_cvt_pk_bf16_f32 v67, v80, v81
	v_cvt_pk_bf16_f32 v68, v88, v89
	v_cvt_pk_bf16_f32 v69, v76, v77
	global_store_dwordx4 v[70:71], v[66:69], off
	s_nop 1
	v_cvt_pk_bf16_f32 v66, v84, v85
	v_cvt_pk_bf16_f32 v67, v74, v75
	v_cvt_pk_bf16_f32 v68, v90, v91
	v_cvt_pk_bf16_f32 v69, v86, v87
	global_store_dwordx4 v[70:71], v[66:69], off offset:256

; __device__ __forceinline__ u32x4 pack8(f32x4 a, f32x4 b) { u32x4 w; w.x = pk2(a[0], a[1]); w.y = pk2(a[2], a[3]); w.z = pk2(b[0], b[1]); w.w = pk2(b[2], b[3]); return w; }
;     __device__ __forceinline__ void operator()(const Acc& acc, const Unit& u, int wr, int wc, int fr, int fq, const RsCtx& rc) const {
;     ...
;                 if (pn == 0) {
;                     float s = 0.f;
; #pragma unroll
;                     for (int e = 0; e < 4; ++e) s += a0[e] * a0[e] + a1[e] * a1[e] + b0[e] * b0[e] + b1[e] * b1[e];
;                     s += __shfl_xor(s, 16); s += __shfl_xor(s, 32);
;                     if (fq == 0) ssq_q[row * 4 + wc] = s;
;                     *(u32x4*)(LAT + (size_t)row * 512 + cw) = pack8(a0, a1); *(u32x4*)(LAT + (size_t)row * 512 + 128 + cw) = pack8(b0, b1);
.LBB0_692:
	v_mul_f32_e32 v66, v88, v88
	v_mul_f32_e32 v67, v89, v89
	v_fmac_f32_e32 v66, v78, v78
	v_fmac_f32_e32 v67, v79, v79
	v_fmac_f32_e32 v66, v84, v84
	v_fmac_f32_e32 v67, v85, v85
	v_fmac_f32_e32 v66, v90, v90
	v_fmac_f32_e32 v67, v91, v91
	v_add_f32_e32 v66, v66, v67
	v_mul_f32_e32 v67, v76, v76
	v_fmac_f32_e32 v67, v80, v80
	v_fmac_f32_e32 v67, v74, v74
	v_fmac_f32_e32 v67, v86, v86
	v_add_f32_e32 v66, v67, v66
	v_mul_f32_e32 v67, v77, v77
	v_fmac_f32_e32 v67, v81, v81
	v_fmac_f32_e32 v67, v75, v75
	v_fmac_f32_e32 v67, v87, v87
	v_and_b32_e32 v68, 64, v217
	v_add_f32_e32 v66, v67, v66
	v_add_u32_e32 v68, 64, v68
	s_nop 1
	v_mov_b32_e32 v67, v66
	s_nop 1
	v_permlane16_swap_b32_e32 v67, v66
	s_waitcnt lgkmcnt(0)
	v_add_f32_e32 v66, v66, v67
	s_nop 1
	v_mov_b32_e32 v67, v66
	s_nop 1
	v_permlane32_swap_b32_e32 v67, v66
	s_and_saveexec_b64 s[20:21], s[42:43]
	s_cbranch_execz .LBB0_694
	s_waitcnt lgkmcnt(0)
	v_add_f32_e32 v68, v66, v67
	v_lshl_or_b32 v66, v82, 2, s76
	v_readlane_b32 s36, v254, 54
	v_ashrrev_i32_e32 v67, 31, v66
	v_readlane_b32 s37, v254, 55
	v_readlane_b32 s38, v254, 56
	v_readlane_b32 s39, v254, 57
	v_readlane_b32 s36, v254, 44
	v_readlane_b32 s37, v254, 45
	v_lshl_add_u64 v[66:67], v[66:67], 2, s[38:39]
	v_readlane_b32 s38, v254, 48
	v_readlane_b32 s39, v254, 49
	global_store_dword v[66:67], v68, off
.LBB0_694:
	s_or_b64 exec, exec, s[20:21]
	v_ashrrev_i32_e32 v83, 31, v82
	v_lshlrev_b64 v[70:71], 10, v[82:83]
	v_cvt_pk_bf16_f32 v66, v78, v79
	s_waitcnt lgkmcnt(0)
	v_cvt_pk_bf16_f32 v67, v80, v81
	v_cvt_pk_bf16_f32 v68, v88, v89
	v_cvt_pk_bf16_f32 v69, v76, v77
	v_lshl_add_u64 v[70:71], v[142:143], 0, v[70:71]
	global_store_dwordx4 v[70:71], v[66:69], off
	s_nop 1
	v_cvt_pk_bf16_f32 v66, v84, v85
	v_cvt_pk_bf16_f32 v67, v74, v75
	v_cvt_pk_bf16_f32 v68, v90, v91
	v_cvt_pk_bf16_f32 v69, v86, v87
	global_store_dwordx4 v[70:71], v[66:69], off offset:256

; __device__ __forceinline__ u32x4 pack8(f32x4 a, f32x4 b) { u32x4 w; w.x = pk2(a[0], a[1]); w.y = pk2(a[2], a[3]); w.z = pk2(b[0], b[1]); w.w = pk2(b[2], b[3]); return w; }
;     __device__ __forceinline__ void operator()(const Acc& acc, const Unit& u, int wr, int wc, int fr, int fq, const RsCtx& rc) const {
;     ...
;             for (int m = 0; m < 4; ++m) { const int row = EPI_ROW(u, ai, wr, m, fr);
;                 const float rs = rc.get(u.pm, ai * 128 + wr * 64 + m * 16 + fr, row);
;                 f32x4 a0 = acc[ai][0][m][0] * rs, a1 = acc[ai][0][m][1] * rs, b0 = acc[ai][1][m][0] * rs, b1 = acc[ai][1][m][1] * rs;
;                 if (pn == 0) {
;                     float s = 0.f;
; #pragma unroll
;                     for (int e = 0; e < 4; ++e) s += a0[e] * a0[e] + a1[e] * a1[e] + b0[e] * b0[e] + b1[e] * b1[e];
;                     s += __shfl_xor(s, 16); s += __shfl_xor(s, 32);
;                     if (fq == 0) ssq_q[row * 4 + wc] = s;
;                     *(u32x4*)(LAT + (size_t)row * 512 + cw) = pack8(a0, a1); *(u32x4*)(LAT + (size_t)row * 512 + 128 + cw) = pack8(b0, b1);
;                 } else if (pn == 1) {
;                     float s = 0.f;
; #pragma unroll
;                     for (int e = 0; e < 4; ++e) s += a0[e] * a0[e] + a1[e] * a1[e];
;                     s += __shfl_xor(s, 16); s += __shfl_xor(s, 32);
;                     if (fq == 0) ssq_kv[row * 4 + wc] = s;
;                     *(u32x4*)(LAT + (size_t)row * 512 + 256 + cw) = pack8(a0, a1);
;                     if (wc == 0) { rope8(b0, b1, TABM + ((size_t)tok_pos(row) * 16 + 4 * fq) * 2); *(u32x4*)(LAT + (size_t)row * 512 + 384 + cw) = pack8(b0, b1); }
.LBB0_703:
	s_waitcnt lgkmcnt(0)
	v_pk_mul_f32 v[64:65], v[64:65], v[74:75] op_sel_hi:[1,0]
	v_pk_mul_f32 v[62:63], v[62:63], v[74:75] op_sel_hi:[1,0]
	v_pk_mul_f32 v[60:61], v[60:61], v[74:75] op_sel_hi:[1,0]
	v_pk_mul_f32 v[72:73], v[58:59], v[74:75] op_sel_hi:[1,0]
	v_pk_mul_f32 v[58:59], v[56:57], v[74:75] op_sel_hi:[1,0]
	v_pk_mul_f32 v[68:69], v[54:55], v[74:75] op_sel_hi:[1,0]
	v_pk_mul_f32 v[70:71], v[52:53], v[74:75] op_sel_hi:[1,0]
	v_pk_mul_f32 v[74:75], v[50:51], v[74:75] op_sel_hi:[1,0]
	s_mov_b64 s[28:29], -1
	s_mov_b64 s[20:21], 0
	s_cmp_lt_i32 s82, 1
	s_mov_b64 s[24:25], 0
	s_cbranch_scc1 .LBB0_731
	s_cmp_eq_u32 s82, 1
	s_mov_b64 s[24:25], -1
	s_cbranch_scc0 .LBB0_710
	v_mul_f32_e32 v50, v72, v72
	v_mul_f32_e32 v51, v73, v73
	v_fmac_f32_e32 v50, v62, v62
	v_fmac_f32_e32 v51, v63, v63
	v_add_f32_e32 v50, v50, v51
	v_mul_f32_e32 v51, v60, v60
	v_fmac_f32_e32 v51, v64, v64
	v_add_f32_e32 v50, v51, v50
	v_mul_f32_e32 v51, v61, v61
	v_fmac_f32_e32 v51, v65, v65
	v_and_b32_e32 v52, 64, v217
	v_add_f32_e32 v50, v51, v50
	v_add_u32_e32 v52, 64, v52
	s_nop 1
	v_mov_b32_e32 v51, v50
	s_nop 1
	v_permlane16_swap_b32_e32 v51, v50
	s_waitcnt lgkmcnt(0)
	v_add_f32_e32 v50, v50, v51
	s_nop 1
	v_mov_b32_e32 v51, v50
	s_nop 1
	v_permlane32_swap_b32_e32 v51, v50
	s_and_saveexec_b64 s[24:25], s[42:43]
	s_cbranch_execz .LBB0_707
	s_waitcnt lgkmcnt(0)
	v_add_f32_e32 v52, v50, v51
	v_lshl_or_b32 v50, v66, 2, s76
	v_ashrrev_i32_e32 v51, 31, v50
	v_lshl_add_u64 v[50:51], v[50:51], 2, s[62:63]
	global_store_dword v[50:51], v52, off
.LBB0_707:
	s_or_b64 exec, exec, s[24:25]
	v_ashrrev_i32_e32 v67, 31, v66
	s_waitcnt lgkmcnt(0)
	v_lshlrev_b64 v[50:51], 10, v[66:67]
	v_cvt_pk_bf16_f32 v52, v62, v63
	v_cvt_pk_bf16_f32 v53, v64, v65
	v_cvt_pk_bf16_f32 v54, v72, v73
	v_cvt_pk_bf16_f32 v55, v60, v61
	v_lshl_add_u64 v[50:51], v[142:143], 0, v[50:51]
	s_andn2_b64 vcc, exec, s[48:49]
	global_store_dwordx4 v[50:51], v[52:55], off offset:512
	s_cbranch_vccnz .LBB0_709
	s_movk_i32 s13, 0x4000
	v_cmp_gt_i32_e32 vcc, s13, v66
	v_mov_b32_e32 v52, 0x1fcf
	v_mov_b32_e32 v53, 0xfcf
	v_cndmask_b32_e32 v52, v52, v53, vcc
	v_and_b32_e32 v52, v52, v66
	v_lshlrev_b32_e32 v53, 2, v176
	v_readlane_b32 s14, v254, 58
	v_lshl_or_b32 v52, v52, 7, v53
	v_mov_b32_e32 v53, v1
	v_readlane_b32 s15, v254, 59
	s_nop 1
	v_lshl_add_u64 v[56:57], s[14:15], 0, v[52:53]
	flat_load_dwordx4 v[52:55], v[56:57]
	flat_load_dwordx4 v[76:79], v[56:57] offset:16
	s_waitcnt vmcnt(0) lgkmcnt(0)
	v_pk_mul_f32 v[56:57], v[68:69], v[52:53] op_sel:[1,1] op_sel_hi:[0,1]
	v_pk_fma_f32 v[80:81], v[68:69], v[52:53], v[56:57] neg_lo:[0,0,1] neg_hi:[0,0,1]
	v_pk_fma_f32 v[52:53], v[68:69], v[52:53], v[56:57] op_sel_hi:[1,0,1]
	s_nop 0
	v_mov_b32_e32 v52, v55
	v_pk_mul_f32 v[56:57], v[58:59], v[52:53] op_sel:[1,0] op_sel_hi:[0,0]
	v_pk_fma_f32 v[82:83], v[58:59], v[54:55], v[56:57] neg_lo:[0,0,1] neg_hi:[0,0,1]
	v_pk_fma_f32 v[54:55], v[58:59], v[54:55], v[56:57] op_sel_hi:[1,0,1]
	v_pk_mul_f32 v[56:57], v[74:75], v[76:77] op_sel:[1,1] op_sel_hi:[0,1]
	v_mov_b32_e32 v52, v79
	v_pk_fma_f32 v[84:85], v[74:75], v[76:77], v[56:57] neg_lo:[0,0,1] neg_hi:[0,0,1]
	v_pk_fma_f32 v[56:57], v[74:75], v[76:77], v[56:57] op_sel_hi:[1,0,1]
	v_pk_mul_f32 v[76:77], v[70:71], v[52:53] op_sel:[1,0] op_sel_hi:[0,0]
	v_pk_fma_f32 v[86:87], v[70:71], v[78:79], v[76:77] neg_lo:[0,0,1] neg_hi:[0,0,1]
	v_pk_fma_f32 v[76:77], v[70:71], v[78:79], v[76:77] op_sel_hi:[1,0,1]
	v_cvt_pk_bf16_f32 v52, v80, v53
	v_cvt_pk_bf16_f32 v53, v82, v55
	v_cvt_pk_bf16_f32 v54, v84, v57
	v_cvt_pk_bf16_f32 v55, v86, v77
	global_store_dwordx4 v[50:51], v[52:55], off offset:768

; __device__ __forceinline__ u32x4 pack8(f32x4 a, f32x4 b) { u32x4 w; w.x = pk2(a[0], a[1]); w.y = pk2(a[2], a[3]); w.z = pk2(b[0], b[1]); w.w = pk2(b[2], b[3]); return w; }
;     __device__ __forceinline__ void operator()(const Acc& acc, const Unit& u, int wr, int wc, int fr, int fq, const RsCtx& rc) const {
;     ...
;                 } else if (pn < 10) {
;                     const int c = (pn - 8) * 256 + cw; const float* tb = TABS + (size_t)tok_pos(row) * 64;
;                     rope8(a0, a1, tb + (c & 63)); rope8(b0, b1, tb + ((c + 128) & 63));
;                     const float sc = 0.125f * LOG2E;
;                     *(u32x4*)(SWAQK + (size_t)row * 768 + c) = pack8(a0 * sc, a1 * sc); *(u32x4*)(SWAQK + (size_t)row * 768 + c + 128) = pack8(b0 * sc, b1 * sc);
;                 } else {
;                     rope8(a0, a1, TABS + (size_t)tok_pos(row) * 64 + (cw & 63));
;                     *(u32x4*)(SWAQK + (size_t)row * 768 + 512 + cw) = pack8(a0, a1);
;                 }
.LBB0_712:
	s_and_b64 vcc, exec, s[4:5]
	s_mov_b64 s[20:21], -1
	s_cbranch_vccnz .LBB0_722
	s_andn2_b64 vcc, exec, s[26:27]
	s_cbranch_vccnz .LBB0_719
	s_movk_i32 s13, 0x4000
	v_cmp_gt_i32_e32 vcc, s13, v66
	v_mov_b32_e32 v50, 0x1fcf
	v_mov_b32_e32 v51, 0xfcf
	v_cndmask_b32_e32 v50, v50, v51, vcc
	v_and_b32_e32 v50, v50, v66
	v_lshlrev_b32_e32 v50, 8, v50
	v_mov_b32_e32 v51, v1
	v_lshl_add_u64 v[50:51], v[140:141], 0, v[50:51]
	flat_load_dwordx4 v[54:57], v[50:51]
	s_nop 0
	flat_load_dwordx4 v[50:53], v[50:51] offset:16
	s_andn2_b64 vcc, exec, s[16:17]
	s_waitcnt vmcnt(0) lgkmcnt(0)
	v_mov_b32_e32 v78, v57
	v_mov_b32_e32 v86, v53
	v_pk_mul_f32 v[76:77], v[62:63], v[54:55] op_sel:[0,1]
	v_pk_mul_f32 v[84:85], v[72:73], v[50:51] op_sel:[0,1]
	v_pk_mul_f32 v[90:91], v[64:65], v[78:79] op_sel_hi:[1,0]
	v_pk_mul_f32 v[86:87], v[60:61], v[86:87] op_sel_hi:[1,0]
	v_pk_fma_f32 v[80:81], v[62:63], v[54:55], v[76:77] op_sel:[0,0,1] op_sel_hi:[1,0,0] neg_lo:[0,0,1] neg_hi:[0,0,1]
	v_pk_fma_f32 v[82:83], v[62:63], v[54:55], v[76:77] op_sel:[0,0,1] op_sel_hi:[1,0,0]
	v_pk_fma_f32 v[76:77], v[72:73], v[50:51], v[84:85] op_sel:[0,0,1] op_sel_hi:[1,0,0] neg_lo:[0,0,1] neg_hi:[0,0,1]
	v_pk_fma_f32 v[78:79], v[72:73], v[50:51], v[84:85] op_sel:[0,0,1] op_sel_hi:[1,0,0]
	v_pk_fma_f32 v[88:89], v[64:65], v[56:57], v[90:91] op_sel:[0,0,1] op_sel_hi:[1,0,0] neg_lo:[0,0,1] neg_hi:[0,0,1]
	v_pk_fma_f32 v[90:91], v[64:65], v[56:57], v[90:91] op_sel:[0,0,1] op_sel_hi:[1,0,0]
	v_pk_fma_f32 v[84:85], v[60:61], v[52:53], v[86:87] op_sel:[0,0,1] op_sel_hi:[1,0,0] neg_lo:[0,0,1] neg_hi:[0,0,1]
	v_pk_fma_f32 v[86:87], v[60:61], v[52:53], v[86:87] op_sel:[0,0,1] op_sel_hi:[1,0,0]
	s_cbranch_vccnz .LBB0_716
	s_movk_i32 s13, 0x600
	v_cvt_pk_bf16_f32 v92, v80, v83
	v_cvt_pk_bf16_f32 v93, v88, v91
	v_cvt_pk_bf16_f32 v94, v76, v79
	v_cvt_pk_bf16_f32 v95, v84, v87
	v_mad_i64_i32 v[96:97], s[14:15], v66, s13, v[144:145]
	s_mov_b64 s[20:21], 0
	global_store_dwordx4 v[96:97], v[92:95], off offset:1024
.LBB0_716:
	s_andn2_b64 vcc, exec, s[20:21]
	s_cbranch_vccnz .LBB0_718
	v_mov_b32_e32 v92, v54
	v_mov_b32_e32 v93, v54
	v_mov_b32_e32 v54, v55
	v_mov_b32_e32 v94, v56
	v_mov_b32_e32 v95, v56
	v_mov_b32_e32 v56, v57
	v_mov_b32_e32 v96, v50
	v_mov_b32_e32 v97, v50
	v_mov_b32_e32 v50, v51
	v_mov_b32_e32 v98, v52
	v_mov_b32_e32 v99, v52
	v_mov_b32_e32 v52, v53
	v_pk_mul_f32 v[54:55], v[68:69], v[54:55]
	v_pk_mul_f32 v[56:57], v[58:59], v[56:57]
	v_pk_mul_f32 v[50:51], v[74:75], v[50:51]
	v_pk_fma_f32 v[100:101], v[68:69], v[92:93], v[54:55] op_sel:[0,0,1] op_sel_hi:[1,1,0] neg_lo:[0,0,1] neg_hi:[0,0,1]
	v_pk_fma_f32 v[54:55], v[68:69], v[92:93], v[54:55] op_sel:[0,0,1] op_sel_hi:[1,1,0]
	v_pk_fma_f32 v[92:93], v[58:59], v[94:95], v[56:57] op_sel:[0,0,1] op_sel_hi:[1,1,0] neg_lo:[0,0,1] neg_hi:[0,0,1]
	v_pk_fma_f32 v[56:57], v[58:59], v[94:95], v[56:57] op_sel:[0,0,1] op_sel_hi:[1,1,0]
	v_pk_fma_f32 v[94:95], v[74:75], v[96:97], v[50:51] op_sel:[0,0,1] op_sel_hi:[1,1,0] neg_lo:[0,0,1] neg_hi:[0,0,1]
	v_pk_fma_f32 v[96:97], v[74:75], v[96:97], v[50:51] op_sel:[0,0,1] op_sel_hi:[1,1,0]
	v_pk_mul_f32 v[50:51], v[70:71], v[52:53]
	v_mov_b32_e32 v89, v91
	s_mov_b32 s20, 0x3e38aa3b
	v_mov_b32_e32 v81, v83
	v_mov_b32_e32 v77, v79
	v_readlane_b32 s14, v255, 4
	v_pk_fma_f32 v[102:103], v[70:71], v[98:99], v[50:51] op_sel:[0,0,1] op_sel_hi:[1,1,0] neg_lo:[0,0,1] neg_hi:[0,0,1]
	v_pk_fma_f32 v[98:99], v[70:71], v[98:99], v[50:51] op_sel:[0,0,1] op_sel_hi:[1,1,0]
	v_pk_mul_f32 v[52:53], v[88:89], s[20:21] op_sel_hi:[1,0]
	v_pk_mul_f32 v[50:51], v[80:81], s[20:21] op_sel_hi:[1,0]
	v_pk_mul_f32 v[76:77], v[76:77], s[20:21] op_sel_hi:[1,0]
	v_readlane_b32 s15, v255, 5
	v_mov_b32_e32 v85, v87
	v_cvt_pk_bf16_f32 v50, v50, v51
	v_cvt_pk_bf16_f32 v51, v52, v53
	v_cvt_pk_bf16_f32 v52, v76, v77
	v_mov_b64_e32 v[76:77], s[14:15]
	s_movk_i32 s13, 0x600
	v_pk_mul_f32 v[80:81], v[84:85], s[20:21] op_sel_hi:[1,0]
	v_mad_i64_i32 v[76:77], s[14:15], v66, s13, v[76:77]
	v_cvt_pk_bf16_f32 v53, v80, v81
	v_lshl_add_u64 v[76:77], v[0:1], 1, v[76:77]
	v_mov_b32_e32 v93, v57
	v_mov_b32_e32 v101, v55
	v_mov_b32_e32 v103, v99
	v_mov_b32_e32 v95, v97
	global_store_dwordx4 v[76:77], v[50:53], off
	v_pk_mul_f32 v[54:55], v[102:103], s[20:21] op_sel_hi:[1,0]
	v_pk_mul_f32 v[56:57], v[94:95], s[20:21] op_sel_hi:[1,0]
	v_pk_mul_f32 v[52:53], v[92:93], s[20:21] op_sel_hi:[1,0]
	v_pk_mul_f32 v[50:51], v[100:101], s[20:21] op_sel_hi:[1,0]
	s_nop 0
	v_cvt_pk_bf16_f32 v50, v50, v51
	v_cvt_pk_bf16_f32 v51, v52, v53
	v_cvt_pk_bf16_f32 v52, v56, v57
	v_cvt_pk_bf16_f32 v53, v54, v55
	global_store_dwordx4 v[76:77], v[50:53], off offset:256

; __device__ __forceinline__ u32x4 pack8(f32x4 a, f32x4 b) { u32x4 w; w.x = pk2(a[0], a[1]); w.y = pk2(a[2], a[3]); w.z = pk2(b[0], b[1]); w.w = pk2(b[2], b[3]); return w; }
;     __device__ __forceinline__ void operator()(const Acc& acc, const Unit& u, int wr, int wc, int fr, int fq, const RsCtx& rc) const {
;     ...
;                 } else if (pn < 8) {
;                     *(u32x4*)(CONVZ + (size_t)row * 512 + (pn - 4) * 128 + cw) = pack8(a0 * b0, a1 * b1);
.LBB0_719:
	s_andn2_b64 vcc, exec, s[20:21]
	s_cbranch_vccnz .LBB0_721
	v_pk_mul_f32 v[52:53], v[64:65], v[58:59]
	v_pk_mul_f32 v[50:51], v[62:63], v[68:69]
	v_pk_mul_f32 v[54:55], v[60:61], v[70:71]
	v_ashrrev_i32_e32 v67, 31, v66
	v_readlane_b32 s14, v255, 2
	v_cvt_pk_bf16_f32 v50, v50, v51
	v_cvt_pk_bf16_f32 v51, v52, v53
	v_cvt_pk_bf16_f32 v53, v54, v55
	v_lshlrev_b64 v[54:55], 10, v[66:67]
	v_readlane_b32 s15, v255, 3
	v_pk_mul_f32 v[56:57], v[72:73], v[74:75]
	s_lshl_b32 s92, s12, 1
	v_lshl_add_u64 v[54:55], s[14:15], 0, v[54:55]
	v_cvt_pk_bf16_f32 v52, v56, v57
	v_lshl_add_u64 v[54:55], v[54:55], 0, s[92:93]
	v_lshlrev_b32_e32 v56, 1, v138
	v_mov_b32_e32 v57, v1
	v_lshl_add_u64 v[54:55], v[54:55], 0, v[56:57]
	v_add_co_u32_e32 v54, vcc, 0xfffffc00, v54
	s_nop 1
	v_addc_co_u32_e32 v55, vcc, -1, v55, vcc
	global_store_dwordx4 v[54:55], v[50:53], off

; __device__ __forceinline__ u32x4 pack8(f32x4 a, f32x4 b) { u32x4 w; w.x = pk2(a[0], a[1]); w.y = pk2(a[2], a[3]); w.z = pk2(b[0], b[1]); w.w = pk2(b[2], b[3]); return w; }
;     __device__ __forceinline__ void operator()(const Acc& acc, const Unit& u, int wr, int wc, int fr, int fq, const RsCtx& rc) const {
;     ...
;                 } else if (pn < 4) {
;                     bf16_t* p = CONVB + (size_t)row * 512 + (pn - 2) * 256 + cw;
;                     *(u32x4*)p = pack8(a0, a1); *(u32x4*)(p + 128) = pack8(b0, b1);
.LBB0_722:
	s_andn2_b64 vcc, exec, s[20:21]
	s_cbranch_vccnz .LBB0_724
	v_ashrrev_i32_e32 v67, 31, v66
	v_lshlrev_b64 v[50:51], 10, v[66:67]
	v_lshl_add_u64 v[50:51], s[54:55], 0, v[50:51]
	v_lshl_add_u64 v[50:51], s[22:23], 1, v[50:51]
	v_lshlrev_b32_e32 v52, 1, v138
	v_mov_b32_e32 v53, v1
	v_lshl_add_u64 v[54:55], v[50:51], 0, v[52:53]
	v_cvt_pk_bf16_f32 v50, v62, v63
	v_cvt_pk_bf16_f32 v51, v64, v65
	v_cvt_pk_bf16_f32 v52, v72, v73
	v_cvt_pk_bf16_f32 v53, v60, v61
	global_store_dwordx4 v[54:55], v[50:53], off
	s_nop 1
	v_cvt_pk_bf16_f32 v50, v68, v69
	v_cvt_pk_bf16_f32 v51, v58, v59
	v_cvt_pk_bf16_f32 v52, v74, v75
	v_cvt_pk_bf16_f32 v53, v70, v71
	global_store_dwordx4 v[54:55], v[50:53], off offset:256

; __device__ __forceinline__ u32x4 pack8(f32x4 a, f32x4 b) { u32x4 w; w.x = pk2(a[0], a[1]); w.y = pk2(a[2], a[3]); w.z = pk2(b[0], b[1]); w.w = pk2(b[2], b[3]); return w; }
;     __device__ __forceinline__ void operator()(const Acc& acc, const Unit& u, int wr, int wc, int fr, int fq, const RsCtx& rc) const {
;     ...
;             for (int m = 0; m < 4; ++m) { const int row = EPI_ROW(u, ai, wr, m, fr);
;                 const float rs = rc.get(u.pm, ai * 128 + wr * 64 + m * 16 + fr, row);
;                 f32x4 a0 = acc[ai][0][m][0] * rs, a1 = acc[ai][0][m][1] * rs, b0 = acc[ai][1][m][0] * rs, b1 = acc[ai][1][m][1] * rs;
;                 if (pn == 0) {
;                     float s = 0.f;
; #pragma unroll
;                     for (int e = 0; e < 4; ++e) s += a0[e] * a0[e] + a1[e] * a1[e] + b0[e] * b0[e] + b1[e] * b1[e];
;                     s += __shfl_xor(s, 16); s += __shfl_xor(s, 32);
;                     if (fq == 0) ssq_q[row * 4 + wc] = s;
;                     *(u32x4*)(LAT + (size_t)row * 512 + cw) = pack8(a0, a1); *(u32x4*)(LAT + (size_t)row * 512 + 128 + cw) = pack8(b0, b1);
.LBB0_734:
	s_nop 0
	v_mul_f32_e32 v50, v72, v72
	v_mul_f32_e32 v51, v73, v73
	v_fmac_f32_e32 v50, v62, v62
	v_fmac_f32_e32 v51, v63, v63
	v_fmac_f32_e32 v50, v68, v68
	v_fmac_f32_e32 v51, v69, v69
	v_fmac_f32_e32 v50, v74, v74
	v_fmac_f32_e32 v51, v75, v75
	v_add_f32_e32 v50, v50, v51
	v_mul_f32_e32 v51, v60, v60
	v_fmac_f32_e32 v51, v64, v64
	v_fmac_f32_e32 v51, v58, v58
	v_fmac_f32_e32 v51, v70, v70
	v_add_f32_e32 v50, v51, v50
	v_mul_f32_e32 v51, v61, v61
	v_fmac_f32_e32 v51, v65, v65
	v_fmac_f32_e32 v51, v59, v59
	v_fmac_f32_e32 v51, v71, v71
	v_and_b32_e32 v52, 64, v217
	v_add_f32_e32 v50, v51, v50
	v_add_u32_e32 v52, 64, v52
	s_nop 1
	v_mov_b32_e32 v51, v50
	s_nop 1
	v_permlane16_swap_b32_e32 v51, v50
	s_waitcnt lgkmcnt(0)
	v_add_f32_e32 v50, v50, v51
	s_nop 1
	v_mov_b32_e32 v51, v50
	s_nop 1
	v_permlane32_swap_b32_e32 v51, v50
	s_and_saveexec_b64 s[20:21], s[42:43]
	s_cbranch_execz .LBB0_736
	s_waitcnt lgkmcnt(0)
	v_add_f32_e32 v52, v50, v51
	v_lshl_or_b32 v50, v66, 2, s76
	v_readlane_b32 s36, v254, 54
	v_ashrrev_i32_e32 v51, 31, v50
	v_readlane_b32 s37, v254, 55
	v_readlane_b32 s38, v254, 56
	v_readlane_b32 s39, v254, 57
	v_readlane_b32 s36, v254, 44
	v_readlane_b32 s37, v254, 45
	v_lshl_add_u64 v[50:51], v[50:51], 2, s[38:39]
	v_readlane_b32 s38, v254, 48
	v_readlane_b32 s39, v254, 49
	global_store_dword v[50:51], v52, off
.LBB0_736:
	s_or_b64 exec, exec, s[20:21]
	v_ashrrev_i32_e32 v67, 31, v66
	v_lshlrev_b64 v[54:55], 10, v[66:67]
	v_cvt_pk_bf16_f32 v50, v62, v63
	s_waitcnt lgkmcnt(0)
	v_cvt_pk_bf16_f32 v51, v64, v65
	v_cvt_pk_bf16_f32 v52, v72, v73
	v_cvt_pk_bf16_f32 v53, v60, v61
	v_lshl_add_u64 v[54:55], v[142:143], 0, v[54:55]
	global_store_dwordx4 v[54:55], v[50:53], off
	s_nop 1
	v_cvt_pk_bf16_f32 v50, v68, v69
	v_cvt_pk_bf16_f32 v51, v58, v59
	v_cvt_pk_bf16_f32 v52, v74, v75
	v_cvt_pk_bf16_f32 v53, v70, v71
	global_store_dwordx4 v[54:55], v[50:53], off offset:256
	s_nop 1
	v_add_u32_e32 v50, 0x90, v150
	s_and_b64 vcc, exec, s[6:7]
	s_mov_b64 s[20:21], -1
	s_cbranch_vccz .LBB0_726

; __device__ __forceinline__ u32x4 pack8(f32x4 a, f32x4 b) { u32x4 w; w.x = pk2(a[0], a[1]); w.y = pk2(a[2], a[3]); w.z = pk2(b[0], b[1]); w.w = pk2(b[2], b[3]); return w; }
;     __device__ __forceinline__ void operator()(const Acc& acc, const Unit& u, int wr, int wc, int fr, int fq, const RsCtx& rc) const {
;     ...
;                 const float rs = rc.get(u.pm, ai * 128 + wr * 64 + m * 16 + fr, row);
;                 f32x4 a0 = acc[ai][0][m][0] * rs, a1 = acc[ai][0][m][1] * rs, b0 = acc[ai][1][m][0] * rs, b1 = acc[ai][1][m][1] * rs;
;                 if (pn == 0) {
;                     float s = 0.f;
; #pragma unroll
;                     for (int e = 0; e < 4; ++e) s += a0[e] * a0[e] + a1[e] * a1[e] + b0[e] * b0[e] + b1[e] * b1[e];
;                     s += __shfl_xor(s, 16); s += __shfl_xor(s, 32);
;                     if (fq == 0) ssq_q[row * 4 + wc] = s;
;                     *(u32x4*)(LAT + (size_t)row * 512 + cw) = pack8(a0, a1); *(u32x4*)(LAT + (size_t)row * 512 + 128 + cw) = pack8(b0, b1);
;                 } else if (pn == 1) {
;                     float s = 0.f;
; #pragma unroll
;                     for (int e = 0; e < 4; ++e) s += a0[e] * a0[e] + a1[e] * a1[e];
;                     s += __shfl_xor(s, 16); s += __shfl_xor(s, 32);
;                     if (fq == 0) ssq_kv[row * 4 + wc] = s;
;                     *(u32x4*)(LAT + (size_t)row * 512 + 256 + cw) = pack8(a0, a1);
;                     if (wc == 0) { rope8(b0, b1, TABM + ((size_t)tok_pos(row) * 16 + 4 * fq) * 2); *(u32x4*)(LAT + (size_t)row * 512 + 384 + cw) = pack8(b0, b1); }
.LBB0_739:
	s_waitcnt lgkmcnt(0)
	v_pk_mul_f32 v[48:49], v[48:49], v[58:59] op_sel_hi:[1,0]
	v_pk_mul_f32 v[46:47], v[46:47], v[58:59] op_sel_hi:[1,0]
	v_pk_mul_f32 v[44:45], v[44:45], v[58:59] op_sel_hi:[1,0]
	v_pk_mul_f32 v[56:57], v[42:43], v[58:59] op_sel_hi:[1,0]
	v_pk_mul_f32 v[42:43], v[40:41], v[58:59] op_sel_hi:[1,0]
	v_pk_mul_f32 v[52:53], v[38:39], v[58:59] op_sel_hi:[1,0]
	v_pk_mul_f32 v[54:55], v[36:37], v[58:59] op_sel_hi:[1,0]
	v_pk_mul_f32 v[58:59], v[34:35], v[58:59] op_sel_hi:[1,0]
	s_mov_b64 s[28:29], -1
	s_mov_b64 s[20:21], 0
	s_cmp_lt_i32 s82, 1
	s_mov_b64 s[24:25], 0
	s_cbranch_scc1 .LBB0_767
	s_cmp_eq_u32 s82, 1
	s_mov_b64 s[24:25], -1
	s_cbranch_scc0 .LBB0_746
	v_mul_f32_e32 v34, v56, v56
	v_mul_f32_e32 v35, v57, v57
	v_fmac_f32_e32 v34, v46, v46
	v_fmac_f32_e32 v35, v47, v47
	v_add_f32_e32 v34, v34, v35
	v_mul_f32_e32 v35, v44, v44
	v_fmac_f32_e32 v35, v48, v48
	v_add_f32_e32 v34, v35, v34
	v_mul_f32_e32 v35, v45, v45
	v_fmac_f32_e32 v35, v49, v49
	v_and_b32_e32 v36, 64, v217
	v_add_f32_e32 v34, v35, v34
	v_add_u32_e32 v36, 64, v36
	s_nop 1
	v_mov_b32_e32 v35, v34
	s_nop 1
	v_permlane16_swap_b32_e32 v35, v34
	s_waitcnt lgkmcnt(0)
	v_add_f32_e32 v34, v34, v35
	s_nop 1
	v_mov_b32_e32 v35, v34
	s_nop 1
	v_permlane32_swap_b32_e32 v35, v34
	s_and_saveexec_b64 s[24:25], s[42:43]
	s_cbranch_execz .LBB0_743
	s_waitcnt lgkmcnt(0)
	v_add_f32_e32 v36, v34, v35
	v_lshl_or_b32 v34, v50, 2, s76
	v_ashrrev_i32_e32 v35, 31, v34
	v_lshl_add_u64 v[34:35], v[34:35], 2, s[62:63]
	global_store_dword v[34:35], v36, off
.LBB0_743:
	s_or_b64 exec, exec, s[24:25]
	v_ashrrev_i32_e32 v51, 31, v50
	s_waitcnt lgkmcnt(0)
	v_lshlrev_b64 v[34:35], 10, v[50:51]
	v_cvt_pk_bf16_f32 v36, v46, v47
	v_cvt_pk_bf16_f32 v37, v48, v49
	v_cvt_pk_bf16_f32 v38, v56, v57
	v_cvt_pk_bf16_f32 v39, v44, v45
	v_lshl_add_u64 v[34:35], v[142:143], 0, v[34:35]
	s_andn2_b64 vcc, exec, s[48:49]
	global_store_dwordx4 v[34:35], v[36:39], off offset:512
	s_cbranch_vccnz .LBB0_745
	s_movk_i32 s13, 0x4000
	v_cmp_gt_i32_e32 vcc, s13, v50
	v_mov_b32_e32 v36, 0x1fdf
	v_mov_b32_e32 v37, 0xfdf
	v_cndmask_b32_e32 v36, v36, v37, vcc
	v_and_b32_e32 v36, v36, v50
	v_lshlrev_b32_e32 v37, 2, v176
	v_readlane_b32 s14, v254, 58
	v_lshl_or_b32 v36, v36, 7, v37
	v_mov_b32_e32 v37, v1
	v_readlane_b32 s15, v254, 59
	s_nop 1
	v_lshl_add_u64 v[40:41], s[14:15], 0, v[36:37]
	flat_load_dwordx4 v[36:39], v[40:41]
	flat_load_dwordx4 v[60:63], v[40:41] offset:16
	s_waitcnt vmcnt(0) lgkmcnt(0)
	v_pk_mul_f32 v[40:41], v[52:53], v[36:37] op_sel:[1,1] op_sel_hi:[0,1]
	v_pk_fma_f32 v[64:65], v[52:53], v[36:37], v[40:41] neg_lo:[0,0,1] neg_hi:[0,0,1]
	v_pk_fma_f32 v[36:37], v[52:53], v[36:37], v[40:41] op_sel_hi:[1,0,1]
	s_nop 0
	v_mov_b32_e32 v36, v39
	v_pk_mul_f32 v[40:41], v[42:43], v[36:37] op_sel:[1,0] op_sel_hi:[0,0]
	v_pk_fma_f32 v[66:67], v[42:43], v[38:39], v[40:41] neg_lo:[0,0,1] neg_hi:[0,0,1]
	v_pk_fma_f32 v[38:39], v[42:43], v[38:39], v[40:41] op_sel_hi:[1,0,1]
	v_pk_mul_f32 v[40:41], v[58:59], v[60:61] op_sel:[1,1] op_sel_hi:[0,1]
	v_mov_b32_e32 v36, v63
	v_pk_fma_f32 v[68:69], v[58:59], v[60:61], v[40:41] neg_lo:[0,0,1] neg_hi:[0,0,1]
	v_pk_fma_f32 v[40:41], v[58:59], v[60:61], v[40:41] op_sel_hi:[1,0,1]
	v_pk_mul_f32 v[60:61], v[54:55], v[36:37] op_sel:[1,0] op_sel_hi:[0,0]
	v_pk_fma_f32 v[70:71], v[54:55], v[62:63], v[60:61] neg_lo:[0,0,1] neg_hi:[0,0,1]
	v_pk_fma_f32 v[60:61], v[54:55], v[62:63], v[60:61] op_sel_hi:[1,0,1]
	v_cvt_pk_bf16_f32 v36, v64, v37
	v_cvt_pk_bf16_f32 v37, v66, v39
	v_cvt_pk_bf16_f32 v38, v68, v41
	v_cvt_pk_bf16_f32 v39, v70, v61
	global_store_dwordx4 v[34:35], v[36:39], off offset:768

; __device__ __forceinline__ u32x4 pack8(f32x4 a, f32x4 b) { u32x4 w; w.x = pk2(a[0], a[1]); w.y = pk2(a[2], a[3]); w.z = pk2(b[0], b[1]); w.w = pk2(b[2], b[3]); return w; }
;     __device__ __forceinline__ void operator()(const Acc& acc, const Unit& u, int wr, int wc, int fr, int fq, const RsCtx& rc) const {
;     ...
;                 } else if (pn < 10) {
;                     const int c = (pn - 8) * 256 + cw; const float* tb = TABS + (size_t)tok_pos(row) * 64;
;                     rope8(a0, a1, tb + (c & 63)); rope8(b0, b1, tb + ((c + 128) & 63));
;                     const float sc = 0.125f * LOG2E;
;                     *(u32x4*)(SWAQK + (size_t)row * 768 + c) = pack8(a0 * sc, a1 * sc); *(u32x4*)(SWAQK + (size_t)row * 768 + c + 128) = pack8(b0 * sc, b1 * sc);
;                 } else {
;                     rope8(a0, a1, TABS + (size_t)tok_pos(row) * 64 + (cw & 63));
;                     *(u32x4*)(SWAQK + (size_t)row * 768 + 512 + cw) = pack8(a0, a1);
.LBB0_748:
	s_and_b64 vcc, exec, s[4:5]
	s_mov_b64 s[20:21], -1
	s_cbranch_vccnz .LBB0_758
	s_andn2_b64 vcc, exec, s[26:27]
	s_cbranch_vccnz .LBB0_755
	s_movk_i32 s13, 0x4000
	v_cmp_gt_i32_e32 vcc, s13, v50
	v_mov_b32_e32 v34, 0x1fdf
	v_mov_b32_e32 v35, 0xfdf
	v_cndmask_b32_e32 v34, v34, v35, vcc
	v_and_b32_e32 v34, v34, v50
	v_lshlrev_b32_e32 v34, 8, v34
	v_mov_b32_e32 v35, v1
	v_lshl_add_u64 v[34:35], v[140:141], 0, v[34:35]
	flat_load_dwordx4 v[38:41], v[34:35]
	s_nop 0
	flat_load_dwordx4 v[34:37], v[34:35] offset:16
	s_andn2_b64 vcc, exec, s[16:17]
	s_waitcnt vmcnt(0) lgkmcnt(0)
	v_mov_b32_e32 v62, v41
	v_mov_b32_e32 v70, v37
	v_pk_mul_f32 v[60:61], v[46:47], v[38:39] op_sel:[0,1]
	v_pk_mul_f32 v[68:69], v[56:57], v[34:35] op_sel:[0,1]
	v_pk_mul_f32 v[74:75], v[48:49], v[62:63] op_sel_hi:[1,0]
	v_pk_mul_f32 v[70:71], v[44:45], v[70:71] op_sel_hi:[1,0]
	v_pk_fma_f32 v[64:65], v[46:47], v[38:39], v[60:61] op_sel:[0,0,1] op_sel_hi:[1,0,0] neg_lo:[0,0,1] neg_hi:[0,0,1]
	v_pk_fma_f32 v[66:67], v[46:47], v[38:39], v[60:61] op_sel:[0,0,1] op_sel_hi:[1,0,0]
	v_pk_fma_f32 v[60:61], v[56:57], v[34:35], v[68:69] op_sel:[0,0,1] op_sel_hi:[1,0,0] neg_lo:[0,0,1] neg_hi:[0,0,1]
	v_pk_fma_f32 v[62:63], v[56:57], v[34:35], v[68:69] op_sel:[0,0,1] op_sel_hi:[1,0,0]
	v_pk_fma_f32 v[72:73], v[48:49], v[40:41], v[74:75] op_sel:[0,0,1] op_sel_hi:[1,0,0] neg_lo:[0,0,1] neg_hi:[0,0,1]
	v_pk_fma_f32 v[74:75], v[48:49], v[40:41], v[74:75] op_sel:[0,0,1] op_sel_hi:[1,0,0]
	v_pk_fma_f32 v[68:69], v[44:45], v[36:37], v[70:71] op_sel:[0,0,1] op_sel_hi:[1,0,0] neg_lo:[0,0,1] neg_hi:[0,0,1]
	v_pk_fma_f32 v[70:71], v[44:45], v[36:37], v[70:71] op_sel:[0,0,1] op_sel_hi:[1,0,0]
	s_cbranch_vccnz .LBB0_752
	s_movk_i32 s13, 0x600
	v_cvt_pk_bf16_f32 v76, v64, v67
	v_cvt_pk_bf16_f32 v77, v72, v75
	v_cvt_pk_bf16_f32 v78, v60, v63
	v_cvt_pk_bf16_f32 v79, v68, v71
	v_mad_i64_i32 v[80:81], s[14:15], v50, s13, v[144:145]
	s_mov_b64 s[20:21], 0
	global_store_dwordx4 v[80:81], v[76:79], off offset:1024
.LBB0_752:
	s_andn2_b64 vcc, exec, s[20:21]
	s_cbranch_vccnz .LBB0_754
	v_mov_b32_e32 v76, v38
	v_mov_b32_e32 v77, v38
	v_mov_b32_e32 v38, v39
	v_mov_b32_e32 v78, v40
	v_mov_b32_e32 v79, v40
	v_mov_b32_e32 v40, v41
	v_mov_b32_e32 v80, v34
	v_mov_b32_e32 v81, v34
	v_mov_b32_e32 v34, v35
	v_mov_b32_e32 v82, v36
	v_mov_b32_e32 v83, v36
	v_mov_b32_e32 v36, v37
	v_pk_mul_f32 v[38:39], v[52:53], v[38:39]
	v_pk_mul_f32 v[40:41], v[42:43], v[40:41]
	v_pk_mul_f32 v[34:35], v[58:59], v[34:35]
	v_pk_fma_f32 v[84:85], v[52:53], v[76:77], v[38:39] op_sel:[0,0,1] op_sel_hi:[1,1,0] neg_lo:[0,0,1] neg_hi:[0,0,1]
	v_pk_fma_f32 v[38:39], v[52:53], v[76:77], v[38:39] op_sel:[0,0,1] op_sel_hi:[1,1,0]
	v_pk_fma_f32 v[76:77], v[42:43], v[78:79], v[40:41] op_sel:[0,0,1] op_sel_hi:[1,1,0] neg_lo:[0,0,1] neg_hi:[0,0,1]
	v_pk_fma_f32 v[40:41], v[42:43], v[78:79], v[40:41] op_sel:[0,0,1] op_sel_hi:[1,1,0]
	v_pk_fma_f32 v[78:79], v[58:59], v[80:81], v[34:35] op_sel:[0,0,1] op_sel_hi:[1,1,0] neg_lo:[0,0,1] neg_hi:[0,0,1]
	v_pk_fma_f32 v[80:81], v[58:59], v[80:81], v[34:35] op_sel:[0,0,1] op_sel_hi:[1,1,0]
	v_pk_mul_f32 v[34:35], v[54:55], v[36:37]
	v_mov_b32_e32 v73, v75
	s_mov_b32 s20, 0x3e38aa3b
	v_mov_b32_e32 v65, v67
	v_mov_b32_e32 v61, v63
	v_readlane_b32 s14, v255, 4
	v_pk_fma_f32 v[86:87], v[54:55], v[82:83], v[34:35] op_sel:[0,0,1] op_sel_hi:[1,1,0] neg_lo:[0,0,1] neg_hi:[0,0,1]
	v_pk_fma_f32 v[82:83], v[54:55], v[82:83], v[34:35] op_sel:[0,0,1] op_sel_hi:[1,1,0]
	v_pk_mul_f32 v[36:37], v[72:73], s[20:21] op_sel_hi:[1,0]
	v_pk_mul_f32 v[34:35], v[64:65], s[20:21] op_sel_hi:[1,0]
	v_pk_mul_f32 v[60:61], v[60:61], s[20:21] op_sel_hi:[1,0]
	v_readlane_b32 s15, v255, 5
	v_mov_b32_e32 v69, v71
	v_cvt_pk_bf16_f32 v34, v34, v35
	v_cvt_pk_bf16_f32 v35, v36, v37
	v_cvt_pk_bf16_f32 v36, v60, v61
	v_mov_b64_e32 v[60:61], s[14:15]
	s_movk_i32 s13, 0x600
	v_pk_mul_f32 v[64:65], v[68:69], s[20:21] op_sel_hi:[1,0]
	v_mad_i64_i32 v[60:61], s[14:15], v50, s13, v[60:61]
	v_cvt_pk_bf16_f32 v37, v64, v65
	v_lshl_add_u64 v[60:61], v[0:1], 1, v[60:61]
	v_mov_b32_e32 v77, v41
	v_mov_b32_e32 v85, v39
	v_mov_b32_e32 v87, v83
	v_mov_b32_e32 v79, v81
	global_store_dwordx4 v[60:61], v[34:37], off
	v_pk_mul_f32 v[38:39], v[86:87], s[20:21] op_sel_hi:[1,0]
	v_pk_mul_f32 v[40:41], v[78:79], s[20:21] op_sel_hi:[1,0]
	v_pk_mul_f32 v[36:37], v[76:77], s[20:21] op_sel_hi:[1,0]
	v_pk_mul_f32 v[34:35], v[84:85], s[20:21] op_sel_hi:[1,0]
	s_nop 0
	v_cvt_pk_bf16_f32 v34, v34, v35
	v_cvt_pk_bf16_f32 v35, v36, v37
	v_cvt_pk_bf16_f32 v36, v40, v41
	v_cvt_pk_bf16_f32 v37, v38, v39
	global_store_dwordx4 v[60:61], v[34:37], off offset:256

; __device__ __forceinline__ u32x4 pack8(f32x4 a, f32x4 b) { u32x4 w; w.x = pk2(a[0], a[1]); w.y = pk2(a[2], a[3]); w.z = pk2(b[0], b[1]); w.w = pk2(b[2], b[3]); return w; }
;     __device__ __forceinline__ void operator()(const Acc& acc, const Unit& u, int wr, int wc, int fr, int fq, const RsCtx& rc) const {
;     ...
;                 } else if (pn < 8) {
;                     *(u32x4*)(CONVZ + (size_t)row * 512 + (pn - 4) * 128 + cw) = pack8(a0 * b0, a1 * b1);
.LBB0_755:
	s_andn2_b64 vcc, exec, s[20:21]
	s_cbranch_vccnz .LBB0_757
	v_pk_mul_f32 v[36:37], v[48:49], v[42:43]
	v_pk_mul_f32 v[34:35], v[46:47], v[52:53]
	v_pk_mul_f32 v[38:39], v[44:45], v[54:55]
	v_ashrrev_i32_e32 v51, 31, v50
	v_readlane_b32 s14, v255, 2
	v_cvt_pk_bf16_f32 v34, v34, v35
	v_cvt_pk_bf16_f32 v35, v36, v37
	v_cvt_pk_bf16_f32 v37, v38, v39
	v_lshlrev_b64 v[38:39], 10, v[50:51]
	v_readlane_b32 s15, v255, 3
	v_pk_mul_f32 v[40:41], v[56:57], v[58:59]
	s_lshl_b32 s92, s12, 1
	v_lshl_add_u64 v[38:39], s[14:15], 0, v[38:39]
	v_cvt_pk_bf16_f32 v36, v40, v41
	v_lshl_add_u64 v[38:39], v[38:39], 0, s[92:93]
	v_lshlrev_b32_e32 v40, 1, v138
	v_mov_b32_e32 v41, v1
	v_lshl_add_u64 v[38:39], v[38:39], 0, v[40:41]
	v_add_co_u32_e32 v38, vcc, 0xfffffc00, v38
	s_nop 1
	v_addc_co_u32_e32 v39, vcc, -1, v39, vcc
	global_store_dwordx4 v[38:39], v[34:37], off

; __device__ __forceinline__ u32x4 pack8(f32x4 a, f32x4 b) { u32x4 w; w.x = pk2(a[0], a[1]); w.y = pk2(a[2], a[3]); w.z = pk2(b[0], b[1]); w.w = pk2(b[2], b[3]); return w; }
;     __device__ __forceinline__ void operator()(const Acc& acc, const Unit& u, int wr, int wc, int fr, int fq, const RsCtx& rc) const {
;     ...
;                 } else if (pn < 4) {
;                     bf16_t* p = CONVB + (size_t)row * 512 + (pn - 2) * 256 + cw;
;                     *(u32x4*)p = pack8(a0, a1); *(u32x4*)(p + 128) = pack8(b0, b1);
.LBB0_758:
	s_andn2_b64 vcc, exec, s[20:21]
	s_cbranch_vccnz .LBB0_760
	v_ashrrev_i32_e32 v51, 31, v50
	v_lshlrev_b64 v[34:35], 10, v[50:51]
	v_lshl_add_u64 v[34:35], s[54:55], 0, v[34:35]
	v_lshl_add_u64 v[34:35], s[22:23], 1, v[34:35]
	v_lshlrev_b32_e32 v36, 1, v138
	v_mov_b32_e32 v37, v1
	v_lshl_add_u64 v[38:39], v[34:35], 0, v[36:37]
	v_cvt_pk_bf16_f32 v34, v46, v47
	v_cvt_pk_bf16_f32 v35, v48, v49
	v_cvt_pk_bf16_f32 v36, v56, v57
	v_cvt_pk_bf16_f32 v37, v44, v45
	global_store_dwordx4 v[38:39], v[34:37], off
	s_nop 1
	v_cvt_pk_bf16_f32 v34, v52, v53
	v_cvt_pk_bf16_f32 v35, v42, v43
	v_cvt_pk_bf16_f32 v36, v58, v59
	v_cvt_pk_bf16_f32 v37, v54, v55
	global_store_dwordx4 v[38:39], v[34:37], off offset:256

; __device__ __forceinline__ u32x4 pack8(f32x4 a, f32x4 b) { u32x4 w; w.x = pk2(a[0], a[1]); w.y = pk2(a[2], a[3]); w.z = pk2(b[0], b[1]); w.w = pk2(b[2], b[3]); return w; }
;     __device__ __forceinline__ void operator()(const Acc& acc, const Unit& u, int wr, int wc, int fr, int fq, const RsCtx& rc) const {
;     ...
;                 if (pn == 0) {
;                     float s = 0.f;
; #pragma unroll
;                     for (int e = 0; e < 4; ++e) s += a0[e] * a0[e] + a1[e] * a1[e] + b0[e] * b0[e] + b1[e] * b1[e];
;                     s += __shfl_xor(s, 16); s += __shfl_xor(s, 32);
;                     if (fq == 0) ssq_q[row * 4 + wc] = s;
;                     *(u32x4*)(LAT + (size_t)row * 512 + cw) = pack8(a0, a1); *(u32x4*)(LAT + (size_t)row * 512 + 128 + cw) = pack8(b0, b1);
.LBB0_770:
	s_nop 0
	v_mul_f32_e32 v34, v56, v56
	v_mul_f32_e32 v35, v57, v57
	v_fmac_f32_e32 v34, v46, v46
	v_fmac_f32_e32 v35, v47, v47
	v_fmac_f32_e32 v34, v52, v52
	v_fmac_f32_e32 v35, v53, v53
	v_fmac_f32_e32 v34, v58, v58
	v_fmac_f32_e32 v35, v59, v59
	v_add_f32_e32 v34, v34, v35
	v_mul_f32_e32 v35, v44, v44
	v_fmac_f32_e32 v35, v48, v48
	v_fmac_f32_e32 v35, v42, v42
	v_fmac_f32_e32 v35, v54, v54
	v_add_f32_e32 v34, v35, v34
	v_mul_f32_e32 v35, v45, v45
	v_fmac_f32_e32 v35, v49, v49
	v_fmac_f32_e32 v35, v43, v43
	v_fmac_f32_e32 v35, v55, v55
	v_and_b32_e32 v36, 64, v217
	v_add_f32_e32 v34, v35, v34
	v_add_u32_e32 v36, 64, v36
	s_nop 1
	v_mov_b32_e32 v35, v34
	s_nop 1
	v_permlane16_swap_b32_e32 v35, v34
	s_waitcnt lgkmcnt(0)
	v_add_f32_e32 v34, v34, v35
	s_nop 1
	v_mov_b32_e32 v35, v34
	s_nop 1
	v_permlane32_swap_b32_e32 v35, v34
	s_and_saveexec_b64 s[20:21], s[42:43]
	s_cbranch_execz .LBB0_772
	s_waitcnt lgkmcnt(0)
	v_add_f32_e32 v36, v34, v35
	v_lshl_or_b32 v34, v50, 2, s76
	v_readlane_b32 s36, v254, 54
	v_ashrrev_i32_e32 v35, 31, v34
	v_readlane_b32 s37, v254, 55
	v_readlane_b32 s38, v254, 56
	v_readlane_b32 s39, v254, 57
	v_readlane_b32 s36, v254, 44
	v_readlane_b32 s37, v254, 45
	v_lshl_add_u64 v[34:35], v[34:35], 2, s[38:39]
	v_readlane_b32 s38, v254, 48
	v_readlane_b32 s39, v254, 49
	global_store_dword v[34:35], v36, off
.LBB0_772:
	s_or_b64 exec, exec, s[20:21]
	v_ashrrev_i32_e32 v51, 31, v50
	v_lshlrev_b64 v[38:39], 10, v[50:51]
	v_cvt_pk_bf16_f32 v34, v46, v47
	s_waitcnt lgkmcnt(0)
	v_cvt_pk_bf16_f32 v35, v48, v49
	v_cvt_pk_bf16_f32 v36, v56, v57
	v_cvt_pk_bf16_f32 v37, v44, v45
	v_lshl_add_u64 v[38:39], v[142:143], 0, v[38:39]
	global_store_dwordx4 v[38:39], v[34:37], off
	s_nop 1
	v_cvt_pk_bf16_f32 v34, v52, v53
	v_cvt_pk_bf16_f32 v35, v42, v43
	v_cvt_pk_bf16_f32 v36, v58, v59
	v_cvt_pk_bf16_f32 v37, v54, v55
	global_store_dwordx4 v[38:39], v[34:37], off offset:256
	s_nop 1
	v_add_u32_e32 v34, 0xa0, v150
	s_and_b64 vcc, exec, s[6:7]
	s_mov_b64 s[20:21], -1
	s_cbranch_vccz .LBB0_762

; __device__ __forceinline__ u32x4 pack8(f32x4 a, f32x4 b) { u32x4 w; w.x = pk2(a[0], a[1]); w.y = pk2(a[2], a[3]); w.z = pk2(b[0], b[1]); w.w = pk2(b[2], b[3]); return w; }
;     __device__ __forceinline__ void operator()(const Acc& acc, const Unit& u, int wr, int wc, int fr, int fq, const RsCtx& rc) const {
;     ...
;                 const float rs = rc.get(u.pm, ai * 128 + wr * 64 + m * 16 + fr, row);
;                 f32x4 a0 = acc[ai][0][m][0] * rs, a1 = acc[ai][0][m][1] * rs, b0 = acc[ai][1][m][0] * rs, b1 = acc[ai][1][m][1] * rs;
;                 if (pn == 0) {
;                     float s = 0.f;
; #pragma unroll
;                     for (int e = 0; e < 4; ++e) s += a0[e] * a0[e] + a1[e] * a1[e] + b0[e] * b0[e] + b1[e] * b1[e];
;                     s += __shfl_xor(s, 16); s += __shfl_xor(s, 32);
;                     if (fq == 0) ssq_q[row * 4 + wc] = s;
;                     *(u32x4*)(LAT + (size_t)row * 512 + cw) = pack8(a0, a1); *(u32x4*)(LAT + (size_t)row * 512 + 128 + cw) = pack8(b0, b1);
;                 } else if (pn == 1) {
;                     float s = 0.f;
; #pragma unroll
;                     for (int e = 0; e < 4; ++e) s += a0[e] * a0[e] + a1[e] * a1[e];
;                     s += __shfl_xor(s, 16); s += __shfl_xor(s, 32);
;                     if (fq == 0) ssq_kv[row * 4 + wc] = s;
;                     *(u32x4*)(LAT + (size_t)row * 512 + 256 + cw) = pack8(a0, a1);
;                     if (wc == 0) { rope8(b0, b1, TABM + ((size_t)tok_pos(row) * 16 + 4 * fq) * 2); *(u32x4*)(LAT + (size_t)row * 512 + 384 + cw) = pack8(b0, b1); }
.LBB0_775:
	s_waitcnt lgkmcnt(0)
	v_pk_mul_f32 v[32:33], v[32:33], v[42:43] op_sel_hi:[1,0]
	v_pk_mul_f32 v[30:31], v[30:31], v[42:43] op_sel_hi:[1,0]
	v_pk_mul_f32 v[28:29], v[28:29], v[42:43] op_sel_hi:[1,0]
	v_pk_mul_f32 v[40:41], v[26:27], v[42:43] op_sel_hi:[1,0]
	v_pk_mul_f32 v[26:27], v[24:25], v[42:43] op_sel_hi:[1,0]
	v_pk_mul_f32 v[36:37], v[22:23], v[42:43] op_sel_hi:[1,0]
	v_pk_mul_f32 v[38:39], v[20:21], v[42:43] op_sel_hi:[1,0]
	v_pk_mul_f32 v[42:43], v[18:19], v[42:43] op_sel_hi:[1,0]
	s_mov_b64 s[28:29], -1
	s_mov_b64 s[20:21], 0
	s_cmp_lt_i32 s82, 1
	s_mov_b64 s[24:25], 0
	s_cbranch_scc1 .LBB0_803
	s_cmp_eq_u32 s82, 1
	s_mov_b64 s[24:25], -1
	s_cbranch_scc0 .LBB0_782
	v_mul_f32_e32 v18, v40, v40
	v_mul_f32_e32 v19, v41, v41
	v_fmac_f32_e32 v18, v30, v30
	v_fmac_f32_e32 v19, v31, v31
	v_add_f32_e32 v18, v18, v19
	v_mul_f32_e32 v19, v28, v28
	v_fmac_f32_e32 v19, v32, v32
	v_add_f32_e32 v18, v19, v18
	v_mul_f32_e32 v19, v29, v29
	v_fmac_f32_e32 v19, v33, v33
	v_and_b32_e32 v20, 64, v217
	v_add_f32_e32 v18, v19, v18
	v_add_u32_e32 v20, 64, v20
	s_nop 1
	v_mov_b32_e32 v19, v18
	s_nop 1
	v_permlane16_swap_b32_e32 v19, v18
	s_waitcnt lgkmcnt(0)
	v_add_f32_e32 v18, v18, v19
	s_nop 1
	v_mov_b32_e32 v19, v18
	s_nop 1
	v_permlane32_swap_b32_e32 v19, v18
	s_and_saveexec_b64 s[24:25], s[42:43]
	s_cbranch_execz .LBB0_779
	s_waitcnt lgkmcnt(0)
	v_add_f32_e32 v20, v18, v19
	v_lshl_or_b32 v18, v34, 2, s76
	v_ashrrev_i32_e32 v19, 31, v18
	v_lshl_add_u64 v[18:19], v[18:19], 2, s[62:63]
	global_store_dword v[18:19], v20, off
.LBB0_779:
	s_or_b64 exec, exec, s[24:25]
	v_ashrrev_i32_e32 v35, 31, v34
	s_waitcnt lgkmcnt(0)
	v_lshlrev_b64 v[18:19], 10, v[34:35]
	v_cvt_pk_bf16_f32 v20, v30, v31
	v_cvt_pk_bf16_f32 v21, v32, v33
	v_cvt_pk_bf16_f32 v22, v40, v41
	v_cvt_pk_bf16_f32 v23, v28, v29
	v_lshl_add_u64 v[18:19], v[142:143], 0, v[18:19]
	s_andn2_b64 vcc, exec, s[48:49]
	global_store_dwordx4 v[18:19], v[20:23], off offset:512
	s_cbranch_vccnz .LBB0_781
	s_movk_i32 s13, 0x4000
	v_cmp_gt_i32_e32 vcc, s13, v34
	v_mov_b32_e32 v20, 0x1fef
	v_mov_b32_e32 v21, 0xfef
	v_cndmask_b32_e32 v20, v20, v21, vcc
	v_and_b32_e32 v20, v20, v34
	v_lshlrev_b32_e32 v21, 2, v176
	v_readlane_b32 s14, v254, 58
	v_lshl_or_b32 v20, v20, 7, v21
	v_mov_b32_e32 v21, v1
	v_readlane_b32 s15, v254, 59
	s_nop 1
	v_lshl_add_u64 v[24:25], s[14:15], 0, v[20:21]
	flat_load_dwordx4 v[20:23], v[24:25]
	flat_load_dwordx4 v[44:47], v[24:25] offset:16
	s_waitcnt vmcnt(0) lgkmcnt(0)
	v_pk_mul_f32 v[24:25], v[36:37], v[20:21] op_sel:[1,1] op_sel_hi:[0,1]
	v_pk_fma_f32 v[48:49], v[36:37], v[20:21], v[24:25] neg_lo:[0,0,1] neg_hi:[0,0,1]
	v_pk_fma_f32 v[20:21], v[36:37], v[20:21], v[24:25] op_sel_hi:[1,0,1]
	s_nop 0
	v_mov_b32_e32 v20, v23
	v_pk_mul_f32 v[24:25], v[26:27], v[20:21] op_sel:[1,0] op_sel_hi:[0,0]
	v_pk_fma_f32 v[50:51], v[26:27], v[22:23], v[24:25] neg_lo:[0,0,1] neg_hi:[0,0,1]
	v_pk_fma_f32 v[22:23], v[26:27], v[22:23], v[24:25] op_sel_hi:[1,0,1]
	v_pk_mul_f32 v[24:25], v[42:43], v[44:45] op_sel:[1,1] op_sel_hi:[0,1]
	v_mov_b32_e32 v20, v47
	v_pk_fma_f32 v[52:53], v[42:43], v[44:45], v[24:25] neg_lo:[0,0,1] neg_hi:[0,0,1]
	v_pk_fma_f32 v[24:25], v[42:43], v[44:45], v[24:25] op_sel_hi:[1,0,1]
	v_pk_mul_f32 v[44:45], v[38:39], v[20:21] op_sel:[1,0] op_sel_hi:[0,0]
	v_pk_fma_f32 v[54:55], v[38:39], v[46:47], v[44:45] neg_lo:[0,0,1] neg_hi:[0,0,1]
	v_pk_fma_f32 v[44:45], v[38:39], v[46:47], v[44:45] op_sel_hi:[1,0,1]
	v_cvt_pk_bf16_f32 v20, v48, v21
	v_cvt_pk_bf16_f32 v21, v50, v23
	v_cvt_pk_bf16_f32 v22, v52, v25
	v_cvt_pk_bf16_f32 v23, v54, v45
	global_store_dwordx4 v[18:19], v[20:23], off offset:768

; __device__ __forceinline__ u32x4 pack8(f32x4 a, f32x4 b) { u32x4 w; w.x = pk2(a[0], a[1]); w.y = pk2(a[2], a[3]); w.z = pk2(b[0], b[1]); w.w = pk2(b[2], b[3]); return w; }
;     __device__ __forceinline__ void operator()(const Acc& acc, const Unit& u, int wr, int wc, int fr, int fq, const RsCtx& rc) const {
;     ...
;                 } else if (pn < 10) {
;                     const int c = (pn - 8) * 256 + cw; const float* tb = TABS + (size_t)tok_pos(row) * 64;
;                     rope8(a0, a1, tb + (c & 63)); rope8(b0, b1, tb + ((c + 128) & 63));
;                     const float sc = 0.125f * LOG2E;
;                     *(u32x4*)(SWAQK + (size_t)row * 768 + c) = pack8(a0 * sc, a1 * sc); *(u32x4*)(SWAQK + (size_t)row * 768 + c + 128) = pack8(b0 * sc, b1 * sc);
;                 } else {
;                     rope8(a0, a1, TABS + (size_t)tok_pos(row) * 64 + (cw & 63));
;                     *(u32x4*)(SWAQK + (size_t)row * 768 + 512 + cw) = pack8(a0, a1);
.LBB0_784:
	s_and_b64 vcc, exec, s[4:5]
	s_mov_b64 s[20:21], -1
	s_cbranch_vccnz .LBB0_794
	s_andn2_b64 vcc, exec, s[26:27]
	s_cbranch_vccnz .LBB0_791
	s_movk_i32 s13, 0x4000
	v_cmp_gt_i32_e32 vcc, s13, v34
	v_mov_b32_e32 v18, 0x1fef
	v_mov_b32_e32 v19, 0xfef
	v_cndmask_b32_e32 v18, v18, v19, vcc
	v_and_b32_e32 v18, v18, v34
	v_lshlrev_b32_e32 v18, 8, v18
	v_mov_b32_e32 v19, v1
	v_lshl_add_u64 v[18:19], v[140:141], 0, v[18:19]
	flat_load_dwordx4 v[22:25], v[18:19]
	s_nop 0
	flat_load_dwordx4 v[18:21], v[18:19] offset:16
	s_andn2_b64 vcc, exec, s[16:17]
	s_waitcnt vmcnt(0) lgkmcnt(0)
	v_mov_b32_e32 v46, v25
	v_mov_b32_e32 v54, v21
	v_pk_mul_f32 v[44:45], v[30:31], v[22:23] op_sel:[0,1]
	v_pk_mul_f32 v[52:53], v[40:41], v[18:19] op_sel:[0,1]
	v_pk_mul_f32 v[58:59], v[32:33], v[46:47] op_sel_hi:[1,0]
	v_pk_mul_f32 v[54:55], v[28:29], v[54:55] op_sel_hi:[1,0]
	v_pk_fma_f32 v[48:49], v[30:31], v[22:23], v[44:45] op_sel:[0,0,1] op_sel_hi:[1,0,0] neg_lo:[0,0,1] neg_hi:[0,0,1]
	v_pk_fma_f32 v[50:51], v[30:31], v[22:23], v[44:45] op_sel:[0,0,1] op_sel_hi:[1,0,0]
	v_pk_fma_f32 v[44:45], v[40:41], v[18:19], v[52:53] op_sel:[0,0,1] op_sel_hi:[1,0,0] neg_lo:[0,0,1] neg_hi:[0,0,1]
	v_pk_fma_f32 v[46:47], v[40:41], v[18:19], v[52:53] op_sel:[0,0,1] op_sel_hi:[1,0,0]
	v_pk_fma_f32 v[56:57], v[32:33], v[24:25], v[58:59] op_sel:[0,0,1] op_sel_hi:[1,0,0] neg_lo:[0,0,1] neg_hi:[0,0,1]
	v_pk_fma_f32 v[58:59], v[32:33], v[24:25], v[58:59] op_sel:[0,0,1] op_sel_hi:[1,0,0]
	v_pk_fma_f32 v[52:53], v[28:29], v[20:21], v[54:55] op_sel:[0,0,1] op_sel_hi:[1,0,0] neg_lo:[0,0,1] neg_hi:[0,0,1]
	v_pk_fma_f32 v[54:55], v[28:29], v[20:21], v[54:55] op_sel:[0,0,1] op_sel_hi:[1,0,0]
	s_cbranch_vccnz .LBB0_788
	s_movk_i32 s13, 0x600
	v_cvt_pk_bf16_f32 v60, v48, v51
	v_cvt_pk_bf16_f32 v61, v56, v59
	v_cvt_pk_bf16_f32 v62, v44, v47
	v_cvt_pk_bf16_f32 v63, v52, v55
	v_mad_i64_i32 v[64:65], s[14:15], v34, s13, v[144:145]
	s_mov_b64 s[20:21], 0
	global_store_dwordx4 v[64:65], v[60:63], off offset:1024
.LBB0_788:
	s_andn2_b64 vcc, exec, s[20:21]
	s_cbranch_vccnz .LBB0_790
	v_mov_b32_e32 v60, v22
	v_mov_b32_e32 v61, v22
	v_mov_b32_e32 v22, v23
	v_mov_b32_e32 v62, v24
	v_mov_b32_e32 v63, v24
	v_mov_b32_e32 v24, v25
	v_mov_b32_e32 v64, v18
	v_mov_b32_e32 v65, v18
	v_mov_b32_e32 v18, v19
	v_mov_b32_e32 v66, v20
	v_mov_b32_e32 v67, v20
	v_mov_b32_e32 v20, v21
	v_pk_mul_f32 v[22:23], v[36:37], v[22:23]
	v_pk_mul_f32 v[24:25], v[26:27], v[24:25]
	v_pk_mul_f32 v[18:19], v[42:43], v[18:19]
	v_pk_fma_f32 v[68:69], v[36:37], v[60:61], v[22:23] op_sel:[0,0,1] op_sel_hi:[1,1,0] neg_lo:[0,0,1] neg_hi:[0,0,1]
	v_pk_fma_f32 v[22:23], v[36:37], v[60:61], v[22:23] op_sel:[0,0,1] op_sel_hi:[1,1,0]
	v_pk_fma_f32 v[60:61], v[26:27], v[62:63], v[24:25] op_sel:[0,0,1] op_sel_hi:[1,1,0] neg_lo:[0,0,1] neg_hi:[0,0,1]
	v_pk_fma_f32 v[24:25], v[26:27], v[62:63], v[24:25] op_sel:[0,0,1] op_sel_hi:[1,1,0]
	v_pk_fma_f32 v[62:63], v[42:43], v[64:65], v[18:19] op_sel:[0,0,1] op_sel_hi:[1,1,0] neg_lo:[0,0,1] neg_hi:[0,0,1]
	v_pk_fma_f32 v[64:65], v[42:43], v[64:65], v[18:19] op_sel:[0,0,1] op_sel_hi:[1,1,0]
	v_pk_mul_f32 v[18:19], v[38:39], v[20:21]
	v_mov_b32_e32 v57, v59
	s_mov_b32 s20, 0x3e38aa3b
	v_mov_b32_e32 v49, v51
	v_mov_b32_e32 v45, v47
	v_readlane_b32 s14, v255, 4
	v_pk_fma_f32 v[70:71], v[38:39], v[66:67], v[18:19] op_sel:[0,0,1] op_sel_hi:[1,1,0] neg_lo:[0,0,1] neg_hi:[0,0,1]
	v_pk_fma_f32 v[66:67], v[38:39], v[66:67], v[18:19] op_sel:[0,0,1] op_sel_hi:[1,1,0]
	v_pk_mul_f32 v[20:21], v[56:57], s[20:21] op_sel_hi:[1,0]
	v_pk_mul_f32 v[18:19], v[48:49], s[20:21] op_sel_hi:[1,0]
	v_pk_mul_f32 v[44:45], v[44:45], s[20:21] op_sel_hi:[1,0]
	v_readlane_b32 s15, v255, 5
	v_mov_b32_e32 v53, v55
	v_cvt_pk_bf16_f32 v18, v18, v19
	v_cvt_pk_bf16_f32 v19, v20, v21
	v_cvt_pk_bf16_f32 v20, v44, v45
	v_mov_b64_e32 v[44:45], s[14:15]
	s_movk_i32 s13, 0x600
	v_pk_mul_f32 v[48:49], v[52:53], s[20:21] op_sel_hi:[1,0]
	v_mad_i64_i32 v[44:45], s[14:15], v34, s13, v[44:45]
	v_cvt_pk_bf16_f32 v21, v48, v49
	v_lshl_add_u64 v[44:45], v[0:1], 1, v[44:45]
	v_mov_b32_e32 v61, v25
	v_mov_b32_e32 v69, v23
	v_mov_b32_e32 v71, v67
	v_mov_b32_e32 v63, v65
	global_store_dwordx4 v[44:45], v[18:21], off
	v_pk_mul_f32 v[22:23], v[70:71], s[20:21] op_sel_hi:[1,0]
	v_pk_mul_f32 v[24:25], v[62:63], s[20:21] op_sel_hi:[1,0]
	v_pk_mul_f32 v[20:21], v[60:61], s[20:21] op_sel_hi:[1,0]
	v_pk_mul_f32 v[18:19], v[68:69], s[20:21] op_sel_hi:[1,0]
	s_nop 0
	v_cvt_pk_bf16_f32 v18, v18, v19
	v_cvt_pk_bf16_f32 v19, v20, v21
	v_cvt_pk_bf16_f32 v20, v24, v25
	v_cvt_pk_bf16_f32 v21, v22, v23
	global_store_dwordx4 v[44:45], v[18:21], off offset:256

; __device__ __forceinline__ u32x4 pack8(f32x4 a, f32x4 b) { u32x4 w; w.x = pk2(a[0], a[1]); w.y = pk2(a[2], a[3]); w.z = pk2(b[0], b[1]); w.w = pk2(b[2], b[3]); return w; }
;     __device__ __forceinline__ void operator()(const Acc& acc, const Unit& u, int wr, int wc, int fr, int fq, const RsCtx& rc) const {
;     ...
;                 } else if (pn < 8) {
;                     *(u32x4*)(CONVZ + (size_t)row * 512 + (pn - 4) * 128 + cw) = pack8(a0 * b0, a1 * b1);
.LBB0_791:
	s_andn2_b64 vcc, exec, s[20:21]
	s_cbranch_vccnz .LBB0_793
	v_pk_mul_f32 v[20:21], v[32:33], v[26:27]
	v_pk_mul_f32 v[18:19], v[30:31], v[36:37]
	v_pk_mul_f32 v[22:23], v[28:29], v[38:39]
	v_ashrrev_i32_e32 v35, 31, v34
	v_readlane_b32 s14, v255, 2
	v_cvt_pk_bf16_f32 v18, v18, v19
	v_cvt_pk_bf16_f32 v19, v20, v21
	v_cvt_pk_bf16_f32 v21, v22, v23
	v_lshlrev_b64 v[22:23], 10, v[34:35]
	v_readlane_b32 s15, v255, 3
	v_pk_mul_f32 v[24:25], v[40:41], v[42:43]
	s_lshl_b32 s92, s12, 1
	v_lshl_add_u64 v[22:23], s[14:15], 0, v[22:23]
	v_cvt_pk_bf16_f32 v20, v24, v25
	v_lshl_add_u64 v[22:23], v[22:23], 0, s[92:93]
	v_lshlrev_b32_e32 v24, 1, v138
	v_mov_b32_e32 v25, v1
	v_lshl_add_u64 v[22:23], v[22:23], 0, v[24:25]
	v_add_co_u32_e32 v22, vcc, 0xfffffc00, v22
	s_nop 1
	v_addc_co_u32_e32 v23, vcc, -1, v23, vcc
	global_store_dwordx4 v[22:23], v[18:21], off

; __device__ __forceinline__ u32x4 pack8(f32x4 a, f32x4 b) { u32x4 w; w.x = pk2(a[0], a[1]); w.y = pk2(a[2], a[3]); w.z = pk2(b[0], b[1]); w.w = pk2(b[2], b[3]); return w; }
;     __device__ __forceinline__ void operator()(const Acc& acc, const Unit& u, int wr, int wc, int fr, int fq, const RsCtx& rc) const {
;     ...
;                 } else if (pn < 4) {
;                     bf16_t* p = CONVB + (size_t)row * 512 + (pn - 2) * 256 + cw;
;                     *(u32x4*)p = pack8(a0, a1); *(u32x4*)(p + 128) = pack8(b0, b1);
.LBB0_794:
	s_andn2_b64 vcc, exec, s[20:21]
	s_cbranch_vccnz .LBB0_796
	v_ashrrev_i32_e32 v35, 31, v34
	v_lshlrev_b64 v[18:19], 10, v[34:35]
	v_lshl_add_u64 v[18:19], s[54:55], 0, v[18:19]
	v_lshl_add_u64 v[18:19], s[22:23], 1, v[18:19]
	v_lshlrev_b32_e32 v20, 1, v138
	v_mov_b32_e32 v21, v1
	v_lshl_add_u64 v[22:23], v[18:19], 0, v[20:21]
	v_cvt_pk_bf16_f32 v18, v30, v31
	v_cvt_pk_bf16_f32 v19, v32, v33
	v_cvt_pk_bf16_f32 v20, v40, v41
	v_cvt_pk_bf16_f32 v21, v28, v29
	global_store_dwordx4 v[22:23], v[18:21], off
	s_nop 1
	v_cvt_pk_bf16_f32 v18, v36, v37
	v_cvt_pk_bf16_f32 v19, v26, v27
	v_cvt_pk_bf16_f32 v20, v42, v43
	v_cvt_pk_bf16_f32 v21, v38, v39
	global_store_dwordx4 v[22:23], v[18:21], off offset:256

; __device__ __forceinline__ u32x4 pack8(f32x4 a, f32x4 b) { u32x4 w; w.x = pk2(a[0], a[1]); w.y = pk2(a[2], a[3]); w.z = pk2(b[0], b[1]); w.w = pk2(b[2], b[3]); return w; }
;     __device__ __forceinline__ void operator()(const Acc& acc, const Unit& u, int wr, int wc, int fr, int fq, const RsCtx& rc) const {
;     ...
;                 if (pn == 0) {
;                     float s = 0.f;
; #pragma unroll
;                     for (int e = 0; e < 4; ++e) s += a0[e] * a0[e] + a1[e] * a1[e] + b0[e] * b0[e] + b1[e] * b1[e];
;                     s += __shfl_xor(s, 16); s += __shfl_xor(s, 32);
;                     if (fq == 0) ssq_q[row * 4 + wc] = s;
;                     *(u32x4*)(LAT + (size_t)row * 512 + cw) = pack8(a0, a1); *(u32x4*)(LAT + (size_t)row * 512 + 128 + cw) = pack8(b0, b1);
.LBB0_806:
	s_nop 0
	v_mul_f32_e32 v18, v40, v40
	v_mul_f32_e32 v19, v41, v41
	v_fmac_f32_e32 v18, v30, v30
	v_fmac_f32_e32 v19, v31, v31
	v_fmac_f32_e32 v18, v36, v36
	v_fmac_f32_e32 v19, v37, v37
	v_fmac_f32_e32 v18, v42, v42
	v_fmac_f32_e32 v19, v43, v43
	v_add_f32_e32 v18, v18, v19
	v_mul_f32_e32 v19, v28, v28
	v_fmac_f32_e32 v19, v32, v32
	v_fmac_f32_e32 v19, v26, v26
	v_fmac_f32_e32 v19, v38, v38
	v_add_f32_e32 v18, v19, v18
	v_mul_f32_e32 v19, v29, v29
	v_fmac_f32_e32 v19, v33, v33
	v_fmac_f32_e32 v19, v27, v27
	v_fmac_f32_e32 v19, v39, v39
	v_and_b32_e32 v20, 64, v217
	v_add_f32_e32 v18, v19, v18
	v_add_u32_e32 v20, 64, v20
	s_nop 1
	v_mov_b32_e32 v19, v18
	s_nop 1
	v_permlane16_swap_b32_e32 v19, v18
	s_waitcnt lgkmcnt(0)
	v_add_f32_e32 v18, v18, v19
	s_nop 1
	v_mov_b32_e32 v19, v18
	s_nop 1
	v_permlane32_swap_b32_e32 v19, v18
	s_and_saveexec_b64 s[20:21], s[42:43]
	s_cbranch_execz .LBB0_808
	s_waitcnt lgkmcnt(0)
	v_add_f32_e32 v20, v18, v19
	v_lshl_or_b32 v18, v34, 2, s76
	v_readlane_b32 s36, v254, 54
	v_ashrrev_i32_e32 v19, 31, v18
	v_readlane_b32 s37, v254, 55
	v_readlane_b32 s38, v254, 56
	v_readlane_b32 s39, v254, 57
	v_readlane_b32 s36, v254, 44
	v_readlane_b32 s37, v254, 45
	v_lshl_add_u64 v[18:19], v[18:19], 2, s[38:39]
	v_readlane_b32 s38, v254, 48
	v_readlane_b32 s39, v254, 49
	global_store_dword v[18:19], v20, off
.LBB0_808:
	s_or_b64 exec, exec, s[20:21]
	v_ashrrev_i32_e32 v35, 31, v34
	v_lshlrev_b64 v[22:23], 10, v[34:35]
	v_cvt_pk_bf16_f32 v18, v30, v31
	s_waitcnt lgkmcnt(0)
	v_cvt_pk_bf16_f32 v19, v32, v33
	v_cvt_pk_bf16_f32 v20, v40, v41
	v_cvt_pk_bf16_f32 v21, v28, v29
	v_lshl_add_u64 v[22:23], v[142:143], 0, v[22:23]
	global_store_dwordx4 v[22:23], v[18:21], off
	s_nop 1
	v_cvt_pk_bf16_f32 v18, v36, v37
	v_cvt_pk_bf16_f32 v19, v26, v27
	v_cvt_pk_bf16_f32 v20, v42, v43
	v_cvt_pk_bf16_f32 v21, v38, v39
	global_store_dwordx4 v[22:23], v[18:21], off offset:256
	s_nop 1
	v_add_u32_e32 v18, 0xb0, v150
	s_and_b64 vcc, exec, s[6:7]
	s_mov_b64 s[6:7], -1
	s_cbranch_vccz .LBB0_798

; __device__ __forceinline__ u32x4 pack8(f32x4 a, f32x4 b) { u32x4 w; w.x = pk2(a[0], a[1]); w.y = pk2(a[2], a[3]); w.z = pk2(b[0], b[1]); w.w = pk2(b[2], b[3]); return w; }
;     __device__ __forceinline__ void operator()(const Acc& acc, const Unit& u, int wr, int wc, int fr, int fq, const RsCtx& rc) const {
;     ...
;                 const float rs = rc.get(u.pm, ai * 128 + wr * 64 + m * 16 + fr, row);
;                 f32x4 a0 = acc[ai][0][m][0] * rs, a1 = acc[ai][0][m][1] * rs, b0 = acc[ai][1][m][0] * rs, b1 = acc[ai][1][m][1] * rs;
;                 if (pn == 0) {
;                     float s = 0.f;
; #pragma unroll
;                     for (int e = 0; e < 4; ++e) s += a0[e] * a0[e] + a1[e] * a1[e] + b0[e] * b0[e] + b1[e] * b1[e];
;                     s += __shfl_xor(s, 16); s += __shfl_xor(s, 32);
;                     if (fq == 0) ssq_q[row * 4 + wc] = s;
;                     *(u32x4*)(LAT + (size_t)row * 512 + cw) = pack8(a0, a1); *(u32x4*)(LAT + (size_t)row * 512 + 128 + cw) = pack8(b0, b1);
;                 } else if (pn == 1) {
;                     float s = 0.f;
; #pragma unroll
;                     for (int e = 0; e < 4; ++e) s += a0[e] * a0[e] + a1[e] * a1[e];
;                     s += __shfl_xor(s, 16); s += __shfl_xor(s, 32);
;                     if (fq == 0) ssq_kv[row * 4 + wc] = s;
;                     *(u32x4*)(LAT + (size_t)row * 512 + 256 + cw) = pack8(a0, a1);
;                     if (wc == 0) { rope8(b0, b1, TABM + ((size_t)tok_pos(row) * 16 + 4 * fq) * 2); *(u32x4*)(LAT + (size_t)row * 512 + 384 + cw) = pack8(b0, b1); }
.LBB0_811:
	s_waitcnt lgkmcnt(0)
	v_pk_mul_f32 v[16:17], v[16:17], v[26:27] op_sel_hi:[1,0]
	v_pk_mul_f32 v[14:15], v[14:15], v[26:27] op_sel_hi:[1,0]
	v_pk_mul_f32 v[12:13], v[12:13], v[26:27] op_sel_hi:[1,0]
	v_pk_mul_f32 v[24:25], v[10:11], v[26:27] op_sel_hi:[1,0]
	v_pk_mul_f32 v[10:11], v[8:9], v[26:27] op_sel_hi:[1,0]
	v_pk_mul_f32 v[20:21], v[6:7], v[26:27] op_sel_hi:[1,0]
	v_pk_mul_f32 v[22:23], v[4:5], v[26:27] op_sel_hi:[1,0]
	v_pk_mul_f32 v[26:27], v[2:3], v[26:27] op_sel_hi:[1,0]
	s_mov_b64 s[24:25], -1
	s_mov_b64 s[6:7], 0
	s_cmp_lt_i32 s82, 1
	s_mov_b64 s[20:21], 0
	s_cbranch_scc1 .LBB0_833
	s_cmp_eq_u32 s82, 1
	s_mov_b64 s[20:21], -1
	s_cbranch_scc0 .LBB0_818
	v_mul_f32_e32 v2, v24, v24
	v_mul_f32_e32 v3, v25, v25
	v_fmac_f32_e32 v2, v14, v14
	v_fmac_f32_e32 v3, v15, v15
	v_add_f32_e32 v2, v2, v3
	v_mul_f32_e32 v3, v12, v12
	v_fmac_f32_e32 v3, v16, v16
	v_add_f32_e32 v2, v3, v2
	v_mul_f32_e32 v3, v13, v13
	v_fmac_f32_e32 v3, v17, v17
	v_and_b32_e32 v4, 64, v217
	v_add_f32_e32 v2, v3, v2
	v_add_u32_e32 v4, 64, v4
	s_nop 1
	v_mov_b32_e32 v3, v2
	s_nop 1
	v_permlane16_swap_b32_e32 v3, v2
	s_waitcnt lgkmcnt(0)
	v_add_f32_e32 v2, v2, v3
	s_nop 1
	v_mov_b32_e32 v3, v2
	s_nop 1
	v_permlane32_swap_b32_e32 v3, v2
	s_and_saveexec_b64 s[20:21], s[42:43]
	s_cbranch_execz .LBB0_815
	s_waitcnt lgkmcnt(0)
	v_add_f32_e32 v4, v2, v3
	v_lshl_or_b32 v2, v18, 2, s76
	v_ashrrev_i32_e32 v3, 31, v2
	v_lshl_add_u64 v[2:3], v[2:3], 2, s[62:63]
	global_store_dword v[2:3], v4, off
.LBB0_815:
	s_or_b64 exec, exec, s[20:21]
	v_ashrrev_i32_e32 v19, 31, v18
	s_waitcnt lgkmcnt(0)
	v_lshlrev_b64 v[2:3], 10, v[18:19]
	v_cvt_pk_bf16_f32 v4, v14, v15
	v_cvt_pk_bf16_f32 v5, v16, v17
	v_cvt_pk_bf16_f32 v6, v24, v25
	v_cvt_pk_bf16_f32 v7, v12, v13
	v_lshl_add_u64 v[2:3], v[142:143], 0, v[2:3]
	s_andn2_b64 vcc, exec, s[48:49]
	global_store_dwordx4 v[2:3], v[4:7], off offset:512
	s_cbranch_vccnz .LBB0_817
	s_movk_i32 s13, 0x4000
	v_cmp_gt_i32_e32 vcc, s13, v18
	v_lshlrev_b32_e32 v5, 2, v176
	v_readlane_b32 s14, v254, 58
	v_cndmask_b32_e32 v4, v215, v216, vcc
	v_and_b32_e32 v4, v4, v18
	v_lshl_or_b32 v4, v4, 7, v5
	v_mov_b32_e32 v5, v1
	v_readlane_b32 s15, v254, 59
	s_nop 1
	v_lshl_add_u64 v[8:9], s[14:15], 0, v[4:5]
	flat_load_dwordx4 v[4:7], v[8:9]
	flat_load_dwordx4 v[28:31], v[8:9] offset:16
	s_waitcnt vmcnt(0) lgkmcnt(0)
	v_pk_mul_f32 v[8:9], v[20:21], v[4:5] op_sel:[1,1] op_sel_hi:[0,1]
	v_pk_fma_f32 v[32:33], v[20:21], v[4:5], v[8:9] neg_lo:[0,0,1] neg_hi:[0,0,1]
	v_pk_fma_f32 v[4:5], v[20:21], v[4:5], v[8:9] op_sel_hi:[1,0,1]
	s_nop 0
	v_mov_b32_e32 v4, v7
	v_pk_mul_f32 v[8:9], v[10:11], v[4:5] op_sel:[1,0] op_sel_hi:[0,0]
	v_pk_fma_f32 v[34:35], v[10:11], v[6:7], v[8:9] neg_lo:[0,0,1] neg_hi:[0,0,1]
	v_pk_fma_f32 v[6:7], v[10:11], v[6:7], v[8:9] op_sel_hi:[1,0,1]
	v_pk_mul_f32 v[8:9], v[26:27], v[28:29] op_sel:[1,1] op_sel_hi:[0,1]
	v_mov_b32_e32 v4, v31
	v_pk_fma_f32 v[36:37], v[26:27], v[28:29], v[8:9] neg_lo:[0,0,1] neg_hi:[0,0,1]
	v_pk_fma_f32 v[8:9], v[26:27], v[28:29], v[8:9] op_sel_hi:[1,0,1]
	v_pk_mul_f32 v[28:29], v[22:23], v[4:5] op_sel:[1,0] op_sel_hi:[0,0]
	v_pk_fma_f32 v[38:39], v[22:23], v[30:31], v[28:29] neg_lo:[0,0,1] neg_hi:[0,0,1]
	v_pk_fma_f32 v[28:29], v[22:23], v[30:31], v[28:29] op_sel_hi:[1,0,1]
	v_cvt_pk_bf16_f32 v4, v32, v5
	v_cvt_pk_bf16_f32 v5, v34, v7
	v_cvt_pk_bf16_f32 v6, v36, v9
	v_cvt_pk_bf16_f32 v7, v38, v29
	global_store_dwordx4 v[2:3], v[4:7], off offset:768

; __device__ __forceinline__ u32x4 pack8(f32x4 a, f32x4 b) { u32x4 w; w.x = pk2(a[0], a[1]); w.y = pk2(a[2], a[3]); w.z = pk2(b[0], b[1]); w.w = pk2(b[2], b[3]); return w; }
;     __device__ __forceinline__ void operator()(const Acc& acc, const Unit& u, int wr, int wc, int fr, int fq, const RsCtx& rc) const {
;     ...
;                 } else if (pn < 10) {
;                     const int c = (pn - 8) * 256 + cw; const float* tb = TABS + (size_t)tok_pos(row) * 64;
;                     rope8(a0, a1, tb + (c & 63)); rope8(b0, b1, tb + ((c + 128) & 63));
;                     const float sc = 0.125f * LOG2E;
;                     *(u32x4*)(SWAQK + (size_t)row * 768 + c) = pack8(a0 * sc, a1 * sc); *(u32x4*)(SWAQK + (size_t)row * 768 + c + 128) = pack8(b0 * sc, b1 * sc);
;                 } else {
;                     rope8(a0, a1, TABS + (size_t)tok_pos(row) * 64 + (cw & 63));
;                     *(u32x4*)(SWAQK + (size_t)row * 768 + 512 + cw) = pack8(a0, a1);
.LBB0_820:
	s_and_b64 vcc, exec, s[4:5]
	s_mov_b64 s[4:5], -1
	s_cbranch_vccnz .LBB0_830
	s_andn2_b64 vcc, exec, s[26:27]
	s_cbranch_vccnz .LBB0_827
	s_movk_i32 s4, 0x4000
	v_cmp_gt_i32_e32 vcc, s4, v18
	v_mov_b32_e32 v3, v1
	s_mov_b64 s[4:5], -1
	v_cndmask_b32_e32 v2, v215, v216, vcc
	v_and_b32_e32 v2, v2, v18
	v_lshlrev_b32_e32 v2, 8, v2
	v_lshl_add_u64 v[2:3], v[140:141], 0, v[2:3]
	flat_load_dwordx4 v[6:9], v[2:3]
	s_nop 0
	flat_load_dwordx4 v[2:5], v[2:3] offset:16
	s_andn2_b64 vcc, exec, s[16:17]
	s_waitcnt vmcnt(0) lgkmcnt(0)
	v_mov_b32_e32 v30, v9
	v_mov_b32_e32 v38, v5
	v_pk_mul_f32 v[28:29], v[14:15], v[6:7] op_sel:[0,1]
	v_pk_mul_f32 v[36:37], v[24:25], v[2:3] op_sel:[0,1]
	v_pk_mul_f32 v[42:43], v[16:17], v[30:31] op_sel_hi:[1,0]
	v_pk_mul_f32 v[38:39], v[12:13], v[38:39] op_sel_hi:[1,0]
	v_pk_fma_f32 v[32:33], v[14:15], v[6:7], v[28:29] op_sel:[0,0,1] op_sel_hi:[1,0,0] neg_lo:[0,0,1] neg_hi:[0,0,1]
	v_pk_fma_f32 v[34:35], v[14:15], v[6:7], v[28:29] op_sel:[0,0,1] op_sel_hi:[1,0,0]
	v_pk_fma_f32 v[28:29], v[24:25], v[2:3], v[36:37] op_sel:[0,0,1] op_sel_hi:[1,0,0] neg_lo:[0,0,1] neg_hi:[0,0,1]
	v_pk_fma_f32 v[30:31], v[24:25], v[2:3], v[36:37] op_sel:[0,0,1] op_sel_hi:[1,0,0]
	v_pk_fma_f32 v[40:41], v[16:17], v[8:9], v[42:43] op_sel:[0,0,1] op_sel_hi:[1,0,0] neg_lo:[0,0,1] neg_hi:[0,0,1]
	v_pk_fma_f32 v[42:43], v[16:17], v[8:9], v[42:43] op_sel:[0,0,1] op_sel_hi:[1,0,0]
	v_pk_fma_f32 v[36:37], v[12:13], v[4:5], v[38:39] op_sel:[0,0,1] op_sel_hi:[1,0,0] neg_lo:[0,0,1] neg_hi:[0,0,1]
	v_pk_fma_f32 v[38:39], v[12:13], v[4:5], v[38:39] op_sel:[0,0,1] op_sel_hi:[1,0,0]
	s_cbranch_vccnz .LBB0_824
	s_movk_i32 s4, 0x600
	v_mad_i64_i32 v[48:49], s[4:5], v18, s4, v[144:145]
	v_cvt_pk_bf16_f32 v44, v32, v35
	v_cvt_pk_bf16_f32 v45, v40, v43
	v_cvt_pk_bf16_f32 v46, v28, v31
	v_cvt_pk_bf16_f32 v47, v36, v39
	s_mov_b64 s[4:5], 0
	global_store_dwordx4 v[48:49], v[44:47], off offset:1024
.LBB0_824:
	s_andn2_b64 vcc, exec, s[4:5]
	s_cbranch_vccnz .LBB0_826
	v_mov_b32_e32 v44, v6
	v_mov_b32_e32 v45, v6
	v_mov_b32_e32 v6, v7
	v_mov_b32_e32 v46, v8
	v_mov_b32_e32 v47, v8
	v_mov_b32_e32 v8, v9
	v_mov_b32_e32 v48, v2
	v_mov_b32_e32 v49, v2
	v_mov_b32_e32 v2, v3
	v_mov_b32_e32 v50, v4
	v_mov_b32_e32 v51, v4
	v_mov_b32_e32 v4, v5
	v_pk_mul_f32 v[6:7], v[20:21], v[6:7]
	v_pk_mul_f32 v[8:9], v[10:11], v[8:9]
	v_pk_mul_f32 v[2:3], v[26:27], v[2:3]
	v_pk_fma_f32 v[52:53], v[20:21], v[44:45], v[6:7] op_sel:[0,0,1] op_sel_hi:[1,1,0] neg_lo:[0,0,1] neg_hi:[0,0,1]
	v_pk_fma_f32 v[6:7], v[20:21], v[44:45], v[6:7] op_sel:[0,0,1] op_sel_hi:[1,1,0]
	v_pk_fma_f32 v[44:45], v[10:11], v[46:47], v[8:9] op_sel:[0,0,1] op_sel_hi:[1,1,0] neg_lo:[0,0,1] neg_hi:[0,0,1]
	v_pk_fma_f32 v[8:9], v[10:11], v[46:47], v[8:9] op_sel:[0,0,1] op_sel_hi:[1,1,0]
	v_pk_fma_f32 v[46:47], v[26:27], v[48:49], v[2:3] op_sel:[0,0,1] op_sel_hi:[1,1,0] neg_lo:[0,0,1] neg_hi:[0,0,1]
	v_pk_fma_f32 v[48:49], v[26:27], v[48:49], v[2:3] op_sel:[0,0,1] op_sel_hi:[1,1,0]
	v_pk_mul_f32 v[2:3], v[22:23], v[4:5]
	v_mov_b32_e32 v41, v43
	s_mov_b32 s6, 0x3e38aa3b
	v_mov_b32_e32 v33, v35
	v_mov_b32_e32 v29, v31
	v_readlane_b32 s4, v255, 4
	v_pk_fma_f32 v[54:55], v[22:23], v[50:51], v[2:3] op_sel:[0,0,1] op_sel_hi:[1,1,0] neg_lo:[0,0,1] neg_hi:[0,0,1]
	v_pk_fma_f32 v[50:51], v[22:23], v[50:51], v[2:3] op_sel:[0,0,1] op_sel_hi:[1,1,0]
	v_pk_mul_f32 v[4:5], v[40:41], s[6:7] op_sel_hi:[1,0]
	v_pk_mul_f32 v[2:3], v[32:33], s[6:7] op_sel_hi:[1,0]
	v_pk_mul_f32 v[28:29], v[28:29], s[6:7] op_sel_hi:[1,0]
	v_readlane_b32 s5, v255, 5
	v_mov_b32_e32 v37, v39
	v_cvt_pk_bf16_f32 v2, v2, v3
	v_cvt_pk_bf16_f32 v3, v4, v5
	v_cvt_pk_bf16_f32 v4, v28, v29
	v_mov_b64_e32 v[28:29], s[4:5]
	s_movk_i32 s4, 0x600
	v_pk_mul_f32 v[32:33], v[36:37], s[6:7] op_sel_hi:[1,0]
	v_mad_i64_i32 v[28:29], s[4:5], v18, s4, v[28:29]
	v_cvt_pk_bf16_f32 v5, v32, v33
	v_lshl_add_u64 v[28:29], v[0:1], 1, v[28:29]
	v_mov_b32_e32 v45, v9
	v_mov_b32_e32 v53, v7
	v_mov_b32_e32 v55, v51
	v_mov_b32_e32 v47, v49
	global_store_dwordx4 v[28:29], v[2:5], off
	v_pk_mul_f32 v[6:7], v[54:55], s[6:7] op_sel_hi:[1,0]
	v_pk_mul_f32 v[8:9], v[46:47], s[6:7] op_sel_hi:[1,0]
	v_pk_mul_f32 v[4:5], v[44:45], s[6:7] op_sel_hi:[1,0]
	v_pk_mul_f32 v[2:3], v[52:53], s[6:7] op_sel_hi:[1,0]
	s_nop 0
	v_cvt_pk_bf16_f32 v2, v2, v3
	v_cvt_pk_bf16_f32 v3, v4, v5
	v_cvt_pk_bf16_f32 v4, v8, v9
	v_cvt_pk_bf16_f32 v5, v6, v7
	global_store_dwordx4 v[28:29], v[2:5], off offset:256

; __device__ __forceinline__ u32x4 pack8(f32x4 a, f32x4 b) { u32x4 w; w.x = pk2(a[0], a[1]); w.y = pk2(a[2], a[3]); w.z = pk2(b[0], b[1]); w.w = pk2(b[2], b[3]); return w; }
;     __device__ __forceinline__ void operator()(const Acc& acc, const Unit& u, int wr, int wc, int fr, int fq, const RsCtx& rc) const {
;     ...
;                 } else if (pn < 8) {
;                     *(u32x4*)(CONVZ + (size_t)row * 512 + (pn - 4) * 128 + cw) = pack8(a0 * b0, a1 * b1);
.LBB0_827:
	s_andn2_b64 vcc, exec, s[4:5]
	s_cbranch_vccnz .LBB0_829
	v_pk_mul_f32 v[4:5], v[16:17], v[10:11]
	v_pk_mul_f32 v[2:3], v[14:15], v[20:21]
	v_pk_mul_f32 v[6:7], v[12:13], v[22:23]
	v_ashrrev_i32_e32 v19, 31, v18
	v_readlane_b32 s4, v255, 2
	v_cvt_pk_bf16_f32 v2, v2, v3
	v_cvt_pk_bf16_f32 v3, v4, v5
	v_cvt_pk_bf16_f32 v5, v6, v7
	v_lshlrev_b64 v[6:7], 10, v[18:19]
	v_readlane_b32 s5, v255, 3
	s_lshl_b32 s92, s12, 1
	v_lshlrev_b32_e32 v0, 1, v138
	v_lshl_add_u64 v[6:7], s[4:5], 0, v[6:7]
	v_lshl_add_u64 v[6:7], v[6:7], 0, s[92:93]
	v_lshl_add_u64 v[6:7], v[6:7], 0, v[0:1]
	v_pk_mul_f32 v[8:9], v[24:25], v[26:27]
	v_add_co_u32_e32 v6, vcc, 0xfffffc00, v6
	v_cvt_pk_bf16_f32 v4, v8, v9
	s_nop 0
	v_addc_co_u32_e32 v7, vcc, -1, v7, vcc
	global_store_dwordx4 v[6:7], v[2:5], off

; __device__ __forceinline__ u32x4 pack8(f32x4 a, f32x4 b) { u32x4 w; w.x = pk2(a[0], a[1]); w.y = pk2(a[2], a[3]); w.z = pk2(b[0], b[1]); w.w = pk2(b[2], b[3]); return w; }
;     __device__ __forceinline__ void operator()(const Acc& acc, const Unit& u, int wr, int wc, int fr, int fq, const RsCtx& rc) const {
;     ...
;                 } else if (pn < 4) {
;                     bf16_t* p = CONVB + (size_t)row * 512 + (pn - 2) * 256 + cw;
;                     *(u32x4*)p = pack8(a0, a1); *(u32x4*)(p + 128) = pack8(b0, b1);
.LBB0_830:
	s_andn2_b64 vcc, exec, s[4:5]
	s_cbranch_vccnz .LBB0_832
	v_ashrrev_i32_e32 v19, 31, v18
	v_lshlrev_b64 v[2:3], 10, v[18:19]
	v_lshl_add_u64 v[2:3], s[54:55], 0, v[2:3]
	v_lshl_add_u64 v[2:3], s[22:23], 1, v[2:3]
	v_lshlrev_b32_e32 v0, 1, v138
	v_lshl_add_u64 v[6:7], v[2:3], 0, v[0:1]
	v_cvt_pk_bf16_f32 v2, v14, v15
	v_cvt_pk_bf16_f32 v3, v16, v17
	v_cvt_pk_bf16_f32 v4, v24, v25
	v_cvt_pk_bf16_f32 v5, v12, v13
	global_store_dwordx4 v[6:7], v[2:5], off
	s_nop 1
	v_cvt_pk_bf16_f32 v2, v20, v21
	v_cvt_pk_bf16_f32 v3, v10, v11
	v_cvt_pk_bf16_f32 v4, v26, v27
	v_cvt_pk_bf16_f32 v5, v22, v23
	global_store_dwordx4 v[6:7], v[2:5], off offset:256

; __device__ __forceinline__ u32x4 pack8(f32x4 a, f32x4 b) { u32x4 w; w.x = pk2(a[0], a[1]); w.y = pk2(a[2], a[3]); w.z = pk2(b[0], b[1]); w.w = pk2(b[2], b[3]); return w; }
;     __device__ __forceinline__ void operator()(const Acc& acc, const Unit& u, int wr, int wc, int fr, int fq, const RsCtx& rc) const {
;     ...
;                 if (pn == 0) {
;                     float s = 0.f;
; #pragma unroll
;                     for (int e = 0; e < 4; ++e) s += a0[e] * a0[e] + a1[e] * a1[e] + b0[e] * b0[e] + b1[e] * b1[e];
;                     s += __shfl_xor(s, 16); s += __shfl_xor(s, 32);
;                     if (fq == 0) ssq_q[row * 4 + wc] = s;
;                     *(u32x4*)(LAT + (size_t)row * 512 + cw) = pack8(a0, a1); *(u32x4*)(LAT + (size_t)row * 512 + 128 + cw) = pack8(b0, b1);
.LBB0_836:
	v_mul_f32_e32 v0, v24, v24
	v_mul_f32_e32 v2, v25, v25
	v_fmac_f32_e32 v0, v14, v14
	v_fmac_f32_e32 v2, v15, v15
	v_fmac_f32_e32 v0, v20, v20
	v_fmac_f32_e32 v2, v21, v21
	v_fmac_f32_e32 v0, v26, v26
	v_fmac_f32_e32 v2, v27, v27
	v_add_f32_e32 v0, v0, v2
	v_mul_f32_e32 v2, v12, v12
	v_fmac_f32_e32 v2, v16, v16
	v_fmac_f32_e32 v2, v10, v10
	v_fmac_f32_e32 v2, v22, v22
	v_add_f32_e32 v0, v2, v0
	v_mul_f32_e32 v2, v13, v13
	v_fmac_f32_e32 v2, v17, v17
	v_fmac_f32_e32 v2, v11, v11
	v_fmac_f32_e32 v2, v23, v23
	v_and_b32_e32 v3, 64, v217
	v_add_f32_e32 v0, v2, v0
	v_add_u32_e32 v3, 64, v3
	s_nop 1
	v_mov_b32_e32 v2, v0
	s_nop 1
	v_permlane16_swap_b32_e32 v2, v0
	s_waitcnt lgkmcnt(0)
	v_add_f32_e32 v0, v0, v2
	s_nop 1
	v_mov_b32_e32 v2, v0
	s_nop 1
	v_permlane32_swap_b32_e32 v2, v0
	s_and_saveexec_b64 s[4:5], s[42:43]
	s_cbranch_execz .LBB0_838
	s_waitcnt lgkmcnt(0)
	v_add_f32_e32 v0, v0, v2
	v_lshl_or_b32 v2, v18, 2, s76
	v_readlane_b32 s12, v254, 54
	v_ashrrev_i32_e32 v3, 31, v2
	v_readlane_b32 s14, v254, 56
	v_readlane_b32 s15, v254, 57
	v_readlane_b32 s13, v254, 55
	s_nop 0
	v_lshl_add_u64 v[2:3], v[2:3], 2, s[14:15]
	global_store_dword v[2:3], v0, off
.LBB0_838:
	s_or_b64 exec, exec, s[4:5]
	v_ashrrev_i32_e32 v19, 31, v18
	v_lshlrev_b64 v[6:7], 10, v[18:19]
	s_waitcnt lgkmcnt(0)
	v_cvt_pk_bf16_f32 v2, v14, v15
	v_cvt_pk_bf16_f32 v3, v16, v17
	v_cvt_pk_bf16_f32 v4, v24, v25
	v_cvt_pk_bf16_f32 v5, v12, v13
	v_lshl_add_u64 v[6:7], v[142:143], 0, v[6:7]
	global_store_dwordx4 v[6:7], v[2:5], off
	s_nop 1
	v_cvt_pk_bf16_f32 v2, v20, v21
	v_cvt_pk_bf16_f32 v3, v10, v11
	v_cvt_pk_bf16_f32 v4, v26, v27
	v_cvt_pk_bf16_f32 v5, v22, v23
	global_store_dwordx4 v[6:7], v[2:5], off offset:256

; __device__ __forceinline__ u32x4 pack8(f32x4 a, f32x4 b) { u32x4 w; w.x = pk2(a[0], a[1]); w.y = pk2(a[2], a[3]); w.z = pk2(b[0], b[1]); w.w = pk2(b[2], b[3]); return w; }
; __device__ __forceinline__ void unpack8(u32x4 w, f32x4& a, f32x4& b) { a = (f32x4){bflo(w.x), bfhi(w.x), bflo(w.y), bfhi(w.y)}; b = (f32x4){bflo(w.z), bfhi(w.z), bflo(w.w), bfhi(w.w)}; }
;     __device__ __forceinline__ void operator()(const Acc& acc, const Unit& u, int wr, int wc, int fr, int fq, const RsCtx& rc) const {
; #pragma unroll
;         for (int ai = 0; ai < 2; ++ai)
; #pragma unroll
;             for (int m = 0; m < 4; ++m) { const int row = EPI_ROW(u, ai, wr, m, fr); float s = 0.f;
; #pragma unroll
;                 for (int bj = 0; bj < 2; ++bj) { const size_t off = (size_t)row * DM + u.pn * 256 + bj * 128 + wc * 32 + 8 * fq;
;                     f32x4 x0, x1; unpack8(*(const u32x4*)(XB + off), x0, x1);
;                     x0 = x0 + acc[ai][bj][m][0] * alpha; x1 = x1 + acc[ai][bj][m][1] * alpha;
;                     *(u32x4*)(XB + off) = pack8(x0, x1);
; #pragma unroll
;                     for (int e = 0; e < 4; ++e) s += x0[e] * x0[e] + x1[e] * x1[e]; }
;                 s += __shfl_xor(s, 16); s += __shfl_xor(s, 32);
;                 if (fq == 0) ssq_x[(size_t)row * 16 + u.pn * 4 + wc] = s;
;                 if (m == 3) asm volatile("" ::: "memory"); }
.LBB0_1104:
	v_and_b32_e32 v149, 64, v217
	v_xor_b32_e32 v0, 16, v217
	v_add_u32_e32 v149, 64, v149
	v_cmp_lt_i32_e32 vcc, v0, v149
	v_lshl_add_u32 v148, s37, 8, v141
	s_lshl_b32 s50, s36, 8
	v_cndmask_b32_e32 v0, v217, v0, vcc
	v_lshlrev_b32_e32 v155, 2, v0
	v_xor_b32_e32 v0, 32, v217
	v_cmp_lt_i32_e32 vcc, v0, v149
	s_lshl_b32 s48, s36, 2
	v_ashrrev_i32_e32 v149, 31, v148
	v_readlane_b32 s36, v254, 44
	v_lshlrev_b64 v[150:151], 11, v[148:149]
	v_readlane_b32 s37, v254, 45
	s_ashr_i32 s51, s50, 31
	v_cndmask_b32_e32 v0, v217, v0, vcc
	v_lshl_add_u64 v[150:151], s[36:37], 0, v[150:151]
	v_lshl_add_u64 v[150:151], s[50:51], 1, v[150:151]
	s_lshl_b32 s92, s55, 1
	v_lshlrev_b32_e32 v154, 2, v0
	v_lshl_add_u64 v[150:151], v[150:151], 0, s[92:93]
	v_lshlrev_b32_e32 v0, 1, v140
	v_lshl_add_u64 v[150:151], v[150:151], 0, v[0:1]
	v_lshl_add_u32 v210, v148, 11, v0
	s_lshl_b64 s[28:29], s[50:51], 1
	s_add_u32 s28, s28, s36
	s_addc_u32 s29, s29, s37
	s_add_u32 s28, s28, s92
	s_addc_u32 s29, s29, s93
	global_load_dwordx4 v[156:159], v210, s[28:29]
	global_load_dwordx4 v[164:167], v210, s[28:29] offset:256
	s_add_u32 s28, s28, 0x8000
	s_addc_u32 s29, s29, 0
	global_load_dwordx4 v[168:171], v210, s[28:29]
	global_load_dwordx4 v[172:175], v210, s[28:29] offset:256
	s_add_u32 s28, s28, 0x8000
	s_addc_u32 s29, s29, 0
	global_load_dwordx4 v[176:179], v210, s[28:29]
	global_load_dwordx4 v[180:183], v210, s[28:29] offset:256
	s_add_u32 s28, s28, 0x8000
	s_addc_u32 s29, s29, 0
	global_load_dwordx4 v[184:187], v210, s[28:29]
	global_load_dwordx4 v[188:191], v210, s[28:29] offset:256
	s_add_u32 s28, s28, 0x28000
	s_addc_u32 s29, s29, 0
	global_load_dwordx4 v[192:195], v210, s[28:29]
	global_load_dwordx4 v[206:209], v210, s[28:29] offset:256
	s_add_u32 s28, s28, 0x8000
	s_addc_u32 s29, s29, 0
	global_load_dwordx4 v[218:221], v210, s[28:29]
	global_load_dwordx4 v[232:235], v210, s[28:29] offset:256
	s_add_u32 s28, s28, 0x8000
	s_addc_u32 s29, s29, 0
	global_load_dwordx4 v[236:239], v210, s[28:29]
	global_load_dwordx4 v[240:243], v210, s[28:29] offset:256
	s_add_u32 s28, s28, 0x8000
	s_addc_u32 s29, s29, 0
	global_load_dwordx4 v[244:247], v210, s[28:29]
	global_load_dwordx4 v[248:251], v210, s[28:29] offset:256
	s_ashr_i32 s49, s48, 31
	s_waitcnt vmcnt(0) lgkmcnt(0)
	v_lshlrev_b32_e32 v160, 16, v156
	v_and_b32_e32 v161, 0xffff0000, v156
	v_lshlrev_b32_e32 v156, 16, v157
	v_and_b32_e32 v157, 0xffff0000, v157
	v_lshlrev_b32_e32 v162, 16, v158
	v_and_b32_e32 v163, 0xffff0000, v158
	v_lshlrev_b32_e32 v158, 16, v159
	v_and_b32_e32 v159, 0xffff0000, v159
	v_pk_fma_f32 v[156:157], v[142:143], v[124:125], v[156:157]
	v_pk_fma_f32 v[160:161], v[130:131], v[122:123], v[160:161]
	v_pk_fma_f32 v[128:129], v[142:143], v[128:129], v[158:159]
	v_pk_fma_f32 v[126:127], v[130:131], v[126:127], v[162:163]
	v_cvt_pk_bf16_f32 v122, v160, v161
	v_cvt_pk_bf16_f32 v123, v156, v157
	v_cvt_pk_bf16_f32 v124, v126, v127
	v_cvt_pk_bf16_f32 v125, v128, v129
	global_store_dwordx4 v[150:151], v[122:125], off
	s_nop 1
	v_mul_f32_e32 v122, v126, v126
	v_mul_f32_e32 v123, v127, v127
	v_fmac_f32_e32 v122, v160, v160
	v_fmac_f32_e32 v123, v161, v161
	v_add_f32_e32 v122, v122, v123
	v_mul_f32_e32 v123, v128, v128
	v_fmac_f32_e32 v123, v156, v156
	v_add_f32_e32 v122, v123, v122
	v_mul_f32_e32 v123, v129, v129
	v_fmac_f32_e32 v123, v157, v157
	v_add_f32_e32 v156, v123, v122
	v_mov_b64_e32 v[122:123], v[164:165]
	v_mov_b64_e32 v[124:125], v[166:167]
	s_waitcnt lgkmcnt(0)
	v_lshlrev_b32_e32 v126, 16, v122
	v_and_b32_e32 v127, 0xffff0000, v122
	v_lshlrev_b32_e32 v122, 16, v123
	v_and_b32_e32 v123, 0xffff0000, v123
	v_lshlrev_b32_e32 v128, 16, v124
	v_and_b32_e32 v129, 0xffff0000, v124
	v_lshlrev_b32_e32 v124, 16, v125
	v_and_b32_e32 v125, 0xffff0000, v125
	v_pk_fma_f32 v[120:121], v[142:143], v[120:121], v[122:123]
	v_pk_fma_f32 v[118:119], v[130:131], v[118:119], v[126:127]
	v_pk_fma_f32 v[122:123], v[142:143], v[116:117], v[124:125]
	v_pk_fma_f32 v[124:125], v[130:131], v[114:115], v[128:129]
	v_cvt_pk_bf16_f32 v114, v118, v119
	v_cvt_pk_bf16_f32 v115, v120, v121
	v_cvt_pk_bf16_f32 v116, v124, v125
	v_cvt_pk_bf16_f32 v117, v122, v123
	global_store_dwordx4 v[150:151], v[114:117], off offset:256
	s_nop 1
	v_mul_f32_e32 v114, v124, v124
	v_fmac_f32_e32 v114, v118, v118
	v_mul_f32_e32 v115, v125, v125
	v_add_f32_e32 v114, v114, v156
	v_fmac_f32_e32 v115, v119, v119
	v_add_f32_e32 v114, v115, v114
	v_mul_f32_e32 v115, v122, v122
	v_fmac_f32_e32 v115, v120, v120
	v_add_f32_e32 v114, v115, v114
	v_mul_f32_e32 v115, v123, v123
	v_fmac_f32_e32 v115, v121, v121
	v_add_f32_e32 v114, v115, v114
	v_mov_b32_e32 v115, v114
	s_nop 1
	v_permlane16_swap_b32_e32 v115, v114
	s_waitcnt lgkmcnt(0)
	v_add_f32_e32 v114, v114, v115
	v_mov_b32_e32 v115, v114
	s_nop 1
	v_permlane32_swap_b32_e32 v115, v114
	s_and_saveexec_b64 s[24:25], s[4:5]
	s_cbranch_execz .LBB0_1106
	s_waitcnt lgkmcnt(0)
	v_add_f32_e32 v116, v114, v115
	v_lshlrev_b64 v[114:115], 6, v[148:149]
	v_lshl_add_u64 v[114:115], s[38:39], 0, v[114:115]
	v_lshl_add_u64 v[114:115], s[48:49], 2, v[114:115]
	s_lshl_b32 s28, s53, 2
	s_mov_b32 s29, s93
	v_lshl_add_u64 v[114:115], v[114:115], 0, s[28:29]
	global_store_dword v[114:115], v116, off
; __device__ __forceinline__ u32x4 pack8(f32x4 a, f32x4 b) { u32x4 w; w.x = pk2(a[0], a[1]); w.y = pk2(a[2], a[3]); w.z = pk2(b[0], b[1]); w.w = pk2(b[2], b[3]); return w; }
; __device__ __forceinline__ void unpack8(u32x4 w, f32x4& a, f32x4& b) { a = (f32x4){bflo(w.x), bfhi(w.x), bflo(w.y), bfhi(w.y)}; b = (f32x4){bflo(w.z), bfhi(w.z), bflo(w.w), bfhi(w.w)}; }
;     __device__ __forceinline__ void operator()(const Acc& acc, const Unit& u, int wr, int wc, int fr, int fq, const RsCtx& rc) const {
;     ...
;             for (int m = 0; m < 4; ++m) { const int row = EPI_ROW(u, ai, wr, m, fr); float s = 0.f;
; #pragma unroll
;                 for (int bj = 0; bj < 2; ++bj) { const size_t off = (size_t)row * DM + u.pn * 256 + bj * 128 + wc * 32 + 8 * fq;
;                     f32x4 x0, x1; unpack8(*(const u32x4*)(XB + off), x0, x1);
;                     x0 = x0 + acc[ai][bj][m][0] * alpha; x1 = x1 + acc[ai][bj][m][1] * alpha;
;                     *(u32x4*)(XB + off) = pack8(x0, x1);
; #pragma unroll
;                     for (int e = 0; e < 4; ++e) s += x0[e] * x0[e] + x1[e] * x1[e]; }
;                 s += __shfl_xor(s, 16); s += __shfl_xor(s, 32);
;                 if (fq == 0) ssq_x[(size_t)row * 16 + u.pn * 4 + wc] = s;
;                 if (m == 3) asm volatile("" ::: "memory"); }
.LBB0_1106:
	s_or_b64 exec, exec, s[24:25]
	v_or_b32_e32 v114, 16, v148
	s_waitcnt lgkmcnt(0)
	v_ashrrev_i32_e32 v115, 31, v114
	v_lshlrev_b64 v[116:117], 11, v[114:115]
	v_lshl_add_u64 v[116:117], s[36:37], 0, v[116:117]
	v_lshl_add_u64 v[116:117], s[50:51], 1, v[116:117]
	v_lshl_add_u64 v[116:117], v[116:117], 0, s[92:93]
	v_lshl_add_u64 v[120:121], v[116:117], 0, v[0:1]
	v_mov_b64_e32 v[116:117], v[168:169]
	v_mov_b64_e32 v[118:119], v[170:171]
	s_waitcnt lgkmcnt(0)
	v_lshlrev_b32_e32 v122, 16, v116
	v_and_b32_e32 v123, 0xffff0000, v116
	v_lshlrev_b32_e32 v116, 16, v117
	v_and_b32_e32 v117, 0xffff0000, v117
	v_lshlrev_b32_e32 v124, 16, v118
	v_and_b32_e32 v125, 0xffff0000, v118
	v_lshlrev_b32_e32 v118, 16, v119
	v_and_b32_e32 v119, 0xffff0000, v119
	v_pk_fma_f32 v[112:113], v[142:143], v[112:113], v[116:117]
	v_pk_fma_f32 v[110:111], v[130:131], v[110:111], v[122:123]
	v_pk_fma_f32 v[116:117], v[142:143], v[108:109], v[118:119]
	v_pk_fma_f32 v[118:119], v[130:131], v[106:107], v[124:125]
	v_cvt_pk_bf16_f32 v106, v110, v111
	v_cvt_pk_bf16_f32 v107, v112, v113
	v_cvt_pk_bf16_f32 v108, v118, v119
	v_cvt_pk_bf16_f32 v109, v116, v117
	global_store_dwordx4 v[120:121], v[106:109], off
	s_nop 1
	v_mul_f32_e32 v106, v118, v118
	v_mul_f32_e32 v107, v119, v119
	v_fmac_f32_e32 v106, v110, v110
	v_fmac_f32_e32 v107, v111, v111
	v_add_f32_e32 v106, v106, v107
	v_mul_f32_e32 v107, v116, v116
	v_fmac_f32_e32 v107, v112, v112
	v_add_f32_e32 v106, v107, v106
	v_mul_f32_e32 v107, v117, v117
	v_fmac_f32_e32 v107, v113, v113
	v_add_f32_e32 v116, v107, v106
	v_mov_b64_e32 v[106:107], v[172:173]
	v_mov_b64_e32 v[108:109], v[174:175]
	s_waitcnt lgkmcnt(0)
	v_lshlrev_b32_e32 v110, 16, v106
	v_and_b32_e32 v111, 0xffff0000, v106
	v_lshlrev_b32_e32 v106, 16, v107
	v_and_b32_e32 v107, 0xffff0000, v107
	v_lshlrev_b32_e32 v112, 16, v108
	v_and_b32_e32 v113, 0xffff0000, v108
	v_lshlrev_b32_e32 v108, 16, v109
	v_and_b32_e32 v109, 0xffff0000, v109
	v_pk_fma_f32 v[104:105], v[142:143], v[104:105], v[106:107]
	v_pk_fma_f32 v[102:103], v[130:131], v[102:103], v[110:111]
	v_pk_fma_f32 v[106:107], v[142:143], v[100:101], v[108:109]
	v_pk_fma_f32 v[108:109], v[130:131], v[98:99], v[112:113]
	v_cvt_pk_bf16_f32 v98, v102, v103
	v_cvt_pk_bf16_f32 v99, v104, v105
	v_cvt_pk_bf16_f32 v100, v108, v109
	v_cvt_pk_bf16_f32 v101, v106, v107
	global_store_dwordx4 v[120:121], v[98:101], off offset:256
	s_nop 1
	v_mul_f32_e32 v98, v108, v108
	v_fmac_f32_e32 v98, v102, v102
	v_mul_f32_e32 v99, v109, v109
	v_add_f32_e32 v98, v98, v116
	v_fmac_f32_e32 v99, v103, v103
	v_add_f32_e32 v98, v99, v98
	v_mul_f32_e32 v99, v106, v106
	v_fmac_f32_e32 v99, v104, v104
	v_add_f32_e32 v98, v99, v98
	v_mul_f32_e32 v99, v107, v107
	v_fmac_f32_e32 v99, v105, v105
	v_add_f32_e32 v98, v99, v98
	v_mov_b32_e32 v99, v98
	s_nop 1
	v_permlane16_swap_b32_e32 v99, v98
	s_waitcnt lgkmcnt(0)
	v_add_f32_e32 v98, v98, v99
	v_mov_b32_e32 v99, v98
	s_nop 1
	v_permlane32_swap_b32_e32 v99, v98
	s_and_saveexec_b64 s[24:25], s[4:5]
	s_cbranch_execz .LBB0_1108
	s_waitcnt lgkmcnt(0)
	v_add_f32_e32 v100, v98, v99
	v_lshlrev_b64 v[98:99], 6, v[114:115]
	v_lshl_add_u64 v[98:99], s[38:39], 0, v[98:99]
	v_lshl_add_u64 v[98:99], s[48:49], 2, v[98:99]
	s_lshl_b32 s28, s53, 2
	s_mov_b32 s29, s93
	v_lshl_add_u64 v[98:99], v[98:99], 0, s[28:29]
	global_store_dword v[98:99], v100, off
.LBB0_1108:
	s_or_b64 exec, exec, s[24:25]
	v_or_b32_e32 v98, 32, v148
	s_waitcnt lgkmcnt(0)
	v_ashrrev_i32_e32 v99, 31, v98
	v_lshlrev_b64 v[100:101], 11, v[98:99]
	v_lshl_add_u64 v[100:101], s[36:37], 0, v[100:101]
	v_lshl_add_u64 v[100:101], s[50:51], 1, v[100:101]
	v_lshl_add_u64 v[100:101], v[100:101], 0, s[92:93]
	v_lshl_add_u64 v[104:105], v[100:101], 0, v[0:1]
	v_mov_b64_e32 v[100:101], v[176:177]
	v_mov_b64_e32 v[102:103], v[178:179]
	s_waitcnt lgkmcnt(0)
	v_lshlrev_b32_e32 v106, 16, v100
	v_and_b32_e32 v107, 0xffff0000, v100
	v_lshlrev_b32_e32 v100, 16, v101
	v_and_b32_e32 v101, 0xffff0000, v101
	v_lshlrev_b32_e32 v108, 16, v102
	v_and_b32_e32 v109, 0xffff0000, v102
	v_lshlrev_b32_e32 v102, 16, v103
	v_and_b32_e32 v103, 0xffff0000, v103
	v_pk_fma_f32 v[96:97], v[142:143], v[96:97], v[100:101]
	v_pk_fma_f32 v[94:95], v[130:131], v[94:95], v[106:107]
	v_pk_fma_f32 v[100:101], v[142:143], v[92:93], v[102:103]
	v_pk_fma_f32 v[102:103], v[130:131], v[90:91], v[108:109]
	v_cvt_pk_bf16_f32 v90, v94, v95
	v_cvt_pk_bf16_f32 v91, v96, v97
	v_cvt_pk_bf16_f32 v92, v102, v103
	v_cvt_pk_bf16_f32 v93, v100, v101
	global_store_dwordx4 v[104:105], v[90:93], off
	s_nop 1
	v_mul_f32_e32 v90, v102, v102
	v_mul_f32_e32 v91, v103, v103
	v_fmac_f32_e32 v90, v94, v94
	v_fmac_f32_e32 v91, v95, v95
	v_add_f32_e32 v90, v90, v91
	v_mul_f32_e32 v91, v100, v100
	v_fmac_f32_e32 v91, v96, v96
	v_add_f32_e32 v90, v91, v90
	v_mul_f32_e32 v91, v101, v101
	v_fmac_f32_e32 v91, v97, v97
	v_add_f32_e32 v100, v91, v90
	v_mov_b64_e32 v[90:91], v[180:181]
	v_mov_b64_e32 v[92:93], v[182:183]
	s_waitcnt lgkmcnt(0)
	v_lshlrev_b32_e32 v94, 16, v90
	v_and_b32_e32 v95, 0xffff0000, v90
	v_lshlrev_b32_e32 v90, 16, v91
	v_and_b32_e32 v91, 0xffff0000, v91
	v_lshlrev_b32_e32 v96, 16, v92
	v_and_b32_e32 v97, 0xffff0000, v92
	v_lshlrev_b32_e32 v92, 16, v93
	v_and_b32_e32 v93, 0xffff0000, v93
	v_pk_fma_f32 v[88:89], v[142:143], v[88:89], v[90:91]
	v_pk_fma_f32 v[86:87], v[130:131], v[86:87], v[94:95]
	v_pk_fma_f32 v[90:91], v[142:143], v[84:85], v[92:93]
	v_pk_fma_f32 v[92:93], v[130:131], v[82:83], v[96:97]
	v_cvt_pk_bf16_f32 v82, v86, v87
	v_cvt_pk_bf16_f32 v83, v88, v89
	v_cvt_pk_bf16_f32 v84, v92, v93
	v_cvt_pk_bf16_f32 v85, v90, v91
	global_store_dwordx4 v[104:105], v[82:85], off offset:256
	s_nop 1
	v_mul_f32_e32 v82, v92, v92
	v_fmac_f32_e32 v82, v86, v86
	v_mul_f32_e32 v83, v93, v93
	v_add_f32_e32 v82, v82, v100
	v_fmac_f32_e32 v83, v87, v87
	v_add_f32_e32 v82, v83, v82
	v_mul_f32_e32 v83, v90, v90
	v_fmac_f32_e32 v83, v88, v88
	v_add_f32_e32 v82, v83, v82
	v_mul_f32_e32 v83, v91, v91
	v_fmac_f32_e32 v83, v89, v89
	v_add_f32_e32 v82, v83, v82
	v_mov_b32_e32 v83, v82
	s_nop 1
	v_permlane16_swap_b32_e32 v83, v82
	s_waitcnt lgkmcnt(0)
	v_add_f32_e32 v82, v82, v83
	v_mov_b32_e32 v83, v82
	s_nop 1
	v_permlane32_swap_b32_e32 v83, v82
	s_and_saveexec_b64 s[24:25], s[4:5]
	s_cbranch_execz .LBB0_1110
	s_waitcnt lgkmcnt(0)
	v_add_f32_e32 v84, v82, v83
	v_lshlrev_b64 v[82:83], 6, v[98:99]
	v_lshl_add_u64 v[82:83], s[38:39], 0, v[82:83]
	v_lshl_add_u64 v[82:83], s[48:49], 2, v[82:83]
	s_lshl_b32 s28, s53, 2
	s_mov_b32 s29, s93
	v_lshl_add_u64 v[82:83], v[82:83], 0, s[28:29]
	global_store_dword v[82:83], v84, off
; __device__ __forceinline__ u32x4 pack8(f32x4 a, f32x4 b) { u32x4 w; w.x = pk2(a[0], a[1]); w.y = pk2(a[2], a[3]); w.z = pk2(b[0], b[1]); w.w = pk2(b[2], b[3]); return w; }
; __device__ __forceinline__ void unpack8(u32x4 w, f32x4& a, f32x4& b) { a = (f32x4){bflo(w.x), bfhi(w.x), bflo(w.y), bfhi(w.y)}; b = (f32x4){bflo(w.z), bfhi(w.z), bflo(w.w), bfhi(w.w)}; }
;     __device__ __forceinline__ void operator()(const Acc& acc, const Unit& u, int wr, int wc, int fr, int fq, const RsCtx& rc) const {
;     ...
;             for (int m = 0; m < 4; ++m) { const int row = EPI_ROW(u, ai, wr, m, fr); float s = 0.f;
; #pragma unroll
;                 for (int bj = 0; bj < 2; ++bj) { const size_t off = (size_t)row * DM + u.pn * 256 + bj * 128 + wc * 32 + 8 * fq;
;                     f32x4 x0, x1; unpack8(*(const u32x4*)(XB + off), x0, x1);
;                     x0 = x0 + acc[ai][bj][m][0] * alpha; x1 = x1 + acc[ai][bj][m][1] * alpha;
;                     *(u32x4*)(XB + off) = pack8(x0, x1);
; #pragma unroll
;                     for (int e = 0; e < 4; ++e) s += x0[e] * x0[e] + x1[e] * x1[e]; }
;                 s += __shfl_xor(s, 16); s += __shfl_xor(s, 32);
;                 if (fq == 0) ssq_x[(size_t)row * 16 + u.pn * 4 + wc] = s;
;                 if (m == 3) asm volatile("" ::: "memory"); }
.LBB0_1110:
	s_or_b64 exec, exec, s[24:25]
	v_or_b32_e32 v82, 48, v148
	s_waitcnt lgkmcnt(0)
	v_ashrrev_i32_e32 v83, 31, v82
	v_lshlrev_b64 v[84:85], 11, v[82:83]
	v_lshl_add_u64 v[84:85], s[36:37], 0, v[84:85]
	v_lshl_add_u64 v[84:85], s[50:51], 1, v[84:85]
	v_lshl_add_u64 v[84:85], v[84:85], 0, s[92:93]
	v_lshl_add_u64 v[88:89], v[84:85], 0, v[0:1]
	v_mov_b64_e32 v[84:85], v[184:185]
	v_mov_b64_e32 v[86:87], v[186:187]
	s_waitcnt lgkmcnt(0)
	v_lshlrev_b32_e32 v90, 16, v84
	v_and_b32_e32 v91, 0xffff0000, v84
	v_lshlrev_b32_e32 v84, 16, v85
	v_and_b32_e32 v85, 0xffff0000, v85
	v_lshlrev_b32_e32 v92, 16, v86
	v_and_b32_e32 v93, 0xffff0000, v86
	v_lshlrev_b32_e32 v86, 16, v87
	v_and_b32_e32 v87, 0xffff0000, v87
	v_pk_fma_f32 v[80:81], v[142:143], v[80:81], v[84:85]
	v_pk_fma_f32 v[78:79], v[130:131], v[78:79], v[90:91]
	v_pk_fma_f32 v[84:85], v[142:143], v[76:77], v[86:87]
	v_pk_fma_f32 v[86:87], v[130:131], v[74:75], v[92:93]
	v_cvt_pk_bf16_f32 v74, v78, v79
	v_cvt_pk_bf16_f32 v75, v80, v81
	v_cvt_pk_bf16_f32 v76, v86, v87
	v_cvt_pk_bf16_f32 v77, v84, v85
	global_store_dwordx4 v[88:89], v[74:77], off
	s_nop 1
	v_mul_f32_e32 v74, v86, v86
	v_mul_f32_e32 v75, v87, v87
	v_fmac_f32_e32 v74, v78, v78
	v_fmac_f32_e32 v75, v79, v79
	v_add_f32_e32 v74, v74, v75
	v_mul_f32_e32 v75, v84, v84
	v_fmac_f32_e32 v75, v80, v80
	v_add_f32_e32 v74, v75, v74
	v_mul_f32_e32 v75, v85, v85
	v_fmac_f32_e32 v75, v81, v81
	v_add_f32_e32 v84, v75, v74
	v_mov_b64_e32 v[74:75], v[188:189]
	v_mov_b64_e32 v[76:77], v[190:191]
	s_waitcnt lgkmcnt(0)
	v_lshlrev_b32_e32 v78, 16, v74
	v_and_b32_e32 v79, 0xffff0000, v74
	v_lshlrev_b32_e32 v74, 16, v75
	v_and_b32_e32 v75, 0xffff0000, v75
	v_lshlrev_b32_e32 v80, 16, v76
	v_and_b32_e32 v81, 0xffff0000, v76
	v_lshlrev_b32_e32 v76, 16, v77
	v_and_b32_e32 v77, 0xffff0000, v77
	v_pk_fma_f32 v[72:73], v[142:143], v[72:73], v[74:75]
	v_pk_fma_f32 v[70:71], v[130:131], v[70:71], v[78:79]
	v_pk_fma_f32 v[74:75], v[142:143], v[68:69], v[76:77]
	v_pk_fma_f32 v[76:77], v[130:131], v[66:67], v[80:81]
	v_cvt_pk_bf16_f32 v66, v70, v71
	v_cvt_pk_bf16_f32 v67, v72, v73
	v_cvt_pk_bf16_f32 v68, v76, v77
	v_cvt_pk_bf16_f32 v69, v74, v75
	global_store_dwordx4 v[88:89], v[66:69], off offset:256
	s_nop 1
	v_mul_f32_e32 v66, v76, v76
	v_fmac_f32_e32 v66, v70, v70
	v_mul_f32_e32 v67, v77, v77
	v_add_f32_e32 v66, v66, v84
	v_fmac_f32_e32 v67, v71, v71
	v_add_f32_e32 v66, v67, v66
	v_mul_f32_e32 v67, v74, v74
	v_fmac_f32_e32 v67, v72, v72
	v_add_f32_e32 v66, v67, v66
	v_mul_f32_e32 v67, v75, v75
	v_fmac_f32_e32 v67, v73, v73
	v_add_f32_e32 v66, v67, v66
	v_mov_b32_e32 v67, v66
	s_nop 1
	v_permlane16_swap_b32_e32 v67, v66
	s_waitcnt lgkmcnt(0)
	v_add_f32_e32 v66, v66, v67
	v_mov_b32_e32 v67, v66
	s_nop 1
	v_permlane32_swap_b32_e32 v67, v66
	s_and_saveexec_b64 s[24:25], s[4:5]
	s_cbranch_execz .LBB0_1112
	s_waitcnt lgkmcnt(0)
	v_add_f32_e32 v68, v66, v67
	v_lshlrev_b64 v[66:67], 6, v[82:83]
	v_lshl_add_u64 v[66:67], s[38:39], 0, v[66:67]
	v_lshl_add_u64 v[66:67], s[48:49], 2, v[66:67]
	s_lshl_b32 s28, s53, 2
	s_mov_b32 s29, s93
	v_lshl_add_u64 v[66:67], v[66:67], 0, s[28:29]
	global_store_dword v[66:67], v68, off
.LBB0_1112:
	s_or_b64 exec, exec, s[24:25]
	v_add_u32_e32 v66, 0x80, v148
	s_waitcnt lgkmcnt(0)
	v_ashrrev_i32_e32 v67, 31, v66
	v_lshlrev_b64 v[68:69], 11, v[66:67]
	v_lshl_add_u64 v[68:69], s[36:37], 0, v[68:69]
	v_lshl_add_u64 v[68:69], s[50:51], 1, v[68:69]
	v_lshl_add_u64 v[68:69], v[68:69], 0, s[92:93]
	v_lshl_add_u64 v[72:73], v[68:69], 0, v[0:1]
	v_mov_b64_e32 v[68:69], v[192:193]
	v_mov_b64_e32 v[70:71], v[194:195]
	s_waitcnt lgkmcnt(0)
	v_lshlrev_b32_e32 v74, 16, v68
	v_and_b32_e32 v75, 0xffff0000, v68
	v_lshlrev_b32_e32 v68, 16, v69
	v_and_b32_e32 v69, 0xffff0000, v69
	v_lshlrev_b32_e32 v76, 16, v70
	v_and_b32_e32 v77, 0xffff0000, v70
	v_lshlrev_b32_e32 v70, 16, v71
	v_and_b32_e32 v71, 0xffff0000, v71
	v_pk_fma_f32 v[64:65], v[142:143], v[64:65], v[68:69]
	v_pk_fma_f32 v[62:63], v[130:131], v[62:63], v[74:75]
	v_pk_fma_f32 v[68:69], v[142:143], v[60:61], v[70:71]
	v_pk_fma_f32 v[70:71], v[130:131], v[58:59], v[76:77]
	v_cvt_pk_bf16_f32 v58, v62, v63
	v_cvt_pk_bf16_f32 v59, v64, v65
	v_cvt_pk_bf16_f32 v60, v70, v71
	v_cvt_pk_bf16_f32 v61, v68, v69
	global_store_dwordx4 v[72:73], v[58:61], off
	s_nop 1
	v_mul_f32_e32 v58, v70, v70
	v_mul_f32_e32 v59, v71, v71
	v_fmac_f32_e32 v58, v62, v62
	v_fmac_f32_e32 v59, v63, v63
	v_add_f32_e32 v58, v58, v59
	v_mul_f32_e32 v59, v68, v68
	v_fmac_f32_e32 v59, v64, v64
	v_add_f32_e32 v58, v59, v58
	v_mul_f32_e32 v59, v69, v69
	v_fmac_f32_e32 v59, v65, v65
	v_add_f32_e32 v68, v59, v58
	v_mov_b64_e32 v[58:59], v[206:207]
	v_mov_b64_e32 v[60:61], v[208:209]
	s_waitcnt lgkmcnt(0)
	v_lshlrev_b32_e32 v62, 16, v58
	v_and_b32_e32 v63, 0xffff0000, v58
	v_lshlrev_b32_e32 v58, 16, v59
	v_and_b32_e32 v59, 0xffff0000, v59
	v_lshlrev_b32_e32 v64, 16, v60
	v_and_b32_e32 v65, 0xffff0000, v60
	v_lshlrev_b32_e32 v60, 16, v61
	v_and_b32_e32 v61, 0xffff0000, v61
	v_pk_fma_f32 v[56:57], v[142:143], v[56:57], v[58:59]
	v_pk_fma_f32 v[54:55], v[130:131], v[54:55], v[62:63]
	v_pk_fma_f32 v[58:59], v[142:143], v[52:53], v[60:61]
	v_pk_fma_f32 v[60:61], v[130:131], v[50:51], v[64:65]
	v_cvt_pk_bf16_f32 v50, v54, v55
	v_cvt_pk_bf16_f32 v51, v56, v57
	v_cvt_pk_bf16_f32 v52, v60, v61
	v_cvt_pk_bf16_f32 v53, v58, v59
	global_store_dwordx4 v[72:73], v[50:53], off offset:256
	s_nop 1
	v_mul_f32_e32 v50, v60, v60
	v_fmac_f32_e32 v50, v54, v54
	v_mul_f32_e32 v51, v61, v61
	v_add_f32_e32 v50, v50, v68
	v_fmac_f32_e32 v51, v55, v55
	v_add_f32_e32 v50, v51, v50
	v_mul_f32_e32 v51, v58, v58
	v_fmac_f32_e32 v51, v56, v56
	v_add_f32_e32 v50, v51, v50
	v_mul_f32_e32 v51, v59, v59
	v_fmac_f32_e32 v51, v57, v57
	v_add_f32_e32 v50, v51, v50
	v_mov_b32_e32 v51, v50
	s_nop 1
	v_permlane16_swap_b32_e32 v51, v50
	s_waitcnt lgkmcnt(0)
	v_add_f32_e32 v50, v50, v51
	v_mov_b32_e32 v51, v50
	s_nop 1
	v_permlane32_swap_b32_e32 v51, v50
	s_and_saveexec_b64 s[24:25], s[4:5]
	s_cbranch_execz .LBB0_1114
	s_waitcnt lgkmcnt(0)
	v_add_f32_e32 v52, v50, v51
	v_lshlrev_b64 v[50:51], 6, v[66:67]
	v_lshl_add_u64 v[50:51], s[38:39], 0, v[50:51]
	v_lshl_add_u64 v[50:51], s[48:49], 2, v[50:51]
	s_lshl_b32 s28, s53, 2
	s_mov_b32 s29, s93
	v_lshl_add_u64 v[50:51], v[50:51], 0, s[28:29]
	global_store_dword v[50:51], v52, off
; __device__ __forceinline__ u32x4 pack8(f32x4 a, f32x4 b) { u32x4 w; w.x = pk2(a[0], a[1]); w.y = pk2(a[2], a[3]); w.z = pk2(b[0], b[1]); w.w = pk2(b[2], b[3]); return w; }
; __device__ __forceinline__ void unpack8(u32x4 w, f32x4& a, f32x4& b) { a = (f32x4){bflo(w.x), bfhi(w.x), bflo(w.y), bfhi(w.y)}; b = (f32x4){bflo(w.z), bfhi(w.z), bflo(w.w), bfhi(w.w)}; }
;     __device__ __forceinline__ void operator()(const Acc& acc, const Unit& u, int wr, int wc, int fr, int fq, const RsCtx& rc) const {
;     ...
;             for (int m = 0; m < 4; ++m) { const int row = EPI_ROW(u, ai, wr, m, fr); float s = 0.f;
; #pragma unroll
;                 for (int bj = 0; bj < 2; ++bj) { const size_t off = (size_t)row * DM + u.pn * 256 + bj * 128 + wc * 32 + 8 * fq;
;                     f32x4 x0, x1; unpack8(*(const u32x4*)(XB + off), x0, x1);
;                     x0 = x0 + acc[ai][bj][m][0] * alpha; x1 = x1 + acc[ai][bj][m][1] * alpha;
;                     *(u32x4*)(XB + off) = pack8(x0, x1);
; #pragma unroll
;                     for (int e = 0; e < 4; ++e) s += x0[e] * x0[e] + x1[e] * x1[e]; }
;                 s += __shfl_xor(s, 16); s += __shfl_xor(s, 32);
;                 if (fq == 0) ssq_x[(size_t)row * 16 + u.pn * 4 + wc] = s;
;                 if (m == 3) asm volatile("" ::: "memory"); }
.LBB0_1114:
	s_or_b64 exec, exec, s[24:25]
	v_add_u32_e32 v50, 0x90, v148
	s_waitcnt lgkmcnt(0)
	v_ashrrev_i32_e32 v51, 31, v50
	v_lshlrev_b64 v[52:53], 11, v[50:51]
	v_lshl_add_u64 v[52:53], s[36:37], 0, v[52:53]
	v_lshl_add_u64 v[52:53], s[50:51], 1, v[52:53]
	v_lshl_add_u64 v[52:53], v[52:53], 0, s[92:93]
	v_lshl_add_u64 v[56:57], v[52:53], 0, v[0:1]
	v_mov_b64_e32 v[52:53], v[218:219]
	v_mov_b64_e32 v[54:55], v[220:221]
	s_waitcnt lgkmcnt(0)
	v_lshlrev_b32_e32 v58, 16, v52
	v_and_b32_e32 v59, 0xffff0000, v52
	v_lshlrev_b32_e32 v52, 16, v53
	v_and_b32_e32 v53, 0xffff0000, v53
	v_lshlrev_b32_e32 v60, 16, v54
	v_and_b32_e32 v61, 0xffff0000, v54
	v_lshlrev_b32_e32 v54, 16, v55
	v_and_b32_e32 v55, 0xffff0000, v55
	v_pk_fma_f32 v[48:49], v[142:143], v[48:49], v[52:53]
	v_pk_fma_f32 v[46:47], v[130:131], v[46:47], v[58:59]
	v_pk_fma_f32 v[52:53], v[142:143], v[44:45], v[54:55]
	v_pk_fma_f32 v[54:55], v[130:131], v[42:43], v[60:61]
	v_cvt_pk_bf16_f32 v42, v46, v47
	v_cvt_pk_bf16_f32 v43, v48, v49
	v_cvt_pk_bf16_f32 v44, v54, v55
	v_cvt_pk_bf16_f32 v45, v52, v53
	global_store_dwordx4 v[56:57], v[42:45], off
	s_nop 1
	v_mul_f32_e32 v42, v54, v54
	v_mul_f32_e32 v43, v55, v55
	v_fmac_f32_e32 v42, v46, v46
	v_fmac_f32_e32 v43, v47, v47
	v_add_f32_e32 v42, v42, v43
	v_mul_f32_e32 v43, v52, v52
	v_fmac_f32_e32 v43, v48, v48
	v_add_f32_e32 v42, v43, v42
	v_mul_f32_e32 v43, v53, v53
	v_fmac_f32_e32 v43, v49, v49
	v_add_f32_e32 v52, v43, v42
	v_mov_b64_e32 v[42:43], v[232:233]
	v_mov_b64_e32 v[44:45], v[234:235]
	s_waitcnt lgkmcnt(0)
	v_lshlrev_b32_e32 v46, 16, v42
	v_and_b32_e32 v47, 0xffff0000, v42
	v_lshlrev_b32_e32 v42, 16, v43
	v_and_b32_e32 v43, 0xffff0000, v43
	v_lshlrev_b32_e32 v48, 16, v44
	v_and_b32_e32 v49, 0xffff0000, v44
	v_lshlrev_b32_e32 v44, 16, v45
	v_and_b32_e32 v45, 0xffff0000, v45
	v_pk_fma_f32 v[40:41], v[142:143], v[40:41], v[42:43]
	v_pk_fma_f32 v[38:39], v[130:131], v[38:39], v[46:47]
	v_pk_fma_f32 v[42:43], v[142:143], v[36:37], v[44:45]
	v_pk_fma_f32 v[44:45], v[130:131], v[34:35], v[48:49]
	v_cvt_pk_bf16_f32 v34, v38, v39
	v_cvt_pk_bf16_f32 v35, v40, v41
	v_cvt_pk_bf16_f32 v36, v44, v45
	v_cvt_pk_bf16_f32 v37, v42, v43
	global_store_dwordx4 v[56:57], v[34:37], off offset:256
	s_nop 1
	v_mul_f32_e32 v34, v44, v44
	v_fmac_f32_e32 v34, v38, v38
	v_mul_f32_e32 v35, v45, v45
	v_add_f32_e32 v34, v34, v52
	v_fmac_f32_e32 v35, v39, v39
	v_add_f32_e32 v34, v35, v34
	v_mul_f32_e32 v35, v42, v42
	v_fmac_f32_e32 v35, v40, v40
	v_add_f32_e32 v34, v35, v34
	v_mul_f32_e32 v35, v43, v43
	v_fmac_f32_e32 v35, v41, v41
	v_add_f32_e32 v34, v35, v34
	v_mov_b32_e32 v35, v34
	s_nop 1
	v_permlane16_swap_b32_e32 v35, v34
	s_waitcnt lgkmcnt(0)
	v_add_f32_e32 v34, v34, v35
	v_mov_b32_e32 v35, v34
	s_nop 1
	v_permlane32_swap_b32_e32 v35, v34
	s_and_saveexec_b64 s[24:25], s[4:5]
	s_cbranch_execz .LBB0_1116
	s_waitcnt lgkmcnt(0)
	v_add_f32_e32 v36, v34, v35
	v_lshlrev_b64 v[34:35], 6, v[50:51]
	v_lshl_add_u64 v[34:35], s[38:39], 0, v[34:35]
	v_lshl_add_u64 v[34:35], s[48:49], 2, v[34:35]
	s_lshl_b32 s28, s53, 2
	s_mov_b32 s29, s93
	v_lshl_add_u64 v[34:35], v[34:35], 0, s[28:29]
	global_store_dword v[34:35], v36, off
; __device__ __forceinline__ u32x4 pack8(f32x4 a, f32x4 b) { u32x4 w; w.x = pk2(a[0], a[1]); w.y = pk2(a[2], a[3]); w.z = pk2(b[0], b[1]); w.w = pk2(b[2], b[3]); return w; }
; __device__ __forceinline__ void unpack8(u32x4 w, f32x4& a, f32x4& b) { a = (f32x4){bflo(w.x), bfhi(w.x), bflo(w.y), bfhi(w.y)}; b = (f32x4){bflo(w.z), bfhi(w.z), bflo(w.w), bfhi(w.w)}; }
;     __device__ __forceinline__ void operator()(const Acc& acc, const Unit& u, int wr, int wc, int fr, int fq, const RsCtx& rc) const {
;     ...
;             for (int m = 0; m < 4; ++m) { const int row = EPI_ROW(u, ai, wr, m, fr); float s = 0.f;
; #pragma unroll
;                 for (int bj = 0; bj < 2; ++bj) { const size_t off = (size_t)row * DM + u.pn * 256 + bj * 128 + wc * 32 + 8 * fq;
;                     f32x4 x0, x1; unpack8(*(const u32x4*)(XB + off), x0, x1);
;                     x0 = x0 + acc[ai][bj][m][0] * alpha; x1 = x1 + acc[ai][bj][m][1] * alpha;
;                     *(u32x4*)(XB + off) = pack8(x0, x1);
; #pragma unroll
;                     for (int e = 0; e < 4; ++e) s += x0[e] * x0[e] + x1[e] * x1[e]; }
;                 s += __shfl_xor(s, 16); s += __shfl_xor(s, 32);
;                 if (fq == 0) ssq_x[(size_t)row * 16 + u.pn * 4 + wc] = s;
;                 if (m == 3) asm volatile("" ::: "memory"); }
.LBB0_1116:
	s_or_b64 exec, exec, s[24:25]
	v_add_u32_e32 v34, 0xa0, v148
	s_waitcnt lgkmcnt(0)
	v_ashrrev_i32_e32 v35, 31, v34
	v_lshlrev_b64 v[36:37], 11, v[34:35]
	v_lshl_add_u64 v[36:37], s[36:37], 0, v[36:37]
	v_lshl_add_u64 v[36:37], s[50:51], 1, v[36:37]
	v_lshl_add_u64 v[36:37], v[36:37], 0, s[92:93]
	v_lshl_add_u64 v[40:41], v[36:37], 0, v[0:1]
	v_mov_b64_e32 v[36:37], v[236:237]
	v_mov_b64_e32 v[38:39], v[238:239]
	s_waitcnt lgkmcnt(0)
	v_lshlrev_b32_e32 v42, 16, v36
	v_and_b32_e32 v43, 0xffff0000, v36
	v_lshlrev_b32_e32 v36, 16, v37
	v_and_b32_e32 v37, 0xffff0000, v37
	v_lshlrev_b32_e32 v44, 16, v38
	v_and_b32_e32 v45, 0xffff0000, v38
	v_lshlrev_b32_e32 v38, 16, v39
	v_and_b32_e32 v39, 0xffff0000, v39
	v_pk_fma_f32 v[32:33], v[142:143], v[32:33], v[36:37]
	v_pk_fma_f32 v[30:31], v[130:131], v[30:31], v[42:43]
	v_pk_fma_f32 v[36:37], v[142:143], v[28:29], v[38:39]
	v_pk_fma_f32 v[38:39], v[130:131], v[26:27], v[44:45]
	v_cvt_pk_bf16_f32 v26, v30, v31
	v_cvt_pk_bf16_f32 v27, v32, v33
	v_cvt_pk_bf16_f32 v28, v38, v39
	v_cvt_pk_bf16_f32 v29, v36, v37
	global_store_dwordx4 v[40:41], v[26:29], off
	s_nop 1
	v_mul_f32_e32 v26, v38, v38
	v_mul_f32_e32 v27, v39, v39
	v_fmac_f32_e32 v26, v30, v30
	v_fmac_f32_e32 v27, v31, v31
	v_add_f32_e32 v26, v26, v27
	v_mul_f32_e32 v27, v36, v36
	v_fmac_f32_e32 v27, v32, v32
	v_add_f32_e32 v26, v27, v26
	v_mul_f32_e32 v27, v37, v37
	v_fmac_f32_e32 v27, v33, v33
	v_add_f32_e32 v36, v27, v26
	v_mov_b64_e32 v[26:27], v[240:241]
	v_mov_b64_e32 v[28:29], v[242:243]
	s_waitcnt lgkmcnt(0)
	v_lshlrev_b32_e32 v30, 16, v26
	v_and_b32_e32 v31, 0xffff0000, v26
	v_lshlrev_b32_e32 v26, 16, v27
	v_and_b32_e32 v27, 0xffff0000, v27
	v_lshlrev_b32_e32 v32, 16, v28
	v_and_b32_e32 v33, 0xffff0000, v28
	v_lshlrev_b32_e32 v28, 16, v29
	v_and_b32_e32 v29, 0xffff0000, v29
	v_pk_fma_f32 v[24:25], v[142:143], v[24:25], v[26:27]
	v_pk_fma_f32 v[22:23], v[130:131], v[22:23], v[30:31]
	v_pk_fma_f32 v[26:27], v[142:143], v[20:21], v[28:29]
	v_pk_fma_f32 v[28:29], v[130:131], v[18:19], v[32:33]
	v_cvt_pk_bf16_f32 v18, v22, v23
	v_cvt_pk_bf16_f32 v19, v24, v25
	v_cvt_pk_bf16_f32 v20, v28, v29
	v_cvt_pk_bf16_f32 v21, v26, v27
	global_store_dwordx4 v[40:41], v[18:21], off offset:256
	s_nop 1
	v_mul_f32_e32 v18, v28, v28
	v_fmac_f32_e32 v18, v22, v22
	v_mul_f32_e32 v19, v29, v29
	v_add_f32_e32 v18, v18, v36
	v_fmac_f32_e32 v19, v23, v23
	v_add_f32_e32 v18, v19, v18
	v_mul_f32_e32 v19, v26, v26
	v_fmac_f32_e32 v19, v24, v24
	v_add_f32_e32 v18, v19, v18
	v_mul_f32_e32 v19, v27, v27
	v_fmac_f32_e32 v19, v25, v25
	v_add_f32_e32 v18, v19, v18
	v_mov_b32_e32 v19, v18
	s_nop 1
	v_permlane16_swap_b32_e32 v19, v18
	s_waitcnt lgkmcnt(0)
	v_add_f32_e32 v18, v18, v19
	v_mov_b32_e32 v19, v18
	s_nop 1
	v_permlane32_swap_b32_e32 v19, v18
	s_and_saveexec_b64 s[24:25], s[4:5]
	s_cbranch_execz .LBB0_1118
	s_waitcnt lgkmcnt(0)
	v_add_f32_e32 v20, v18, v19
	v_lshlrev_b64 v[18:19], 6, v[34:35]
	v_lshl_add_u64 v[18:19], s[38:39], 0, v[18:19]
	v_lshl_add_u64 v[18:19], s[48:49], 2, v[18:19]
	s_lshl_b32 s28, s53, 2
	s_mov_b32 s29, s93
	v_lshl_add_u64 v[18:19], v[18:19], 0, s[28:29]
	global_store_dword v[18:19], v20, off
.LBB0_1118:
	s_or_b64 exec, exec, s[24:25]
	v_add_u32_e32 v18, 0xb0, v148
	s_waitcnt lgkmcnt(0)
	v_ashrrev_i32_e32 v19, 31, v18
	v_lshlrev_b64 v[20:21], 11, v[18:19]
	v_lshl_add_u64 v[20:21], s[36:37], 0, v[20:21]
	v_lshl_add_u64 v[20:21], s[50:51], 1, v[20:21]
	v_lshl_add_u64 v[20:21], v[20:21], 0, s[92:93]
	v_lshl_add_u64 v[24:25], v[20:21], 0, v[0:1]
	v_mov_b64_e32 v[20:21], v[244:245]
	v_mov_b64_e32 v[22:23], v[246:247]
	s_waitcnt lgkmcnt(0)
	v_lshlrev_b32_e32 v26, 16, v20
	v_and_b32_e32 v27, 0xffff0000, v20
	v_lshlrev_b32_e32 v20, 16, v21
	v_and_b32_e32 v21, 0xffff0000, v21
	v_lshlrev_b32_e32 v28, 16, v22
	v_and_b32_e32 v29, 0xffff0000, v22
	v_lshlrev_b32_e32 v22, 16, v23
	v_and_b32_e32 v23, 0xffff0000, v23
	v_pk_fma_f32 v[16:17], v[142:143], v[16:17], v[20:21]
	v_pk_fma_f32 v[14:15], v[130:131], v[14:15], v[26:27]
	v_pk_fma_f32 v[20:21], v[142:143], v[12:13], v[22:23]
	v_pk_fma_f32 v[22:23], v[130:131], v[10:11], v[28:29]
	v_cvt_pk_bf16_f32 v10, v14, v15
	v_cvt_pk_bf16_f32 v11, v16, v17
	v_cvt_pk_bf16_f32 v12, v22, v23
	v_cvt_pk_bf16_f32 v13, v20, v21
	global_store_dwordx4 v[24:25], v[10:13], off
	v_mul_f32_e32 v0, v22, v22
	v_fmac_f32_e32 v0, v14, v14
	v_mul_f32_e32 v10, v23, v23
	v_fmac_f32_e32 v10, v15, v15
	v_add_f32_e32 v0, v0, v10
	v_mul_f32_e32 v10, v20, v20
	v_fmac_f32_e32 v10, v16, v16
	v_add_f32_e32 v0, v10, v0
	v_mul_f32_e32 v10, v21, v21
	v_fmac_f32_e32 v10, v17, v17
	v_add_f32_e32 v0, v10, v0
	v_mov_b64_e32 v[10:11], v[248:249]
	v_mov_b64_e32 v[12:13], v[250:251]
	s_waitcnt lgkmcnt(0)
	v_lshlrev_b32_e32 v14, 16, v10
	v_and_b32_e32 v15, 0xffff0000, v10
	v_lshlrev_b32_e32 v10, 16, v11
	v_and_b32_e32 v11, 0xffff0000, v11
	v_lshlrev_b32_e32 v16, 16, v12
	v_and_b32_e32 v17, 0xffff0000, v12
	v_lshlrev_b32_e32 v12, 16, v13
	v_and_b32_e32 v13, 0xffff0000, v13
	v_pk_fma_f32 v[8:9], v[142:143], v[8:9], v[10:11]
	v_pk_fma_f32 v[6:7], v[130:131], v[6:7], v[14:15]
	v_pk_fma_f32 v[10:11], v[142:143], v[4:5], v[12:13]
	v_pk_fma_f32 v[12:13], v[130:131], v[2:3], v[16:17]
	v_cvt_pk_bf16_f32 v2, v6, v7
	v_cvt_pk_bf16_f32 v3, v8, v9
	v_cvt_pk_bf16_f32 v4, v12, v13
	v_cvt_pk_bf16_f32 v5, v10, v11
	global_store_dwordx4 v[24:25], v[2:5], off offset:256
	s_nop 1
	v_mul_f32_e32 v2, v12, v12
	v_fmac_f32_e32 v2, v6, v6
	v_add_f32_e32 v0, v2, v0
	v_mul_f32_e32 v2, v13, v13
	v_fmac_f32_e32 v2, v7, v7
	v_add_f32_e32 v0, v2, v0
	v_mul_f32_e32 v2, v10, v10
	v_fmac_f32_e32 v2, v8, v8
	v_add_f32_e32 v0, v2, v0
	v_mul_f32_e32 v2, v11, v11
	v_fmac_f32_e32 v2, v9, v9
	v_add_f32_e32 v0, v2, v0
	v_mov_b32_e32 v2, v0
	s_nop 1
	v_permlane16_swap_b32_e32 v2, v0
	s_waitcnt lgkmcnt(0)
	v_add_f32_e32 v0, v0, v2
	v_mov_b32_e32 v2, v0
	s_nop 1
	v_permlane32_swap_b32_e32 v2, v0
	s_and_saveexec_b64 s[24:25], s[4:5]
	s_cbranch_execz .LBB0_1120
	s_waitcnt lgkmcnt(0)
	v_add_f32_e32 v0, v0, v2
	v_lshlrev_b64 v[2:3], 6, v[18:19]
	v_lshl_add_u64 v[2:3], s[38:39], 0, v[2:3]
	v_lshl_add_u64 v[2:3], s[48:49], 2, v[2:3]
	s_lshl_b32 s92, s53, 2
	v_lshl_add_u64 v[2:3], v[2:3], 0, s[92:93]
	global_store_dword v[2:3], v0, off

; __device__ __forceinline__ unsigned pk2(float lo, float hi) { f32x2_t v = {lo, hi}; bf16x2_t b = __builtin_convertvector(v, bf16x2_t); return __builtin_bit_cast(unsigned, b); }
; __device__ __forceinline__ bf16_t* wdst(int kind, int n, unsigned char* Wb) {
;     ...
;     case 0: case 2: { const int up = n >= FF, j = up ? n - FF : n; const int row = 256 * (j >> 7) + (j & 127) + (up ? 128 : 0); return (bf16_t*)(Wb + (kind == 0 ? O_GU1 : O_GU2)) + (size_t)row * 1024; }
; __device__ __forceinline__ void conv_item(const float* W, int K, int N, int kind, int item, const float* gain, unsigned char* Wb, float* scr, int lane) {
;     ...
;     for (int i = 0; i < 32; ++i) scr[(2 * i + (lane >> 5)) * 33 + (lane & 31)] = wv_[i];
;     __builtin_amdgcn_s_waitcnt(0); asm volatile("" ::: "memory");
;     const int c = lane & 7; float gg[8];
; #pragma unroll
;     for (int e = 0; e < 8; ++e) gg[e] = gain ? gain[k0 + 8 * c + e] : 1.0f;
; #pragma unroll
;     for (int j = 0; j < 4; ++j) { const int n = (lane >> 3) + 8 * j; const float* s = scr + (8 * c) * 33 + n;
;         u32x4 o; o.x = pk2(s[0] * gg[0], s[33] * gg[1]); o.y = pk2(s[2 * 33] * gg[2], s[3 * 33] * gg[3]); o.z = pk2(s[4 * 33] * gg[4], s[5 * 33] * gg[5]); o.w = pk2(s[6 * 33] * gg[6], s[7 * 33] * gg[7]);
;         *(u32x4*)(wdst(kind, n0 + n, Wb) + k0 + 8 * c) = o; }
.LBB0_1127:
	ds_read_b32 v14, v17
	ds_read_b32 v15, v17 offset:132
	ds_read_b32 v24, v17 offset:264
	ds_read_b32 v25, v17 offset:396
	ds_read_b32 v26, v17 offset:528
	ds_read_b32 v27, v17 offset:660
	ds_read_b32 v28, v17 offset:792
	ds_read_b32 v29, v17 offset:924
	s_waitcnt vmcnt(0) lgkmcnt(6)
	v_pk_mul_f32 v[14:15], v[6:7], v[14:15]
	v_add_u32_e32 v30, s22, v16
	v_cvt_pk_bf16_f32 v22, v14, v15
	s_waitcnt lgkmcnt(4)
	v_pk_mul_f32 v[14:15], v[8:9], v[24:25]
	s_movk_i32 s14, 0xaff
	v_cvt_pk_bf16_f32 v23, v14, v15
	s_waitcnt lgkmcnt(2)
	v_pk_mul_f32 v[14:15], v[10:11], v[26:27]
	v_add_u32_e32 v0, 0xfffff500, v30
	v_cmp_lt_i32_e32 vcc, s14, v30
	v_cvt_pk_bf16_f32 v24, v14, v15
	s_waitcnt lgkmcnt(0)
	v_pk_mul_f32 v[14:15], v[12:13], v[28:29]
	v_cndmask_b32_e32 v0, v30, v0, vcc
	v_cvt_pk_bf16_f32 v25, v14, v15
	v_lshlrev_b32_e32 v14, 1, v0
	v_and_b32_e32 v14, 0xffffff00, v14
	v_and_b32_e32 v0, 0x67, v0
	v_cndmask_b32_e32 v15, 0, v225, vcc
	v_or3_b32 v14, v0, v15, v14
	v_ashrrev_i32_e32 v15, 31, v14
	s_ashr_i32 s7, s6, 31
	v_lshlrev_b64 v[14:15], 11, v[14:15]
	v_lshl_add_u64 v[14:15], s[20:21], 0, v[14:15]
	s_lshl_b64 s[4:5], s[6:7], 1
	v_lshl_add_u64 v[14:15], v[14:15], 0, s[4:5]
	v_lshlrev_b32_e32 v0, 1, v4
	v_lshl_add_u64 v[14:15], v[14:15], 0, v[0:1]
	global_store_dwordx4 v[14:15], v[22:25], off
	ds_read_b32 v14, v17 offset:32
	ds_read_b32 v15, v17 offset:164
	ds_read_b32 v24, v17 offset:296
	ds_read_b32 v25, v17 offset:428
	ds_read_b32 v26, v17 offset:560
	ds_read_b32 v27, v17 offset:692
	ds_read_b32 v28, v17 offset:824
	ds_read_b32 v29, v17 offset:956
	s_waitcnt lgkmcnt(0)
	v_pk_mul_f32 v[14:15], v[6:7], v[14:15]
	s_nop 0
	v_cvt_pk_bf16_f32 v22, v14, v15
	v_pk_mul_f32 v[14:15], v[8:9], v[24:25]
	s_nop 0
	v_cvt_pk_bf16_f32 v23, v14, v15
	v_pk_mul_f32 v[14:15], v[10:11], v[26:27]
	s_nop 0
	v_cvt_pk_bf16_f32 v24, v14, v15
	v_pk_mul_f32 v[14:15], v[12:13], v[28:29]
	s_nop 0
	v_cvt_pk_bf16_f32 v25, v14, v15
	v_add_u32_e32 v14, 8, v30
	v_add_u32_e32 v15, 0xfffff508, v30
	v_cmp_lt_i32_e32 vcc, s14, v14
	s_nop 1
	v_cndmask_b32_e32 v14, v14, v15, vcc
	v_lshlrev_b32_e32 v15, 1, v14
	v_and_b32_e32 v15, 0xffffff00, v15
	v_and_b32_e32 v14, 0x6f, v14
	v_cndmask_b32_e32 v26, 0, v225, vcc
	v_or3_b32 v14, v14, v26, v15
	v_ashrrev_i32_e32 v15, 31, v14
	v_lshlrev_b64 v[14:15], 11, v[14:15]
	v_lshl_add_u64 v[14:15], s[20:21], 0, v[14:15]
	v_lshl_add_u64 v[14:15], v[14:15], 0, s[4:5]
	v_lshl_add_u64 v[14:15], v[14:15], 0, v[0:1]
	global_store_dwordx4 v[14:15], v[22:25], off
	ds_read_b32 v14, v17 offset:64
	ds_read_b32 v15, v17 offset:196
	ds_read_b32 v24, v17 offset:328
	ds_read_b32 v25, v17 offset:460
	ds_read_b32 v26, v17 offset:592
	ds_read_b32 v27, v17 offset:724
	ds_read_b32 v28, v17 offset:856
	ds_read_b32 v29, v17 offset:988
	s_waitcnt lgkmcnt(0)
	v_pk_mul_f32 v[14:15], v[6:7], v[14:15]
	s_nop 0
	v_cvt_pk_bf16_f32 v22, v14, v15
	v_pk_mul_f32 v[14:15], v[8:9], v[24:25]
	s_nop 0
	v_cvt_pk_bf16_f32 v23, v14, v15
	v_pk_mul_f32 v[14:15], v[10:11], v[26:27]
	s_nop 0
	v_cvt_pk_bf16_f32 v24, v14, v15
	v_pk_mul_f32 v[14:15], v[12:13], v[28:29]
	v_add_u32_e32 v28, 24, v30
	v_cvt_pk_bf16_f32 v25, v14, v15
	v_add_u32_e32 v14, 16, v30
	v_add_u32_e32 v15, 0xfffff510, v30
	v_cmp_lt_i32_e32 vcc, s14, v14
	v_add_u32_e32 v29, 0xfffff518, v30
	s_nop 0
	v_cndmask_b32_e32 v14, v14, v15, vcc
	v_lshlrev_b32_e32 v15, 1, v14
	v_and_b32_e32 v15, 0xffffff00, v15
	v_and_b32_e32 v14, 0x77, v14
	v_cndmask_b32_e32 v26, 0, v225, vcc
	v_or3_b32 v14, v14, v26, v15
	v_ashrrev_i32_e32 v15, 31, v14
	v_lshlrev_b64 v[14:15], 11, v[14:15]
	v_lshl_add_u64 v[14:15], s[20:21], 0, v[14:15]
	v_lshl_add_u64 v[14:15], v[14:15], 0, s[4:5]
	v_lshl_add_u64 v[14:15], v[14:15], 0, v[0:1]
	v_cmp_lt_i32_e32 vcc, s14, v28
	global_store_dwordx4 v[14:15], v[22:25], off
	ds_read_b32 v14, v17 offset:96
	ds_read_b32 v15, v17 offset:228
	ds_read_b32 v22, v17 offset:360
	ds_read_b32 v23, v17 offset:492
	ds_read_b32 v24, v17 offset:624
	ds_read_b32 v25, v17 offset:756
	ds_read_b32 v26, v17 offset:888
	ds_read_b32 v27, v17 offset:1020
	v_cndmask_b32_e32 v28, v28, v29, vcc
	v_lshlrev_b32_e32 v29, 1, v28
	v_and_b32_e32 v29, 0xffffff00, v29
	v_and_b32_e32 v28, 0x7f, v28
	v_cndmask_b32_e32 v30, 0, v225, vcc
	v_or3_b32 v28, v28, v30, v29
	v_ashrrev_i32_e32 v29, 31, v28
	v_lshlrev_b64 v[28:29], 11, v[28:29]
	s_waitcnt lgkmcnt(0)
	v_pk_mul_f32 v[6:7], v[6:7], v[14:15]
	v_pk_mul_f32 v[8:9], v[8:9], v[22:23]
	v_lshl_add_u64 v[28:29], s[20:21], 0, v[28:29]
	v_cvt_pk_bf16_f32 v6, v6, v7
	v_cvt_pk_bf16_f32 v7, v8, v9
	v_pk_mul_f32 v[8:9], v[10:11], v[24:25]
	v_pk_mul_f32 v[10:11], v[12:13], v[26:27]
	v_cvt_pk_bf16_f32 v8, v8, v9
	v_cvt_pk_bf16_f32 v9, v10, v11
	v_lshl_add_u64 v[10:11], v[28:29], 0, s[4:5]
	v_lshl_add_u64 v[10:11], v[10:11], 0, v[0:1]
	global_store_dwordx4 v[10:11], v[6:9], off
	s_waitcnt lgkmcnt(0)
